# G2/G3 epilogues: B-tile column remap + DPP half-row exchange, gate/y loads and y stores cover 8 rows x 128B
# baseline (speedup 1.0000x reference)
; #define PG8_STAGE(bufoff, gbase, voff) do { _Pragma("unroll") for (int _i = 0; _i < 2; ++_i) \
;         __builtin_amdgcn_global_load_lds((const unsigned*)((const char*)(gbase) + (voff)[_i]), (PG8_LAS unsigned*)(lds + (bufoff) + ldsw + _i * 8192), 16, 0, 0); } while (0)
; #define PG8_WAIT_V(n) asm volatile("s_waitcnt vmcnt(" #n ")" ::: "memory")
; #define PG8_BAR __builtin_amdgcn_s_barrier()
; template <class Epi, class Sched, bool ALIGN_EPI = false, bool SP2 = false>
; __device__ __forceinline__ void gemm_phase(PG8_LAS unsigned char* lds, const Gemm g, const Sched& S, const Epi& E) {
;     ...
;     const int tid = tid_, wid = __builtin_amdgcn_readfirstlane(tid >> 6), lane = tid & 63, wr = wid >> 2, wc = wid & 3, fr = lane & 15, fq = lane >> 4;
;     const int K = g.K, nt = K / BK;
;     unsigned voffA[2], voffB[2];
; #pragma unroll
;     for (int i = 0; i < 2; ++i) { int R, C; stage_rc(tid * 16 + i * 8192, R, C); const int Rb = Epi::PERM ? ((R & ~31) + perm32(R & 31)) : R;
;         voffA[i] = (unsigned)(R * K + C) * 2u; voffB[i] = (unsigned)(Rb * K + C) * 2u; }
;     const size_t kstep = (size_t)(BK * 2);
;     const size_t hstep = (size_t)HALF * K * 2;
;     const size_t tstep = 2 * hstep;
;     const unsigned ldsw = (unsigned)wid * 1024u;
;     const int aoff = lds_byte(wr * 64 + fr, fq * 8), boff = lds_byte(wc * 32 + fr, fq * 8);
;     ...
;     if constexpr (SP2) {
;         PG8_STAGE(PG8_SB(0, 0), cB, voffB); PG8_STAGE(PG8_SB(0, 1), cB + hstep, voffB); PG8_STAGE(PG8_SA(0, 0), cA, voffA); PG8_STAGE(PG8_SA(0, 1), cA + hstep, voffA);
;         if (wr == 1) PG8_BAR;
;         PG8_WAIT_V(2); PG8_BAR;
;         PG8_STAGE(PG8_SB(1, 0), cB + kstep, voffB); PG8_STAGE(PG8_SA(1, 0), cA + kstep, voffA); PG8_STAGE(PG8_SB(1, 1), cB + hstep + kstep, voffB);
;         PG8_WAIT_V(6); PG8_BAR;
.LBB0_546:
	s_or_b64 exec, exec, s[0:1]
	v_readlane_b32 s2, v252, 29
	v_readlane_b32 s3, v252, 30
	v_mov_b32_e32 v7, v188
	s_waitcnt lgkmcnt(0)
	v_cndmask_b32_e64 v0, 0, 1, s[2:3]
	s_barrier
	v_cmp_ne_u32_e64 s[0:1], 1, v0
	s_andn2_b64 vcc, exec, s[2:3]
	v_readfirstlane_b32 s2, v7
	s_cbranch_vccnz .LBB0_566
	v_lshlrev_b32_e32 v4, 4, v7
	v_add_u32_e32 v2, 0x2000, v4
	v_ashrrev_i32_e32 v0, 31, v2
	v_lshrrev_b32_e32 v0, 22, v0
	v_add_u32_e32 v0, v2, v0
	v_ashrrev_i32_e32 v0, 10, v0
	v_mul_i32_i24_e32 v3, 0x400, v0
	v_sub_u32_e32 v2, v2, v3
	v_lshrrev_b32_e32 v3, 4, v2
	v_bitop3_b32 v3, v3, v2, 32 bitop3:0x6c
	v_ashrrev_i32_e32 v2, 31, v3
	v_lshrrev_b32_e32 v2, 26, v2
	v_add_u32_e32 v5, v3, v2
	v_lshlrev_b32_e32 v6, 3, v0
	v_ashrrev_i32_e32 v2, 6, v5
	v_and_b32_e32 v6, -16, v6
	v_add_u32_e32 v6, v2, v6
	v_and_b32_e32 v8, 3, v2
	s_mov_b32 s4, 0x3fffe0
	v_lshrrev_b32_e32 v9, 2, v6
	v_lshlrev_b32_e32 v10, 1, v6
	v_and_b32_e32 v5, 0xc0, v5
	v_and_or_b32 v8, v6, s4, v8
	v_and_b32_e32 v9, 4, v9
	v_and_b32_e32 v10, 24, v10
	v_sub_u32_e32 v3, v3, v5
	v_or3_b32 v8, v8, v9, v10
	v_lshlrev_b32_e32 v9, 5, v0
	v_ashrrev_i16_sdwa v3, v189, sext(v3) dst_sel:DWORD dst_unused:UNUSED_PAD src0_sel:DWORD src1_sel:BYTE_0
	v_and_b32_e32 v9, 32, v9
	v_bfe_i32 v3, v3, 0, 16
	v_add_lshl_u32 v5, v9, v3, 1
	v_lshl_add_u32 v130, v8, 10, v5
	v_lshl_add_u32 v132, v6, 10, v5
	v_bfe_i32 v5, v7, 27, 1
	v_lshrrev_b32_e32 v5, 22, v5
	v_add_u32_e32 v5, v4, v5
	v_and_b32_e32 v5, 0xfffffc00, v5
	v_sub_u32_e32 v4, v4, v5
	v_lshrrev_b32_e32 v5, 4, v4
	v_bitop3_b32 v6, v5, v4, 32 bitop3:0x6c
	v_ashrrev_i32_e32 v5, 31, v7
	v_lshrrev_b32_e32 v5, 26, v5
	v_ashrrev_i32_e32 v4, 31, v6
	v_add_u32_e32 v5, v7, v5
	v_lshrrev_b32_e32 v4, 26, v4
	v_ashrrev_i32_e32 v5, 6, v5
	v_add_u32_e32 v8, v6, v4
	v_lshlrev_b32_e32 v9, 3, v5
	v_ashrrev_i32_e32 v4, 6, v8
	v_and_b32_e32 v9, -16, v9
	v_add_u32_e32 v9, v4, v9
	v_and_b32_e32 v10, 3, v4
	v_lshrrev_b32_e32 v11, 2, v9
	v_lshlrev_b32_e32 v12, 1, v9
	v_and_b32_e32 v8, 0xc0, v8
	v_and_or_b32 v10, v9, s4, v10
	v_and_b32_e32 v11, 4, v11
	v_and_b32_e32 v12, 24, v12
	v_sub_u32_e32 v6, v6, v8
	s_ashr_i32 s3, s2, 6
	v_or3_b32 v10, v10, v11, v12
	v_lshlrev_b32_e32 v11, 5, v5
	v_ashrrev_i16_sdwa v6, v189, sext(v6) dst_sel:DWORD dst_unused:UNUSED_PAD src0_sel:DWORD src1_sel:BYTE_0
	s_lshl_b32 s22, s3, 10
	v_and_b32_e32 v11, 32, v11
	v_bfe_i32 v6, v6, 0, 16
	v_add_lshl_u32 v8, v11, v6, 1
	s_add_i32 s23, s22, 0
	v_readlane_b32 s4, v252, 47
	v_lshl_add_u32 v134, v10, 10, v8
	s_ashr_i32 s98, s2, 8
	s_lshl_b32 s98, s98, 15
	v_add_u32_e32 v134, s98, v134
	s_add_i32 s99, s98, 0x10000
	v_add_u32_e32 v130, s99, v130
	s_add_i32 m0, s23, 0x10000
	v_readlane_b32 s5, v252, 48
	v_lshl_add_u32 v136, v9, 10, v8
	s_add_i32 s24, s23, 0x2000
	s_add_i32 s25, s23, 0x4000
	s_add_i32 s26, s23, 0x6000
	s_nop 0
	global_load_lds_dwordx4 v134, s[4:5]
	s_add_i32 m0, s23, 0x12000
	s_nop 0
	global_load_lds_dwordx4 v130, s[4:5]
	v_readlane_b32 s4, v252, 41
	s_add_i32 m0, s23, 0x14000
	v_readlane_b32 s5, v252, 42
	s_nop 4
	s_sub_u32 s4, s4, 0x18000
	s_subb_u32 s5, s5, 0
	s_nop 0
	global_load_lds_dwordx4 v134, s[4:5]
	s_add_i32 m0, s23, 0x16000
	s_nop 0
	global_load_lds_dwordx4 v130, s[4:5]
	v_readlane_b32 s4, v252, 43
	s_mov_b32 m0, s23
	v_readlane_b32 s5, v252, 44
	s_nop 4
	global_load_lds_dwordx4 v136, s[4:5]
	s_mov_b32 m0, s24
	s_nop 0
	global_load_lds_dwordx4 v132, s[4:5]
	v_readlane_b32 s4, v252, 45
	s_mov_b32 m0, s25
	v_readlane_b32 s5, v252, 46
	s_nop 4
	global_load_lds_dwordx4 v136, s[4:5]
	s_mov_b32 m0, s26
	s_nop 0
	global_load_lds_dwordx4 v132, s[4:5]
	s_ashr_i32 s4, s2, 8
	s_cmp_eq_u32 s4, 1
	s_cselect_b64 s[6:7], -1, 0
	s_cmp_lg_u32 s4, 1
	s_cbranch_scc1 .LBB0_549
	s_barrier
.LBB0_549:
	v_readlane_b32 s18, v252, 47
	v_lshrrev_b32_e32 v17, 1, v7
	v_mov_b32_e32 v135, v1
	v_readlane_b32 s19, v252, 48
	v_and_b32_e32 v17, 24, v17
	v_mov_b32_e32 v131, v1
	v_lshl_add_u64 v[8:9], s[18:19], 0, v[134:135]
	v_readlane_b32 s14, v252, 43
	v_and_b32_e32 v16, 15, v7
	v_lshlrev_b32_e32 v18, 1, v17
	v_lshlrev_b32_e32 v7, 2, v7
	s_lshl_b32 s3, s3, 5
	v_lshl_add_u64 v[10:11], s[18:19], 0, v[130:131]
	v_mov_b32_e32 v137, v1
	v_readlane_b32 s15, v252, 44
	v_lshl_or_b32 v139, s4, 6, v16
	v_lshl_or_b32 v16, v16, 6, v18
	s_lshl_b32 s4, s4, 13
	v_and_b32_e32 v7, 32, v7
	s_and_b32 s3, s3, 0x60
	s_add_i32 m0, s23, 0x18000
	v_lshl_add_u64 v[8:9], v[8:9], 0, s[84:85]
	v_lshl_add_u64 v[12:13], s[14:15], 0, v[136:137]
	v_mov_b32_e32 v133, v1
	v_bitop3_b32 v18, v16, s4, v7 bitop3:0xde
	s_lshl_b32 s4, s3, 7
	s_waitcnt vmcnt(2)
	s_barrier
	global_load_lds_dwordx4 v[8:9], off
	v_lshl_add_u64 v[8:9], v[10:11], 0, s[84:85]
	s_add_i32 m0, s23, 0x1a000
	s_add_i32 s27, s23, 0x8000
	v_lshl_add_u64 v[14:15], s[14:15], 0, v[132:133]
	v_bitop3_b32 v148, v16, s4, v7 bitop3:0xde
	global_load_lds_dwordx4 v[8:9], off
	v_lshl_add_u64 v[8:9], v[12:13], 0, s[84:85]
	s_mov_b32 m0, s27
	s_add_i32 s28, s23, 0xa000
	v_readlane_b32 s4, v252, 49
	global_load_lds_dwordx4 v[8:9], off
	v_lshl_add_u64 v[8:9], v[14:15], 0, s[84:85]
	s_mov_b32 m0, s28
	v_readlane_b32 s5, v252, 50
	global_load_lds_dwordx4 v[8:9], off
	s_add_i32 m0, s23, 0x1c000
	s_sub_u32 s4, s4, 0x18000
	s_subb_u32 s5, s5, 0
	v_lshl_add_u64 v[8:9], s[4:5], 0, v[134:135]
	global_load_lds_dwordx4 v[8:9], off
	v_lshl_add_u64 v[8:9], s[4:5], 0, v[130:131]
	s_add_i32 m0, s23, 0x1e000
	v_lshlrev_b32_e32 v7, 13, v5
	global_load_lds_dwordx4 v[8:9], off
	v_and_b32_e32 v7, 0xffffc000, v7
	v_lshl_add_u32 v4, v4, 10, v7
	v_and_b32_e32 v5, 1, v5
	v_lshl_or_b32 v4, v5, 6, v4
	v_lshl_add_u32 v140, v6, 1, v4
	v_lshlrev_b32_e32 v4, 13, v0
	v_and_b32_e32 v4, 0xffffc000, v4
	v_lshl_add_u32 v2, v2, 10, v4
	v_and_b32_e32 v0, 1, v0
	s_cmpk_lt_u32 s2, 0x100
	v_or_b32_e32 v138, s3, v17
	v_lshl_or_b32 v0, v0, 6, v2
	s_movk_i32 s2, 0xf8
	s_waitcnt vmcnt(6)
	v_lshl_add_u32 v142, v3, 1, v0
	v_bitop3_b32 v0, v138, s2, v198 bitop3:0xc8
	v_readlane_b32 s2, v253, 10
	v_readlane_b32 s3, v253, 11
	s_cselect_b64 s[8:9], -1, 0
	v_mov_b32_e32 v141, v1
	v_mov_b32_e32 v143, v1
	s_mov_b32 s29, 0
	v_add_u32_e32 v149, 0, v18
	v_lshlrev_b32_e32 v144, 1, v0
	v_readlane_b32 s30, v252, 35
	s_mov_b32 s31, s2
	s_mov_b64 s[2:3], s[14:15]
	s_barrier
	s_branch .LBB0_552

; #define PG8_STAGE(bufoff, gbase, voff) do { _Pragma("unroll") for (int _i = 0; _i < 2; ++_i) \
;         __builtin_amdgcn_global_load_lds((const unsigned*)((const char*)(gbase) + (voff)[_i]), (PG8_LAS unsigned*)(lds + (bufoff) + ldsw + _i * 8192), 16, 0, 0); } while (0)
; #define PG8_LDA(dst, b, h) do { _Pragma("unroll") for (int m = 0; m < 4; ++m) _Pragma("unroll") for (int k = 0; k < 2; ++k) dst[m][k] = *(const PG8_LAS bf16x8*)(lds + PG8_SA(b, h) + aoff + m * 2048 + k * 1024); } while (0)
; #define PG8_LDB(dst, b, h) do { _Pragma("unroll") for (int n = 0; n < 2; ++n) _Pragma("unroll") for (int k = 0; k < 2; ++k) dst[n][k] = *(const PG8_LAS bf16x8*)(lds + PG8_SB(b, h) + boff + n * 2048 + k * 1024); } while (0)
; #define PG8_MMA(ai, bj, At, Bt) do { __builtin_amdgcn_s_setprio(1); _Pragma("unroll") for (int m = 0; m < 4; ++m) _Pragma("unroll") for (int n = 0; n < 2; ++n) _Pragma("unroll") for (int k = 0; k < 2; ++k) \
;         acc[ai][bj][m][n] = __builtin_amdgcn_mfma_f32_16x16x32_bf16(Bt[n][k], At[m][k], acc[ai][bj][m][n], 0, 0, 0); __builtin_amdgcn_s_setprio(0); } while (0)
; #define PG8_WAIT_V(n) asm volatile("s_waitcnt vmcnt(" #n ")" ::: "memory")
; #define PG8_WAIT_L(n) asm volatile("s_waitcnt lgkmcnt(" #n ")" ::: "memory")
; #define PG8_BAR __builtin_amdgcn_s_barrier()
; #define PG8_SCHED __builtin_amdgcn_sched_barrier(0)
; template <class Epi, class Sched, bool ALIGN_EPI = false, bool SP2 = false>
; __device__ __forceinline__ void gemm_phase(PG8_LAS unsigned char* lds, const Gemm g, const Sched& S, const Epi& E) {
;     ...
;             PG8_LDB(B0, 0, 0); PG8_LDB(B1, 0, 1); PG8_SCHED; PG8_LDA(At, 0, 0); PG8_STAGE(PG8_SA(1, 1), a1 + hstep, voffA);
;             PG8_WAIT_V(8); PG8_WAIT_L(0); PG8_BAR; PG8_MMA(0, 0, At, B0); PG8_MMA(0, 1, At, B1); PG8_BAR; PG8_SCHED;
;             PG8_LDA(At, 0, 1); PG8_STAGE(PG8_SB(0, 0), b2, voffB); PG8_STAGE(PG8_SB(0, 1), b2 + hstep, voffB); PG8_STAGE(PG8_SA(0, 0), a2, voffA);
;             PG8_WAIT_V(8); PG8_WAIT_L(0); PG8_BAR; PG8_MMA(1, 0, At, B0); PG8_MMA(1, 1, At, B1); PG8_BAR; PG8_SCHED;
.LBB0_559:
	s_add_u32 s18, s2, 0xfffe0080
	s_addc_u32 s19, s3, -1
	s_add_i32 s38, 0, 0x10000
	s_cmp_eq_u32 s37, 4
	s_cselect_b32 s21, s13, s19
	s_cselect_b32 s20, s33, s18
	v_add_u32_e32 v0, s38, v148
	s_cselect_b32 s19, s11, s36
	s_cselect_b32 s18, s34, s35
	s_add_i32 s40, 0, 0x14000
	ds_read_b128 v[150:153], v0
	ds_read_b128 v[154:157], v0 offset:1024
	ds_read_b128 v[158:161], v0 offset:2048
	ds_read_b128 v[178:181], v0 offset:3072
	v_add_u32_e32 v0, s40, v148
	ds_read_b128 v[182:185], v0
	ds_read_b128 v[200:203], v0 offset:1024
	ds_read_b128 v[204:207], v0 offset:2048
	ds_read_b128 v[208:211], v0 offset:3072
	v_lshl_add_u64 v[146:147], s[2:3], 0, v[140:141]
	s_add_i32 m0, s23, 0xc000
	ds_read_b128 v[212:215], v149
	ds_read_b128 v[216:219], v149 offset:1024
	ds_read_b128 v[220:223], v149 offset:2048
	ds_read_b128 v[224:227], v149 offset:3072
	ds_read_b128 v[228:231], v149 offset:4096
	ds_read_b128 v[232:235], v149 offset:5120
	ds_read_b128 v[236:239], v149 offset:6144
	ds_read_b128 v[244:247], v149 offset:7168
	global_load_lds_dwordx4 v[146:147], off
	v_lshl_add_u64 v[146:147], s[2:3], 0, v[142:143]
	s_add_i32 m0, s23, 0xe000
	s_nop 0
	global_load_lds_dwordx4 v[146:147], off
	s_waitcnt vmcnt(8)
	s_waitcnt lgkmcnt(0)
	s_barrier
	s_setprio 1
	s_waitcnt lgkmcnt(0)
	v_mfma_f32_16x16x32_bf16 v[126:129], v[150:153], v[212:215], v[126:129]
	v_mfma_f32_16x16x32_bf16 v[122:125], v[158:161], v[212:215], v[122:125]
	v_mfma_f32_16x16x32_bf16 v[110:113], v[150:153], v[220:223], v[110:113]
	v_mfma_f32_16x16x32_bf16 v[106:109], v[158:161], v[220:223], v[106:109]
	v_mfma_f32_16x16x32_bf16 v[94:97], v[150:153], v[228:231], v[94:97]
	v_mfma_f32_16x16x32_bf16 v[90:93], v[158:161], v[228:231], v[90:93]
	v_mfma_f32_16x16x32_bf16 v[78:81], v[150:153], v[236:239], v[78:81]
	v_mfma_f32_16x16x32_bf16 v[74:77], v[158:161], v[236:239], v[74:77]
	v_mfma_f32_16x16x32_bf16 v[126:129], v[154:157], v[216:219], v[126:129]
	v_mfma_f32_16x16x32_bf16 v[122:125], v[178:181], v[216:219], v[122:125]
	v_mfma_f32_16x16x32_bf16 v[110:113], v[154:157], v[224:227], v[110:113]
	v_mfma_f32_16x16x32_bf16 v[106:109], v[178:181], v[224:227], v[106:109]
	v_mfma_f32_16x16x32_bf16 v[94:97], v[154:157], v[232:235], v[94:97]
	v_mfma_f32_16x16x32_bf16 v[90:93], v[178:181], v[232:235], v[90:93]
	v_mfma_f32_16x16x32_bf16 v[78:81], v[154:157], v[244:247], v[78:81]
	v_mfma_f32_16x16x32_bf16 v[74:77], v[178:181], v[244:247], v[74:77]
	s_setprio 0
	s_setprio 1
	v_mfma_f32_16x16x32_bf16 v[118:121], v[182:185], v[212:215], v[118:121]
	v_mfma_f32_16x16x32_bf16 v[114:117], v[204:207], v[212:215], v[114:117]
	v_mfma_f32_16x16x32_bf16 v[102:105], v[182:185], v[220:223], v[102:105]
	v_mfma_f32_16x16x32_bf16 v[98:101], v[204:207], v[220:223], v[98:101]
	v_mfma_f32_16x16x32_bf16 v[86:89], v[182:185], v[228:231], v[86:89]
	v_mfma_f32_16x16x32_bf16 v[82:85], v[204:207], v[228:231], v[82:85]
	v_mfma_f32_16x16x32_bf16 v[70:73], v[182:185], v[236:239], v[70:73]
	v_mfma_f32_16x16x32_bf16 v[66:69], v[204:207], v[236:239], v[66:69]
	v_mfma_f32_16x16x32_bf16 v[118:121], v[200:203], v[216:219], v[118:121]
	v_mfma_f32_16x16x32_bf16 v[114:117], v[208:211], v[216:219], v[114:117]
	v_mfma_f32_16x16x32_bf16 v[102:105], v[200:203], v[224:227], v[102:105]
	v_mfma_f32_16x16x32_bf16 v[98:101], v[208:211], v[224:227], v[98:101]
	v_mfma_f32_16x16x32_bf16 v[86:89], v[200:203], v[232:235], v[86:89]
	v_mfma_f32_16x16x32_bf16 v[82:85], v[208:211], v[232:235], v[82:85]
	v_mfma_f32_16x16x32_bf16 v[70:73], v[200:203], v[244:247], v[70:73]
	v_mfma_f32_16x16x32_bf16 v[66:69], v[208:211], v[244:247], v[66:69]
	s_setprio 0
	s_barrier
	s_add_i32 s38, s38, s22
	v_lshl_add_u64 v[146:147], s[18:19], 0, v[134:135]
	s_mov_b32 m0, s38
	ds_read_b128 v[212:215], v149 offset:16384
	ds_read_b128 v[216:219], v149 offset:17408
	ds_read_b128 v[220:223], v149 offset:18432
	ds_read_b128 v[224:227], v149 offset:19456
	ds_read_b128 v[228:231], v149 offset:20480
	ds_read_b128 v[232:235], v149 offset:21504
	ds_read_b128 v[236:239], v149 offset:22528
	ds_read_b128 v[244:247], v149 offset:23552
	global_load_lds_dwordx4 v[146:147], off
	s_add_i32 m0, s38, 0x2000
	s_add_u32 s38, s18, 0x8000
	v_lshl_add_u64 v[162:163], s[18:19], 0, v[130:131]
	s_addc_u32 s39, s19, 0
	s_add_i32 s40, s40, s22
	global_load_lds_dwordx4 v[162:163], off
	v_lshl_add_u64 v[164:165], s[38:39], 0, v[134:135]
	s_mov_b32 m0, s40
	v_lshl_add_u64 v[186:187], s[20:21], 0, v[132:133]
	global_load_lds_dwordx4 v[164:165], off
	v_lshl_add_u64 v[164:165], s[38:39], 0, v[130:131]
	s_add_i32 m0, s40, 0x2000
	s_nop 0
	global_load_lds_dwordx4 v[164:165], off
	v_lshl_add_u64 v[164:165], s[20:21], 0, v[136:137]
	s_mov_b32 m0, s23
	s_nop 0
	global_load_lds_dwordx4 v[164:165], off
	s_mov_b32 m0, s24
	s_nop 0
	global_load_lds_dwordx4 v[186:187], off
	s_waitcnt vmcnt(8)
	s_waitcnt lgkmcnt(0)
	s_barrier
; #define PG8_STAGE(bufoff, gbase, voff) do { _Pragma("unroll") for (int _i = 0; _i < 2; ++_i) \
;         __builtin_amdgcn_global_load_lds((const unsigned*)((const char*)(gbase) + (voff)[_i]), (PG8_LAS unsigned*)(lds + (bufoff) + ldsw + _i * 8192), 16, 0, 0); } while (0)
; #define PG8_LDA(dst, b, h) do { _Pragma("unroll") for (int m = 0; m < 4; ++m) _Pragma("unroll") for (int k = 0; k < 2; ++k) dst[m][k] = *(const PG8_LAS bf16x8*)(lds + PG8_SA(b, h) + aoff + m * 2048 + k * 1024); } while (0)
; #define PG8_LDB(dst, b, h) do { _Pragma("unroll") for (int n = 0; n < 2; ++n) _Pragma("unroll") for (int k = 0; k < 2; ++k) dst[n][k] = *(const PG8_LAS bf16x8*)(lds + PG8_SB(b, h) + boff + n * 2048 + k * 1024); } while (0)
; #define PG8_MMA(ai, bj, At, Bt) do { __builtin_amdgcn_s_setprio(1); _Pragma("unroll") for (int m = 0; m < 4; ++m) _Pragma("unroll") for (int n = 0; n < 2; ++n) _Pragma("unroll") for (int k = 0; k < 2; ++k) \
;         acc[ai][bj][m][n] = __builtin_amdgcn_mfma_f32_16x16x32_bf16(Bt[n][k], At[m][k], acc[ai][bj][m][n], 0, 0, 0); __builtin_amdgcn_s_setprio(0); } while (0)
; #define PG8_WAIT_V(n) asm volatile("s_waitcnt vmcnt(" #n ")" ::: "memory")
; #define PG8_WAIT_L(n) asm volatile("s_waitcnt lgkmcnt(" #n ")" ::: "memory")
; #define PG8_BAR __builtin_amdgcn_s_barrier()
; #define PG8_SCHED __builtin_amdgcn_sched_barrier(0)
; template <class Epi, class Sched, bool ALIGN_EPI = false, bool SP2 = false>
; __device__ __forceinline__ void gemm_phase(PG8_LAS unsigned char* lds, const Gemm g, const Sched& S, const Epi& E) {
;     ...
;             PG8_WAIT_V(8); PG8_WAIT_L(0); PG8_BAR; PG8_MMA(1, 0, At, B0); PG8_MMA(1, 1, At, B1); PG8_BAR; PG8_SCHED;
;             PG8_LDB(B0, 1, 0); PG8_LDB(B1, 1, 1); PG8_SCHED; PG8_LDA(At, 1, 0); PG8_STAGE(PG8_SA(0, 1), a2 + hstep, voffA);
;             PG8_WAIT_V(8); PG8_WAIT_L(0); PG8_BAR; PG8_MMA(0, 0, At, B0); PG8_MMA(0, 1, At, B1); PG8_BAR; PG8_SCHED;
;             PG8_LDA(At, 1, 1); PG8_STAGE(PG8_SB(1, 0), b3, voffB); PG8_STAGE(PG8_SB(1, 1), b3 + hstep, voffB); PG8_STAGE(PG8_SA(1, 0), a3, voffA);
	s_setprio 1
	s_waitcnt lgkmcnt(0)
	v_mfma_f32_16x16x32_bf16 v[62:65], v[150:153], v[212:215], v[62:65]
	v_mfma_f32_16x16x32_bf16 v[58:61], v[158:161], v[212:215], v[58:61]
	v_mfma_f32_16x16x32_bf16 v[46:49], v[150:153], v[220:223], v[46:49]
	v_mfma_f32_16x16x32_bf16 v[42:45], v[158:161], v[220:223], v[42:45]
	v_mfma_f32_16x16x32_bf16 v[30:33], v[150:153], v[228:231], v[30:33]
	v_mfma_f32_16x16x32_bf16 v[26:29], v[158:161], v[228:231], v[26:29]
	v_mfma_f32_16x16x32_bf16 v[14:17], v[150:153], v[236:239], v[14:17]
	v_mfma_f32_16x16x32_bf16 v[10:13], v[158:161], v[236:239], v[10:13]
	v_mfma_f32_16x16x32_bf16 v[62:65], v[154:157], v[216:219], v[62:65]
	v_mfma_f32_16x16x32_bf16 v[58:61], v[178:181], v[216:219], v[58:61]
	v_mfma_f32_16x16x32_bf16 v[46:49], v[154:157], v[224:227], v[46:49]
	v_mfma_f32_16x16x32_bf16 v[42:45], v[178:181], v[224:227], v[42:45]
	v_mfma_f32_16x16x32_bf16 v[30:33], v[154:157], v[232:235], v[30:33]
	v_mfma_f32_16x16x32_bf16 v[26:29], v[178:181], v[232:235], v[26:29]
	v_mfma_f32_16x16x32_bf16 v[14:17], v[154:157], v[244:247], v[14:17]
	v_mfma_f32_16x16x32_bf16 v[10:13], v[178:181], v[244:247], v[10:13]
	s_setprio 0
	s_setprio 1
	v_mfma_f32_16x16x32_bf16 v[54:57], v[182:185], v[212:215], v[54:57]
	v_mfma_f32_16x16x32_bf16 v[50:53], v[204:207], v[212:215], v[50:53]
	v_mfma_f32_16x16x32_bf16 v[38:41], v[182:185], v[220:223], v[38:41]
	v_mfma_f32_16x16x32_bf16 v[34:37], v[204:207], v[220:223], v[34:37]
	v_mfma_f32_16x16x32_bf16 v[22:25], v[182:185], v[228:231], v[22:25]
	v_mfma_f32_16x16x32_bf16 v[18:21], v[204:207], v[228:231], v[18:21]
	v_mfma_f32_16x16x32_bf16 v[6:9], v[182:185], v[236:239], v[6:9]
	v_mfma_f32_16x16x32_bf16 v[2:5], v[204:207], v[236:239], v[2:5]
	v_mfma_f32_16x16x32_bf16 v[54:57], v[200:203], v[216:219], v[54:57]
	v_mfma_f32_16x16x32_bf16 v[50:53], v[208:211], v[216:219], v[50:53]
	v_mfma_f32_16x16x32_bf16 v[38:41], v[200:203], v[224:227], v[38:41]
	v_mfma_f32_16x16x32_bf16 v[34:37], v[208:211], v[224:227], v[34:37]
	v_mfma_f32_16x16x32_bf16 v[22:25], v[200:203], v[232:235], v[22:25]
	v_mfma_f32_16x16x32_bf16 v[18:21], v[208:211], v[232:235], v[18:21]
	v_mfma_f32_16x16x32_bf16 v[6:9], v[200:203], v[244:247], v[6:9]
	v_mfma_f32_16x16x32_bf16 v[2:5], v[208:211], v[244:247], v[2:5]
	s_setprio 0
	s_barrier
	s_add_i32 s38, 0, 0x18000
	v_add_u32_e32 v0, s38, v148
	s_add_i32 s39, 0, 0x1c000
	ds_read_b128 v[150:153], v0
	ds_read_b128 v[154:157], v0 offset:1024
	ds_read_b128 v[158:161], v0 offset:2048
	ds_read_b128 v[178:181], v0 offset:3072
	v_add_u32_e32 v0, s39, v148
	ds_read_b128 v[182:185], v0
	ds_read_b128 v[200:203], v0 offset:1024
	ds_read_b128 v[204:207], v0 offset:2048
	ds_read_b128 v[208:211], v0 offset:3072
	s_add_u32 s20, s20, 0x20000
	s_addc_u32 s21, s21, 0
	s_mov_b32 m0, s25
	v_lshl_add_u64 v[190:191], s[20:21], 0, v[136:137]
	ds_read_b128 v[212:215], v149 offset:32768
	ds_read_b128 v[216:219], v149 offset:33792
	ds_read_b128 v[220:223], v149 offset:34816
	ds_read_b128 v[224:227], v149 offset:35840
	ds_read_b128 v[228:231], v149 offset:36864
	ds_read_b128 v[232:235], v149 offset:37888
	ds_read_b128 v[236:239], v149 offset:38912
	ds_read_b128 v[244:247], v149 offset:39936
	global_load_lds_dwordx4 v[190:191], off
	v_lshl_add_u64 v[190:191], s[20:21], 0, v[132:133]
	s_mov_b32 m0, s26
	s_nop 0
	global_load_lds_dwordx4 v[190:191], off
	s_waitcnt vmcnt(8)
	s_waitcnt lgkmcnt(0)
	s_barrier
	s_setprio 1
	s_waitcnt lgkmcnt(0)
	v_mfma_f32_16x16x32_bf16 v[126:129], v[150:153], v[212:215], v[126:129]
	v_mfma_f32_16x16x32_bf16 v[122:125], v[158:161], v[212:215], v[122:125]
	v_mfma_f32_16x16x32_bf16 v[110:113], v[150:153], v[220:223], v[110:113]
	v_mfma_f32_16x16x32_bf16 v[106:109], v[158:161], v[220:223], v[106:109]
	v_mfma_f32_16x16x32_bf16 v[94:97], v[150:153], v[228:231], v[94:97]
	v_mfma_f32_16x16x32_bf16 v[90:93], v[158:161], v[228:231], v[90:93]
	v_mfma_f32_16x16x32_bf16 v[78:81], v[150:153], v[236:239], v[78:81]
	v_mfma_f32_16x16x32_bf16 v[74:77], v[158:161], v[236:239], v[74:77]
	v_mfma_f32_16x16x32_bf16 v[126:129], v[154:157], v[216:219], v[126:129]
	v_mfma_f32_16x16x32_bf16 v[122:125], v[178:181], v[216:219], v[122:125]
	v_mfma_f32_16x16x32_bf16 v[110:113], v[154:157], v[224:227], v[110:113]
	v_mfma_f32_16x16x32_bf16 v[106:109], v[178:181], v[224:227], v[106:109]
	v_mfma_f32_16x16x32_bf16 v[94:97], v[154:157], v[232:235], v[94:97]
	v_mfma_f32_16x16x32_bf16 v[90:93], v[178:181], v[232:235], v[90:93]
	v_mfma_f32_16x16x32_bf16 v[78:81], v[154:157], v[244:247], v[78:81]
	v_mfma_f32_16x16x32_bf16 v[74:77], v[178:181], v[244:247], v[74:77]
	s_setprio 0
	s_setprio 1
	v_mfma_f32_16x16x32_bf16 v[118:121], v[182:185], v[212:215], v[118:121]
	v_mfma_f32_16x16x32_bf16 v[114:117], v[204:207], v[212:215], v[114:117]
	v_mfma_f32_16x16x32_bf16 v[102:105], v[182:185], v[220:223], v[102:105]
	v_mfma_f32_16x16x32_bf16 v[98:101], v[204:207], v[220:223], v[98:101]
	v_mfma_f32_16x16x32_bf16 v[86:89], v[182:185], v[228:231], v[86:89]
	v_mfma_f32_16x16x32_bf16 v[82:85], v[204:207], v[228:231], v[82:85]
	v_mfma_f32_16x16x32_bf16 v[70:73], v[182:185], v[236:239], v[70:73]
	v_mfma_f32_16x16x32_bf16 v[66:69], v[204:207], v[236:239], v[66:69]
	v_mfma_f32_16x16x32_bf16 v[118:121], v[200:203], v[216:219], v[118:121]
	v_mfma_f32_16x16x32_bf16 v[114:117], v[208:211], v[216:219], v[114:117]
	v_mfma_f32_16x16x32_bf16 v[102:105], v[200:203], v[224:227], v[102:105]
	v_mfma_f32_16x16x32_bf16 v[98:101], v[208:211], v[224:227], v[98:101]
	v_mfma_f32_16x16x32_bf16 v[86:89], v[200:203], v[232:235], v[86:89]
	v_mfma_f32_16x16x32_bf16 v[82:85], v[208:211], v[232:235], v[82:85]
	v_mfma_f32_16x16x32_bf16 v[70:73], v[200:203], v[244:247], v[70:73]
	v_mfma_f32_16x16x32_bf16 v[66:69], v[208:211], v[244:247], v[66:69]
	s_setprio 0
	s_barrier
; #define PG8_STAGE(bufoff, gbase, voff) do { _Pragma("unroll") for (int _i = 0; _i < 2; ++_i) \
;         __builtin_amdgcn_global_load_lds((const unsigned*)((const char*)(gbase) + (voff)[_i]), (PG8_LAS unsigned*)(lds + (bufoff) + ldsw + _i * 8192), 16, 0, 0); } while (0)
; #define PG8_LDA(dst, b, h) do { _Pragma("unroll") for (int m = 0; m < 4; ++m) _Pragma("unroll") for (int k = 0; k < 2; ++k) dst[m][k] = *(const PG8_LAS bf16x8*)(lds + PG8_SA(b, h) + aoff + m * 2048 + k * 1024); } while (0)
; #define PG8_LDB(dst, b, h) do { _Pragma("unroll") for (int n = 0; n < 2; ++n) _Pragma("unroll") for (int k = 0; k < 2; ++k) dst[n][k] = *(const PG8_LAS bf16x8*)(lds + PG8_SB(b, h) + boff + n * 2048 + k * 1024); } while (0)
; #define PG8_MMA(ai, bj, At, Bt) do { __builtin_amdgcn_s_setprio(1); _Pragma("unroll") for (int m = 0; m < 4; ++m) _Pragma("unroll") for (int n = 0; n < 2; ++n) _Pragma("unroll") for (int k = 0; k < 2; ++k) \
;         acc[ai][bj][m][n] = __builtin_amdgcn_mfma_f32_16x16x32_bf16(Bt[n][k], At[m][k], acc[ai][bj][m][n], 0, 0, 0); __builtin_amdgcn_s_setprio(0); } while (0)
; #define PG8_BAR __builtin_amdgcn_s_barrier()
; template <class Epi, class Sched, bool ALIGN_EPI = false, bool SP2 = false>
; __device__ __forceinline__ void gemm_phase(PG8_LAS unsigned char* lds, const Gemm g, const Sched& S, const Epi& E) {
;     ...
;             PG8_LDB(B0, 1, 0); PG8_LDB(B1, 1, 1); PG8_SCHED; PG8_LDA(At, 1, 0); PG8_STAGE(PG8_SA(0, 1), a2 + hstep, voffA);
;             PG8_WAIT_V(8); PG8_WAIT_L(0); PG8_BAR; PG8_MMA(0, 0, At, B0); PG8_MMA(0, 1, At, B1); PG8_BAR; PG8_SCHED;
;             PG8_LDA(At, 1, 1); PG8_STAGE(PG8_SB(1, 0), b3, voffB); PG8_STAGE(PG8_SB(1, 1), b3 + hstep, voffB); PG8_STAGE(PG8_SA(1, 0), a3, voffA);
;             PG8_WAIT_V(8); PG8_WAIT_L(0); PG8_BAR; PG8_MMA(1, 0, At, B0); PG8_MMA(1, 1, At, B1); PG8_BAR; PG8_SCHED;
;     DI void operator()(const f32x4 (&acc)[2][2][4][2], const Unit& u, int wr, int wc, int fr, int fq) const {
;         const int row0 = u.pm * 256 + wr * 64 + fr, col0 = u.pn * 256 + wc * 32 + 8 * fq;
; #pragma unroll
;         for (int ai = 0; ai < 2; ++ai)
; #pragma unroll
;             for (int m = 0; m < 4; ++m) { const size_t r = (size_t)(row0 + ai * 128 + m * 16);
; #pragma unroll
;                 for (int bj = 0; bj < 2; ++bj) { const int c = col0 + bj * 128; const v4u g = *(const v4u*)(P + pidx(r, 7680 + c));
	s_add_i32 s20, s38, s22
	v_lshl_add_u64 v[146:147], v[146:147], 0, s[84:85]
	s_mov_b32 m0, s20
	ds_read_b128 v[212:215], v149 offset:49152
	ds_read_b128 v[216:219], v149 offset:50176
	ds_read_b128 v[220:223], v149 offset:51200
	ds_read_b128 v[224:227], v149 offset:52224
	ds_read_b128 v[228:231], v149 offset:53248
	ds_read_b128 v[232:235], v149 offset:54272
	ds_read_b128 v[236:239], v149 offset:55296
	ds_read_b128 v[244:247], v149 offset:56320
	global_load_lds_dwordx4 v[146:147], off
	s_add_i32 m0, s20, 0x2000
	s_add_u32 s18, s18, 0x8080
	v_lshl_add_u64 v[146:147], v[162:163], 0, s[84:85]
	s_addc_u32 s19, s19, 0
	s_add_i32 s20, s39, s22
	global_load_lds_dwordx4 v[146:147], off
	v_lshl_add_u64 v[146:147], s[18:19], 0, v[134:135]
	s_mov_b32 m0, s20
	s_nop 0
	global_load_lds_dwordx4 v[146:147], off
	v_lshl_add_u64 v[146:147], s[18:19], 0, v[130:131]
	s_add_i32 m0, s20, 0x2000
	s_nop 0
	global_load_lds_dwordx4 v[146:147], off
	v_lshl_add_u64 v[146:147], v[164:165], 0, s[84:85]
	s_mov_b32 m0, s27
	s_nop 0
	global_load_lds_dwordx4 v[146:147], off
	v_lshl_add_u64 v[146:147], v[186:187], 0, s[84:85]
	s_mov_b32 m0, s28
	s_nop 0
	global_load_lds_dwordx4 v[146:147], off
	s_waitcnt vmcnt(8)
	s_waitcnt lgkmcnt(0)
	s_barrier
	s_setprio 1
	s_waitcnt lgkmcnt(0)
	v_mfma_f32_16x16x32_bf16 v[62:65], v[150:153], v[212:215], v[62:65]
	v_mfma_f32_16x16x32_bf16 v[58:61], v[158:161], v[212:215], v[58:61]
	v_mfma_f32_16x16x32_bf16 v[46:49], v[150:153], v[220:223], v[46:49]
	v_mfma_f32_16x16x32_bf16 v[42:45], v[158:161], v[220:223], v[42:45]
	v_mfma_f32_16x16x32_bf16 v[30:33], v[150:153], v[228:231], v[30:33]
	v_mfma_f32_16x16x32_bf16 v[26:29], v[158:161], v[228:231], v[26:29]
	v_mfma_f32_16x16x32_bf16 v[14:17], v[150:153], v[236:239], v[14:17]
	v_mfma_f32_16x16x32_bf16 v[10:13], v[158:161], v[236:239], v[10:13]
	v_mfma_f32_16x16x32_bf16 v[62:65], v[154:157], v[216:219], v[62:65]
	v_mfma_f32_16x16x32_bf16 v[58:61], v[178:181], v[216:219], v[58:61]
	v_mfma_f32_16x16x32_bf16 v[46:49], v[154:157], v[224:227], v[46:49]
	v_mfma_f32_16x16x32_bf16 v[42:45], v[178:181], v[224:227], v[42:45]
	v_mfma_f32_16x16x32_bf16 v[30:33], v[154:157], v[232:235], v[30:33]
	v_mfma_f32_16x16x32_bf16 v[26:29], v[178:181], v[232:235], v[26:29]
	v_mfma_f32_16x16x32_bf16 v[14:17], v[154:157], v[244:247], v[14:17]
	v_mfma_f32_16x16x32_bf16 v[10:13], v[178:181], v[244:247], v[10:13]
	s_setprio 0
	s_setprio 1
	v_mfma_f32_16x16x32_bf16 v[54:57], v[182:185], v[212:215], v[54:57]
	v_mfma_f32_16x16x32_bf16 v[50:53], v[204:207], v[212:215], v[50:53]
	v_mfma_f32_16x16x32_bf16 v[38:41], v[182:185], v[220:223], v[38:41]
	v_mfma_f32_16x16x32_bf16 v[34:37], v[204:207], v[220:223], v[34:37]
	v_mfma_f32_16x16x32_bf16 v[22:25], v[182:185], v[228:231], v[22:25]
	v_mfma_f32_16x16x32_bf16 v[18:21], v[204:207], v[228:231], v[18:21]
	v_mfma_f32_16x16x32_bf16 v[6:9], v[182:185], v[236:239], v[6:9]
	v_mfma_f32_16x16x32_bf16 v[2:5], v[204:207], v[236:239], v[2:5]
	v_mfma_f32_16x16x32_bf16 v[54:57], v[200:203], v[216:219], v[54:57]
	v_mfma_f32_16x16x32_bf16 v[50:53], v[208:211], v[216:219], v[50:53]
	v_mfma_f32_16x16x32_bf16 v[38:41], v[200:203], v[224:227], v[38:41]
	v_mfma_f32_16x16x32_bf16 v[34:37], v[208:211], v[224:227], v[34:37]
	v_mfma_f32_16x16x32_bf16 v[22:25], v[200:203], v[232:235], v[22:25]
	v_mfma_f32_16x16x32_bf16 v[18:21], v[208:211], v[232:235], v[18:21]
	v_mfma_f32_16x16x32_bf16 v[6:9], v[200:203], v[244:247], v[6:9]
	v_mfma_f32_16x16x32_bf16 v[2:5], v[208:211], v[244:247], v[2:5]
	s_setprio 0
	s_barrier
	s_add_i32 s37, s37, 2
	s_add_u32 s2, s2, 0x100
	s_addc_u32 s3, s3, 0
	s_add_u32 s35, s35, 0x100
	s_addc_u32 s36, s36, 0
	s_cmp_gt_u32 s37, 5
	s_cbranch_scc0 .LBB0_559
	s_and_b64 vcc, exec, s[8:9]
	s_cbranch_vccz .LBB0_562
	s_barrier
.LBB0_562:
	s_lshl_b32 s2, s30, 8
	v_or_b32_e32 v154, s2, v138
	s_addk_i32 s2, 0x1e00
	s_ashr_i32 s2, s2, 8
	s_ashr_i32 s3, s2, 31
	v_lshl_add_u32 v146, s31, 8, v139
	s_lshl_b64 s[2:3], s[2:3], 24
	v_ashrrev_i32_e32 v147, 31, v146
	s_add_u32 s2, s86, s2
	v_lshlrev_b64 v[150:151], 9, v[146:147]
	s_addc_u32 s3, s87, s3
	v_lshl_add_u64 v[158:159], s[2:3], 0, v[150:151]
	v_lshlrev_b32_e32 v0, 1, v138
	v_lshl_add_u64 v[150:151], v[158:159], 0, v[0:1]
	s_andn2_b64 vcc, exec, s[4:5]
	v_lshrrev_b32_e32 v182, 5, v138
	v_lshlrev_b32_e32 v182, 6, v182
	v_and_b32_e32 v183, 24, v138
	v_or_b32_e32 v182, v182, v183
	v_bfe_u32 v183, v146, 3, 1
	v_lshl_or_b32 v182, v183, 5, v182
	v_and_b32_e32 v184, 0xfffffff7, v146
	v_ashrrev_i32_e32 v185, 31, v184
	v_lshlrev_b64 v[178:179], 9, v[184:185]
	v_lshl_add_u64 v[178:179], s[2:3], 0, v[178:179]
	v_lshlrev_b32_e32 v180, 1, v182
	v_add_u32_e32 v180, 0x1000, v180
	v_mov_b32_e32 v181, 0
	v_lshl_add_u64 v[178:179], v[178:179], 0, v[180:181]
	v_lshlrev_b64 v[184:185], 11, v[184:185]
	v_lshl_add_u64 v[184:185], s[88:89], 0, v[184:185]
	v_and_b32_e32 v180, 0xffffff00, v154
	v_or_b32_e32 v180, v180, v182
	v_lshlrev_b32_e32 v180, 1, v180
	v_lshl_add_u64 v[184:185], v[184:185], 0, v[180:181]
	s_mov_b64 s[98:99], 0x0
	v_lshl_add_u64 v[180:181], v[178:179], 0, s[98:99]
	global_load_dwordx4 v[200:203], v[180:181], off offset:-4096
	global_load_dwordx4 v[204:207], v[180:181], off
	s_mov_b64 s[98:99], 0x2000
	v_lshl_add_u64 v[180:181], v[178:179], 0, s[98:99]
	global_load_dwordx4 v[208:211], v[180:181], off offset:-4096
	global_load_dwordx4 v[212:215], v[180:181], off
	s_mov_b64 s[98:99], 0x4000
	v_lshl_add_u64 v[180:181], v[178:179], 0, s[98:99]
	global_load_dwordx4 v[216:219], v[180:181], off offset:-4096
	global_load_dwordx4 v[220:223], v[180:181], off
	s_mov_b64 s[98:99], 0x6000
	v_lshl_add_u64 v[180:181], v[178:179], 0, s[98:99]
	global_load_dwordx4 v[224:227], v[180:181], off offset:-4096
	global_load_dwordx4 v[228:231], v[180:181], off
	s_waitcnt vmcnt(6)
; DI size_t pidx(size_t row, int col) { return (size_t)(col >> 8) * ((size_t)TH * 256) + row * 256 + (size_t)(col & 255); }
; DI float lo_f(unsigned u) { return __uint_as_float(u << 16); }
; DI float hi_f(unsigned u) { return __uint_as_float(u & 0xffff0000u); }
; DI unsigned pk2(float lo, float hi) { return pg8::cvt_pk_bf16(lo, hi); }
;     DI void operator()(const f32x4 (&acc)[2][2][4][2], const Unit& u, int wr, int wc, int fr, int fq) const {
;     ...
; #pragma unroll
;         for (int ai = 0; ai < 2; ++ai)
; #pragma unroll
;             for (int m = 0; m < 4; ++m) { const size_t r = (size_t)(row0 + ai * 128 + m * 16);
; #pragma unroll
;                 for (int bj = 0; bj < 2; ++bj) { const int c = col0 + bj * 128; const v4u g = *(const v4u*)(P + pidx(r, 7680 + c));
;                     const f32x4 v0 = acc[ai][bj][m][0], v1 = acc[ai][bj][m][1];
;                     v4u w; w.x = pk2(v0[0] * lo_f(g.x), v0[1] * hi_f(g.x)); w.y = pk2(v0[2] * lo_f(g.y), v0[3] * hi_f(g.y)); w.z = pk2(v1[0] * lo_f(g.z), v1[1] * hi_f(g.z)); w.w = pk2(v1[2] * lo_f(g.w), v1[3] * hi_f(g.w));
;                     *(v4u*)(Y + r * 1024 + c) = w; } }
	v_mov_b32_e32 v244, v200
	v_mov_b32_e32 v245, v201
	v_mov_b32_e32 v246, v202
	v_mov_b32_e32 v247, v203
	v_mov_b32_dpp v200, v204 row_shr:8 row_mask:0xf bank_mask:0xc
	v_mov_b32_dpp v201, v205 row_shr:8 row_mask:0xf bank_mask:0xc
	v_mov_b32_dpp v202, v206 row_shr:8 row_mask:0xf bank_mask:0xc
	v_mov_b32_dpp v203, v207 row_shr:8 row_mask:0xf bank_mask:0xc
	v_mov_b32_dpp v204, v244 row_shl:8 row_mask:0xf bank_mask:0x3
	v_mov_b32_dpp v205, v245 row_shl:8 row_mask:0xf bank_mask:0x3
	v_mov_b32_dpp v206, v246 row_shl:8 row_mask:0xf bank_mask:0x3
	v_mov_b32_dpp v207, v247 row_shl:8 row_mask:0xf bank_mask:0x3
	v_lshlrev_b32_e32 v180, 16, v200
	v_and_b32_e32 v181, 0xffff0000, v200
	v_mul_f32_e32 v126, v126, v180
	v_mul_f32_e32 v127, v127, v181
	v_cvt_pk_bf16_f32 v232, v126, v127
	v_lshlrev_b32_e32 v180, 16, v201
	v_and_b32_e32 v181, 0xffff0000, v201
	v_mul_f32_e32 v128, v128, v180
	v_mul_f32_e32 v129, v129, v181
	v_cvt_pk_bf16_f32 v233, v128, v129
	v_lshlrev_b32_e32 v180, 16, v202
	v_and_b32_e32 v181, 0xffff0000, v202
	v_mul_f32_e32 v122, v122, v180
	v_mul_f32_e32 v123, v123, v181
	v_cvt_pk_bf16_f32 v234, v122, v123
	v_lshlrev_b32_e32 v180, 16, v203
	v_and_b32_e32 v181, 0xffff0000, v203
	v_mul_f32_e32 v124, v124, v180
	v_mul_f32_e32 v125, v125, v181
	v_cvt_pk_bf16_f32 v235, v124, v125
	v_lshlrev_b32_e32 v180, 16, v204
	v_and_b32_e32 v181, 0xffff0000, v204
	v_mul_f32_e32 v118, v118, v180
	v_mul_f32_e32 v119, v119, v181
	v_cvt_pk_bf16_f32 v236, v118, v119
	v_lshlrev_b32_e32 v180, 16, v205
	v_and_b32_e32 v181, 0xffff0000, v205
	v_mul_f32_e32 v120, v120, v180
	v_mul_f32_e32 v121, v121, v181
	v_cvt_pk_bf16_f32 v237, v120, v121
	v_lshlrev_b32_e32 v180, 16, v206
	v_and_b32_e32 v181, 0xffff0000, v206
	v_mul_f32_e32 v114, v114, v180
	v_mul_f32_e32 v115, v115, v181
	v_cvt_pk_bf16_f32 v238, v114, v115
	v_lshlrev_b32_e32 v180, 16, v207
	v_and_b32_e32 v181, 0xffff0000, v207
	v_mul_f32_e32 v116, v116, v180
	v_mul_f32_e32 v117, v117, v181
	v_cvt_pk_bf16_f32 v239, v116, v117
	v_mov_b32_e32 v244, v236
	v_mov_b32_e32 v245, v237
	v_mov_b32_e32 v246, v238
	v_mov_b32_e32 v247, v239
	v_mov_b32_dpp v236, v232 row_shl:8 row_mask:0xf bank_mask:0x3
	v_mov_b32_dpp v237, v233 row_shl:8 row_mask:0xf bank_mask:0x3
	v_mov_b32_dpp v238, v234 row_shl:8 row_mask:0xf bank_mask:0x3
	v_mov_b32_dpp v239, v235 row_shl:8 row_mask:0xf bank_mask:0x3
	v_mov_b32_dpp v232, v244 row_shr:8 row_mask:0xf bank_mask:0xc
	v_mov_b32_dpp v233, v245 row_shr:8 row_mask:0xf bank_mask:0xc
	v_mov_b32_dpp v234, v246 row_shr:8 row_mask:0xf bank_mask:0xc
	v_mov_b32_dpp v235, v247 row_shr:8 row_mask:0xf bank_mask:0xc
	s_mov_b64 s[98:99], 0x0
	v_lshl_add_u64 v[156:157], v[184:185], 0, s[98:99]
	s_mov_b64 s[98:99], 0x4000
	v_lshl_add_u64 v[158:159], v[184:185], 0, s[98:99]
	global_store_dwordx4 v[156:157], v[232:235], off
	global_store_dwordx4 v[158:159], v[236:239], off
	s_mov_b64 s[98:99], 0x10000
	v_lshl_add_u64 v[180:181], v[178:179], 0, s[98:99]
	global_load_dwordx4 v[200:203], v[180:181], off offset:-4096
	global_load_dwordx4 v[204:207], v[180:181], off
	s_waitcnt vmcnt(8)
	v_mov_b32_e32 v244, v208
	v_mov_b32_e32 v245, v209
	v_mov_b32_e32 v246, v210
	v_mov_b32_e32 v247, v211
	v_mov_b32_dpp v208, v212 row_shr:8 row_mask:0xf bank_mask:0xc
	v_mov_b32_dpp v209, v213 row_shr:8 row_mask:0xf bank_mask:0xc
	v_mov_b32_dpp v210, v214 row_shr:8 row_mask:0xf bank_mask:0xc
	v_mov_b32_dpp v211, v215 row_shr:8 row_mask:0xf bank_mask:0xc
	v_mov_b32_dpp v212, v244 row_shl:8 row_mask:0xf bank_mask:0x3
	v_mov_b32_dpp v213, v245 row_shl:8 row_mask:0xf bank_mask:0x3
	v_mov_b32_dpp v214, v246 row_shl:8 row_mask:0xf bank_mask:0x3
	v_mov_b32_dpp v215, v247 row_shl:8 row_mask:0xf bank_mask:0x3
	v_lshlrev_b32_e32 v180, 16, v208
	v_and_b32_e32 v181, 0xffff0000, v208
	v_mul_f32_e32 v110, v110, v180
	v_mul_f32_e32 v111, v111, v181
	v_cvt_pk_bf16_f32 v232, v110, v111
	v_lshlrev_b32_e32 v180, 16, v209
	v_and_b32_e32 v181, 0xffff0000, v209
	v_mul_f32_e32 v112, v112, v180
	v_mul_f32_e32 v113, v113, v181
	v_cvt_pk_bf16_f32 v233, v112, v113
	v_lshlrev_b32_e32 v180, 16, v210
	v_and_b32_e32 v181, 0xffff0000, v210
	v_mul_f32_e32 v106, v106, v180
	v_mul_f32_e32 v107, v107, v181
	v_cvt_pk_bf16_f32 v234, v106, v107
	v_lshlrev_b32_e32 v180, 16, v211
	v_and_b32_e32 v181, 0xffff0000, v211
	v_mul_f32_e32 v108, v108, v180
	v_mul_f32_e32 v109, v109, v181
	v_cvt_pk_bf16_f32 v235, v108, v109
	v_lshlrev_b32_e32 v180, 16, v212
	v_and_b32_e32 v181, 0xffff0000, v212
	v_mul_f32_e32 v102, v102, v180
	v_mul_f32_e32 v103, v103, v181
	v_cvt_pk_bf16_f32 v236, v102, v103
	v_lshlrev_b32_e32 v180, 16, v213
	v_and_b32_e32 v181, 0xffff0000, v213
	v_mul_f32_e32 v104, v104, v180
	v_mul_f32_e32 v105, v105, v181
	v_cvt_pk_bf16_f32 v237, v104, v105
	v_lshlrev_b32_e32 v180, 16, v214
	v_and_b32_e32 v181, 0xffff0000, v214
	v_mul_f32_e32 v98, v98, v180
	v_mul_f32_e32 v99, v99, v181
	v_cvt_pk_bf16_f32 v238, v98, v99
	v_lshlrev_b32_e32 v180, 16, v215
	v_and_b32_e32 v181, 0xffff0000, v215
	v_mul_f32_e32 v100, v100, v180
	v_mul_f32_e32 v101, v101, v181
	v_cvt_pk_bf16_f32 v239, v100, v101
	v_mov_b32_e32 v244, v236
	v_mov_b32_e32 v245, v237
	v_mov_b32_e32 v246, v238
	v_mov_b32_e32 v247, v239
	v_mov_b32_dpp v236, v232 row_shl:8 row_mask:0xf bank_mask:0x3
	v_mov_b32_dpp v237, v233 row_shl:8 row_mask:0xf bank_mask:0x3
	v_mov_b32_dpp v238, v234 row_shl:8 row_mask:0xf bank_mask:0x3
	v_mov_b32_dpp v239, v235 row_shl:8 row_mask:0xf bank_mask:0x3
	v_mov_b32_dpp v232, v244 row_shr:8 row_mask:0xf bank_mask:0xc
	v_mov_b32_dpp v233, v245 row_shr:8 row_mask:0xf bank_mask:0xc
	v_mov_b32_dpp v234, v246 row_shr:8 row_mask:0xf bank_mask:0xc
	v_mov_b32_dpp v235, v247 row_shr:8 row_mask:0xf bank_mask:0xc
	s_mov_b64 s[98:99], 0x8000
	v_lshl_add_u64 v[156:157], v[184:185], 0, s[98:99]
	s_mov_b64 s[98:99], 0xc000
	v_lshl_add_u64 v[158:159], v[184:185], 0, s[98:99]
	global_store_dwordx4 v[156:157], v[232:235], off
	global_store_dwordx4 v[158:159], v[236:239], off
	s_mov_b64 s[98:99], 0x12000
	v_lshl_add_u64 v[180:181], v[178:179], 0, s[98:99]
	global_load_dwordx4 v[208:211], v[180:181], off offset:-4096
	global_load_dwordx4 v[212:215], v[180:181], off
	s_waitcnt vmcnt(10)
; DI size_t pidx(size_t row, int col) { return (size_t)(col >> 8) * ((size_t)TH * 256) + row * 256 + (size_t)(col & 255); }
; DI float lo_f(unsigned u) { return __uint_as_float(u << 16); }
; DI float hi_f(unsigned u) { return __uint_as_float(u & 0xffff0000u); }
; DI unsigned pk2(float lo, float hi) { return pg8::cvt_pk_bf16(lo, hi); }
;     DI void operator()(const f32x4 (&acc)[2][2][4][2], const Unit& u, int wr, int wc, int fr, int fq) const {
;         const int row0 = u.pm * 256 + wr * 64 + fr, col0 = u.pn * 256 + wc * 32 + 8 * fq;
; #pragma unroll
;         for (int ai = 0; ai < 2; ++ai)
; #pragma unroll
;             for (int m = 0; m < 4; ++m) { const size_t r = (size_t)(row0 + ai * 128 + m * 16);
; #pragma unroll
;                 for (int bj = 0; bj < 2; ++bj) { const int c = col0 + bj * 128; const v4u g = *(const v4u*)(P + pidx(r, 7680 + c));
;                     const f32x4 v0 = acc[ai][bj][m][0], v1 = acc[ai][bj][m][1];
;                     v4u w; w.x = pk2(v0[0] * lo_f(g.x), v0[1] * hi_f(g.x)); w.y = pk2(v0[2] * lo_f(g.y), v0[3] * hi_f(g.y)); w.z = pk2(v1[0] * lo_f(g.z), v1[1] * hi_f(g.z)); w.w = pk2(v1[2] * lo_f(g.w), v1[3] * hi_f(g.w));
;                     *(v4u*)(Y + r * 1024 + c) = w; } }
	v_mov_b32_e32 v244, v216
	v_mov_b32_e32 v245, v217
	v_mov_b32_e32 v246, v218
	v_mov_b32_e32 v247, v219
	v_mov_b32_dpp v216, v220 row_shr:8 row_mask:0xf bank_mask:0xc
	v_mov_b32_dpp v217, v221 row_shr:8 row_mask:0xf bank_mask:0xc
	v_mov_b32_dpp v218, v222 row_shr:8 row_mask:0xf bank_mask:0xc
	v_mov_b32_dpp v219, v223 row_shr:8 row_mask:0xf bank_mask:0xc
	v_mov_b32_dpp v220, v244 row_shl:8 row_mask:0xf bank_mask:0x3
	v_mov_b32_dpp v221, v245 row_shl:8 row_mask:0xf bank_mask:0x3
	v_mov_b32_dpp v222, v246 row_shl:8 row_mask:0xf bank_mask:0x3
	v_mov_b32_dpp v223, v247 row_shl:8 row_mask:0xf bank_mask:0x3
	v_lshlrev_b32_e32 v180, 16, v216
	v_and_b32_e32 v181, 0xffff0000, v216
	v_mul_f32_e32 v94, v94, v180
	v_mul_f32_e32 v95, v95, v181
	v_cvt_pk_bf16_f32 v232, v94, v95
	v_lshlrev_b32_e32 v180, 16, v217
	v_and_b32_e32 v181, 0xffff0000, v217
	v_mul_f32_e32 v96, v96, v180
	v_mul_f32_e32 v97, v97, v181
	v_cvt_pk_bf16_f32 v233, v96, v97
	v_lshlrev_b32_e32 v180, 16, v218
	v_and_b32_e32 v181, 0xffff0000, v218
	v_mul_f32_e32 v90, v90, v180
	v_mul_f32_e32 v91, v91, v181
	v_cvt_pk_bf16_f32 v234, v90, v91
	v_lshlrev_b32_e32 v180, 16, v219
	v_and_b32_e32 v181, 0xffff0000, v219
	v_mul_f32_e32 v92, v92, v180
	v_mul_f32_e32 v93, v93, v181
	v_cvt_pk_bf16_f32 v235, v92, v93
	v_lshlrev_b32_e32 v180, 16, v220
	v_and_b32_e32 v181, 0xffff0000, v220
	v_mul_f32_e32 v86, v86, v180
	v_mul_f32_e32 v87, v87, v181
	v_cvt_pk_bf16_f32 v236, v86, v87
	v_lshlrev_b32_e32 v180, 16, v221
	v_and_b32_e32 v181, 0xffff0000, v221
	v_mul_f32_e32 v88, v88, v180
	v_mul_f32_e32 v89, v89, v181
	v_cvt_pk_bf16_f32 v237, v88, v89
	v_lshlrev_b32_e32 v180, 16, v222
	v_and_b32_e32 v181, 0xffff0000, v222
	v_mul_f32_e32 v82, v82, v180
	v_mul_f32_e32 v83, v83, v181
	v_cvt_pk_bf16_f32 v238, v82, v83
	v_lshlrev_b32_e32 v180, 16, v223
	v_and_b32_e32 v181, 0xffff0000, v223
	v_mul_f32_e32 v84, v84, v180
	v_mul_f32_e32 v85, v85, v181
	v_cvt_pk_bf16_f32 v239, v84, v85
	v_mov_b32_e32 v244, v236
	v_mov_b32_e32 v245, v237
	v_mov_b32_e32 v246, v238
	v_mov_b32_e32 v247, v239
	v_mov_b32_dpp v236, v232 row_shl:8 row_mask:0xf bank_mask:0x3
	v_mov_b32_dpp v237, v233 row_shl:8 row_mask:0xf bank_mask:0x3
	v_mov_b32_dpp v238, v234 row_shl:8 row_mask:0xf bank_mask:0x3
	v_mov_b32_dpp v239, v235 row_shl:8 row_mask:0xf bank_mask:0x3
	v_mov_b32_dpp v232, v244 row_shr:8 row_mask:0xf bank_mask:0xc
	v_mov_b32_dpp v233, v245 row_shr:8 row_mask:0xf bank_mask:0xc
	v_mov_b32_dpp v234, v246 row_shr:8 row_mask:0xf bank_mask:0xc
	v_mov_b32_dpp v235, v247 row_shr:8 row_mask:0xf bank_mask:0xc
	s_mov_b64 s[98:99], 0x10000
	v_lshl_add_u64 v[156:157], v[184:185], 0, s[98:99]
	s_mov_b64 s[98:99], 0x14000
	v_lshl_add_u64 v[158:159], v[184:185], 0, s[98:99]
	global_store_dwordx4 v[156:157], v[232:235], off
	global_store_dwordx4 v[158:159], v[236:239], off
	s_mov_b64 s[98:99], 0x14000
	v_lshl_add_u64 v[180:181], v[178:179], 0, s[98:99]
	global_load_dwordx4 v[216:219], v[180:181], off offset:-4096
	global_load_dwordx4 v[220:223], v[180:181], off
	s_waitcnt vmcnt(12)
	v_mov_b32_e32 v244, v224
	v_mov_b32_e32 v245, v225
	v_mov_b32_e32 v246, v226
	v_mov_b32_e32 v247, v227
	v_mov_b32_dpp v224, v228 row_shr:8 row_mask:0xf bank_mask:0xc
	v_mov_b32_dpp v225, v229 row_shr:8 row_mask:0xf bank_mask:0xc
	v_mov_b32_dpp v226, v230 row_shr:8 row_mask:0xf bank_mask:0xc
	v_mov_b32_dpp v227, v231 row_shr:8 row_mask:0xf bank_mask:0xc
	v_mov_b32_dpp v228, v244 row_shl:8 row_mask:0xf bank_mask:0x3
	v_mov_b32_dpp v229, v245 row_shl:8 row_mask:0xf bank_mask:0x3
	v_mov_b32_dpp v230, v246 row_shl:8 row_mask:0xf bank_mask:0x3
	v_mov_b32_dpp v231, v247 row_shl:8 row_mask:0xf bank_mask:0x3
	v_lshlrev_b32_e32 v180, 16, v224
	v_and_b32_e32 v181, 0xffff0000, v224
	v_mul_f32_e32 v78, v78, v180
	v_mul_f32_e32 v79, v79, v181
	v_cvt_pk_bf16_f32 v232, v78, v79
	v_lshlrev_b32_e32 v180, 16, v225
	v_and_b32_e32 v181, 0xffff0000, v225
	v_mul_f32_e32 v80, v80, v180
	v_mul_f32_e32 v81, v81, v181
	v_cvt_pk_bf16_f32 v233, v80, v81
	v_lshlrev_b32_e32 v180, 16, v226
	v_and_b32_e32 v181, 0xffff0000, v226
	v_mul_f32_e32 v74, v74, v180
	v_mul_f32_e32 v75, v75, v181
	v_cvt_pk_bf16_f32 v234, v74, v75
	v_lshlrev_b32_e32 v180, 16, v227
	v_and_b32_e32 v181, 0xffff0000, v227
	v_mul_f32_e32 v76, v76, v180
	v_mul_f32_e32 v77, v77, v181
	v_cvt_pk_bf16_f32 v235, v76, v77
	v_lshlrev_b32_e32 v180, 16, v228
	v_and_b32_e32 v181, 0xffff0000, v228
	v_mul_f32_e32 v70, v70, v180
	v_mul_f32_e32 v71, v71, v181
	v_cvt_pk_bf16_f32 v236, v70, v71
	v_lshlrev_b32_e32 v180, 16, v229
	v_and_b32_e32 v181, 0xffff0000, v229
	v_mul_f32_e32 v72, v72, v180
	v_mul_f32_e32 v73, v73, v181
	v_cvt_pk_bf16_f32 v237, v72, v73
	v_lshlrev_b32_e32 v180, 16, v230
	v_and_b32_e32 v181, 0xffff0000, v230
	v_mul_f32_e32 v66, v66, v180
	v_mul_f32_e32 v67, v67, v181
	v_cvt_pk_bf16_f32 v238, v66, v67
	v_lshlrev_b32_e32 v180, 16, v231
	v_and_b32_e32 v181, 0xffff0000, v231
	v_mul_f32_e32 v68, v68, v180
	v_mul_f32_e32 v69, v69, v181
	v_cvt_pk_bf16_f32 v239, v68, v69
	v_mov_b32_e32 v244, v236
	v_mov_b32_e32 v245, v237
	v_mov_b32_e32 v246, v238
	v_mov_b32_e32 v247, v239
	v_mov_b32_dpp v236, v232 row_shl:8 row_mask:0xf bank_mask:0x3
	v_mov_b32_dpp v237, v233 row_shl:8 row_mask:0xf bank_mask:0x3
	v_mov_b32_dpp v238, v234 row_shl:8 row_mask:0xf bank_mask:0x3
	v_mov_b32_dpp v239, v235 row_shl:8 row_mask:0xf bank_mask:0x3
	v_mov_b32_dpp v232, v244 row_shr:8 row_mask:0xf bank_mask:0xc
	v_mov_b32_dpp v233, v245 row_shr:8 row_mask:0xf bank_mask:0xc
	v_mov_b32_dpp v234, v246 row_shr:8 row_mask:0xf bank_mask:0xc
	v_mov_b32_dpp v235, v247 row_shr:8 row_mask:0xf bank_mask:0xc
	s_mov_b64 s[98:99], 0x18000
	v_lshl_add_u64 v[156:157], v[184:185], 0, s[98:99]
	s_mov_b64 s[98:99], 0x1c000
	v_lshl_add_u64 v[158:159], v[184:185], 0, s[98:99]
	global_store_dwordx4 v[156:157], v[232:235], off
	global_store_dwordx4 v[158:159], v[236:239], off
	s_mov_b64 s[98:99], 0x16000
	v_lshl_add_u64 v[180:181], v[178:179], 0, s[98:99]
	global_load_dwordx4 v[224:227], v[180:181], off offset:-4096
	global_load_dwordx4 v[228:231], v[180:181], off
	s_waitcnt vmcnt(12)
; DI size_t pidx(size_t row, int col) { return (size_t)(col >> 8) * ((size_t)TH * 256) + row * 256 + (size_t)(col & 255); }
; DI float lo_f(unsigned u) { return __uint_as_float(u << 16); }
; DI float hi_f(unsigned u) { return __uint_as_float(u & 0xffff0000u); }
; DI unsigned pk2(float lo, float hi) { return pg8::cvt_pk_bf16(lo, hi); }
;     DI void operator()(const f32x4 (&acc)[2][2][4][2], const Unit& u, int wr, int wc, int fr, int fq) const {
;         const int row0 = u.pm * 256 + wr * 64 + fr, col0 = u.pn * 256 + wc * 32 + 8 * fq;
; #pragma unroll
;         for (int ai = 0; ai < 2; ++ai)
; #pragma unroll
;             for (int m = 0; m < 4; ++m) { const size_t r = (size_t)(row0 + ai * 128 + m * 16);
; #pragma unroll
;                 for (int bj = 0; bj < 2; ++bj) { const int c = col0 + bj * 128; const v4u g = *(const v4u*)(P + pidx(r, 7680 + c));
;                     const f32x4 v0 = acc[ai][bj][m][0], v1 = acc[ai][bj][m][1];
;                     v4u w; w.x = pk2(v0[0] * lo_f(g.x), v0[1] * hi_f(g.x)); w.y = pk2(v0[2] * lo_f(g.y), v0[3] * hi_f(g.y)); w.z = pk2(v1[0] * lo_f(g.z), v1[1] * hi_f(g.z)); w.w = pk2(v1[2] * lo_f(g.w), v1[3] * hi_f(g.w));
;                     *(v4u*)(Y + r * 1024 + c) = w; } }
	v_mov_b32_e32 v244, v200
	v_mov_b32_e32 v245, v201
	v_mov_b32_e32 v246, v202
	v_mov_b32_e32 v247, v203
	v_mov_b32_dpp v200, v204 row_shr:8 row_mask:0xf bank_mask:0xc
	v_mov_b32_dpp v201, v205 row_shr:8 row_mask:0xf bank_mask:0xc
	v_mov_b32_dpp v202, v206 row_shr:8 row_mask:0xf bank_mask:0xc
	v_mov_b32_dpp v203, v207 row_shr:8 row_mask:0xf bank_mask:0xc
	v_mov_b32_dpp v204, v244 row_shl:8 row_mask:0xf bank_mask:0x3
	v_mov_b32_dpp v205, v245 row_shl:8 row_mask:0xf bank_mask:0x3
	v_mov_b32_dpp v206, v246 row_shl:8 row_mask:0xf bank_mask:0x3
	v_mov_b32_dpp v207, v247 row_shl:8 row_mask:0xf bank_mask:0x3
	v_lshlrev_b32_e32 v180, 16, v200
	v_and_b32_e32 v181, 0xffff0000, v200
	v_mul_f32_e32 v62, v62, v180
	v_mul_f32_e32 v63, v63, v181
	v_cvt_pk_bf16_f32 v232, v62, v63
	v_lshlrev_b32_e32 v180, 16, v201
	v_and_b32_e32 v181, 0xffff0000, v201
	v_mul_f32_e32 v64, v64, v180
	v_mul_f32_e32 v65, v65, v181
	v_cvt_pk_bf16_f32 v233, v64, v65
	v_lshlrev_b32_e32 v180, 16, v202
	v_and_b32_e32 v181, 0xffff0000, v202
	v_mul_f32_e32 v58, v58, v180
	v_mul_f32_e32 v59, v59, v181
	v_cvt_pk_bf16_f32 v234, v58, v59
	v_lshlrev_b32_e32 v180, 16, v203
	v_and_b32_e32 v181, 0xffff0000, v203
	v_mul_f32_e32 v60, v60, v180
	v_mul_f32_e32 v61, v61, v181
	v_cvt_pk_bf16_f32 v235, v60, v61
	v_lshlrev_b32_e32 v180, 16, v204
	v_and_b32_e32 v181, 0xffff0000, v204
	v_mul_f32_e32 v54, v54, v180
	v_mul_f32_e32 v55, v55, v181
	v_cvt_pk_bf16_f32 v236, v54, v55
	v_lshlrev_b32_e32 v180, 16, v205
	v_and_b32_e32 v181, 0xffff0000, v205
	v_mul_f32_e32 v56, v56, v180
	v_mul_f32_e32 v57, v57, v181
	v_cvt_pk_bf16_f32 v237, v56, v57
	v_lshlrev_b32_e32 v180, 16, v206
	v_and_b32_e32 v181, 0xffff0000, v206
	v_mul_f32_e32 v50, v50, v180
	v_mul_f32_e32 v51, v51, v181
	v_cvt_pk_bf16_f32 v238, v50, v51
	v_lshlrev_b32_e32 v180, 16, v207
	v_and_b32_e32 v181, 0xffff0000, v207
	v_mul_f32_e32 v52, v52, v180
	v_mul_f32_e32 v53, v53, v181
	v_cvt_pk_bf16_f32 v239, v52, v53
	v_mov_b32_e32 v244, v236
	v_mov_b32_e32 v245, v237
	v_mov_b32_e32 v246, v238
	v_mov_b32_e32 v247, v239
	v_mov_b32_dpp v236, v232 row_shl:8 row_mask:0xf bank_mask:0x3
	v_mov_b32_dpp v237, v233 row_shl:8 row_mask:0xf bank_mask:0x3
	v_mov_b32_dpp v238, v234 row_shl:8 row_mask:0xf bank_mask:0x3
	v_mov_b32_dpp v239, v235 row_shl:8 row_mask:0xf bank_mask:0x3
	v_mov_b32_dpp v232, v244 row_shr:8 row_mask:0xf bank_mask:0xc
	v_mov_b32_dpp v233, v245 row_shr:8 row_mask:0xf bank_mask:0xc
	v_mov_b32_dpp v234, v246 row_shr:8 row_mask:0xf bank_mask:0xc
	v_mov_b32_dpp v235, v247 row_shr:8 row_mask:0xf bank_mask:0xc
	s_mov_b64 s[98:99], 0x40000
	v_lshl_add_u64 v[156:157], v[184:185], 0, s[98:99]
	s_mov_b64 s[98:99], 0x44000
	v_lshl_add_u64 v[158:159], v[184:185], 0, s[98:99]
	global_store_dwordx4 v[156:157], v[232:235], off
	global_store_dwordx4 v[158:159], v[236:239], off
	s_nop 1
	s_waitcnt vmcnt(10)
	v_mov_b32_e32 v244, v208
	v_mov_b32_e32 v245, v209
	v_mov_b32_e32 v246, v210
	v_mov_b32_e32 v247, v211
	v_mov_b32_dpp v208, v212 row_shr:8 row_mask:0xf bank_mask:0xc
	v_mov_b32_dpp v209, v213 row_shr:8 row_mask:0xf bank_mask:0xc
	v_mov_b32_dpp v210, v214 row_shr:8 row_mask:0xf bank_mask:0xc
	v_mov_b32_dpp v211, v215 row_shr:8 row_mask:0xf bank_mask:0xc
	v_mov_b32_dpp v212, v244 row_shl:8 row_mask:0xf bank_mask:0x3
	v_mov_b32_dpp v213, v245 row_shl:8 row_mask:0xf bank_mask:0x3
	v_mov_b32_dpp v214, v246 row_shl:8 row_mask:0xf bank_mask:0x3
	v_mov_b32_dpp v215, v247 row_shl:8 row_mask:0xf bank_mask:0x3
	v_lshlrev_b32_e32 v180, 16, v208
	v_and_b32_e32 v181, 0xffff0000, v208
	v_mul_f32_e32 v46, v46, v180
	v_mul_f32_e32 v47, v47, v181
	v_cvt_pk_bf16_f32 v232, v46, v47
	v_lshlrev_b32_e32 v180, 16, v209
	v_and_b32_e32 v181, 0xffff0000, v209
	v_mul_f32_e32 v48, v48, v180
	v_mul_f32_e32 v49, v49, v181
	v_cvt_pk_bf16_f32 v233, v48, v49
	v_lshlrev_b32_e32 v180, 16, v210
	v_and_b32_e32 v181, 0xffff0000, v210
	v_mul_f32_e32 v42, v42, v180
	v_mul_f32_e32 v43, v43, v181
	v_cvt_pk_bf16_f32 v234, v42, v43
	v_lshlrev_b32_e32 v180, 16, v211
	v_and_b32_e32 v181, 0xffff0000, v211
	v_mul_f32_e32 v44, v44, v180
	v_mul_f32_e32 v45, v45, v181
	v_cvt_pk_bf16_f32 v235, v44, v45
	v_lshlrev_b32_e32 v180, 16, v212
	v_and_b32_e32 v181, 0xffff0000, v212
	v_mul_f32_e32 v38, v38, v180
	v_mul_f32_e32 v39, v39, v181
	v_cvt_pk_bf16_f32 v236, v38, v39
	v_lshlrev_b32_e32 v180, 16, v213
	v_and_b32_e32 v181, 0xffff0000, v213
	v_mul_f32_e32 v40, v40, v180
	v_mul_f32_e32 v41, v41, v181
	v_cvt_pk_bf16_f32 v237, v40, v41
	v_lshlrev_b32_e32 v180, 16, v214
	v_and_b32_e32 v181, 0xffff0000, v214
	v_mul_f32_e32 v34, v34, v180
	v_mul_f32_e32 v35, v35, v181
	v_cvt_pk_bf16_f32 v238, v34, v35
	v_lshlrev_b32_e32 v180, 16, v215
	v_and_b32_e32 v181, 0xffff0000, v215
	v_mul_f32_e32 v36, v36, v180
	v_mul_f32_e32 v37, v37, v181
	v_cvt_pk_bf16_f32 v239, v36, v37
	v_mov_b32_e32 v244, v236
	v_mov_b32_e32 v245, v237
	v_mov_b32_e32 v246, v238
	v_mov_b32_e32 v247, v239
	v_mov_b32_dpp v236, v232 row_shl:8 row_mask:0xf bank_mask:0x3
	v_mov_b32_dpp v237, v233 row_shl:8 row_mask:0xf bank_mask:0x3
	v_mov_b32_dpp v238, v234 row_shl:8 row_mask:0xf bank_mask:0x3
	v_mov_b32_dpp v239, v235 row_shl:8 row_mask:0xf bank_mask:0x3
	v_mov_b32_dpp v232, v244 row_shr:8 row_mask:0xf bank_mask:0xc
	v_mov_b32_dpp v233, v245 row_shr:8 row_mask:0xf bank_mask:0xc
	v_mov_b32_dpp v234, v246 row_shr:8 row_mask:0xf bank_mask:0xc
	v_mov_b32_dpp v235, v247 row_shr:8 row_mask:0xf bank_mask:0xc
	s_mov_b64 s[98:99], 0x48000
	v_lshl_add_u64 v[156:157], v[184:185], 0, s[98:99]
	s_mov_b64 s[98:99], 0x4c000
	v_lshl_add_u64 v[158:159], v[184:185], 0, s[98:99]
	global_store_dwordx4 v[156:157], v[232:235], off
	global_store_dwordx4 v[158:159], v[236:239], off
	s_nop 1
	s_waitcnt vmcnt(8)
; DI size_t pidx(size_t row, int col) { return (size_t)(col >> 8) * ((size_t)TH * 256) + row * 256 + (size_t)(col & 255); }
; DI float lo_f(unsigned u) { return __uint_as_float(u << 16); }
; DI float hi_f(unsigned u) { return __uint_as_float(u & 0xffff0000u); }
; DI unsigned pk2(float lo, float hi) { return pg8::cvt_pk_bf16(lo, hi); }
;     DI void operator()(const f32x4 (&acc)[2][2][4][2], const Unit& u, int wr, int wc, int fr, int fq) const {
;         const int row0 = u.pm * 256 + wr * 64 + fr, col0 = u.pn * 256 + wc * 32 + 8 * fq;
; #pragma unroll
;         for (int ai = 0; ai < 2; ++ai)
; #pragma unroll
;             for (int m = 0; m < 4; ++m) { const size_t r = (size_t)(row0 + ai * 128 + m * 16);
; #pragma unroll
;                 for (int bj = 0; bj < 2; ++bj) { const int c = col0 + bj * 128; const v4u g = *(const v4u*)(P + pidx(r, 7680 + c));
;                     const f32x4 v0 = acc[ai][bj][m][0], v1 = acc[ai][bj][m][1];
;                     v4u w; w.x = pk2(v0[0] * lo_f(g.x), v0[1] * hi_f(g.x)); w.y = pk2(v0[2] * lo_f(g.y), v0[3] * hi_f(g.y)); w.z = pk2(v1[0] * lo_f(g.z), v1[1] * hi_f(g.z)); w.w = pk2(v1[2] * lo_f(g.w), v1[3] * hi_f(g.w));
;                     *(v4u*)(Y + r * 1024 + c) = w; } }
	v_mov_b32_e32 v244, v216
	v_mov_b32_e32 v245, v217
	v_mov_b32_e32 v246, v218
	v_mov_b32_e32 v247, v219
	v_mov_b32_dpp v216, v220 row_shr:8 row_mask:0xf bank_mask:0xc
	v_mov_b32_dpp v217, v221 row_shr:8 row_mask:0xf bank_mask:0xc
	v_mov_b32_dpp v218, v222 row_shr:8 row_mask:0xf bank_mask:0xc
	v_mov_b32_dpp v219, v223 row_shr:8 row_mask:0xf bank_mask:0xc
	v_mov_b32_dpp v220, v244 row_shl:8 row_mask:0xf bank_mask:0x3
	v_mov_b32_dpp v221, v245 row_shl:8 row_mask:0xf bank_mask:0x3
	v_mov_b32_dpp v222, v246 row_shl:8 row_mask:0xf bank_mask:0x3
	v_mov_b32_dpp v223, v247 row_shl:8 row_mask:0xf bank_mask:0x3
	v_lshlrev_b32_e32 v180, 16, v216
	v_and_b32_e32 v181, 0xffff0000, v216
	v_mul_f32_e32 v30, v30, v180
	v_mul_f32_e32 v31, v31, v181
	v_cvt_pk_bf16_f32 v232, v30, v31
	v_lshlrev_b32_e32 v180, 16, v217
	v_and_b32_e32 v181, 0xffff0000, v217
	v_mul_f32_e32 v32, v32, v180
	v_mul_f32_e32 v33, v33, v181
	v_cvt_pk_bf16_f32 v233, v32, v33
	v_lshlrev_b32_e32 v180, 16, v218
	v_and_b32_e32 v181, 0xffff0000, v218
	v_mul_f32_e32 v26, v26, v180
	v_mul_f32_e32 v27, v27, v181
	v_cvt_pk_bf16_f32 v234, v26, v27
	v_lshlrev_b32_e32 v180, 16, v219
	v_and_b32_e32 v181, 0xffff0000, v219
	v_mul_f32_e32 v28, v28, v180
	v_mul_f32_e32 v29, v29, v181
	v_cvt_pk_bf16_f32 v235, v28, v29
	v_lshlrev_b32_e32 v180, 16, v220
	v_and_b32_e32 v181, 0xffff0000, v220
	v_mul_f32_e32 v22, v22, v180
	v_mul_f32_e32 v23, v23, v181
	v_cvt_pk_bf16_f32 v236, v22, v23
	v_lshlrev_b32_e32 v180, 16, v221
	v_and_b32_e32 v181, 0xffff0000, v221
	v_mul_f32_e32 v24, v24, v180
	v_mul_f32_e32 v25, v25, v181
	v_cvt_pk_bf16_f32 v237, v24, v25
	v_lshlrev_b32_e32 v180, 16, v222
	v_and_b32_e32 v181, 0xffff0000, v222
	v_mul_f32_e32 v18, v18, v180
	v_mul_f32_e32 v19, v19, v181
	v_cvt_pk_bf16_f32 v238, v18, v19
	v_lshlrev_b32_e32 v180, 16, v223
	v_and_b32_e32 v181, 0xffff0000, v223
	v_mul_f32_e32 v20, v20, v180
	v_mul_f32_e32 v21, v21, v181
	v_cvt_pk_bf16_f32 v239, v20, v21
	v_mov_b32_e32 v244, v236
	v_mov_b32_e32 v245, v237
	v_mov_b32_e32 v246, v238
	v_mov_b32_e32 v247, v239
	v_mov_b32_dpp v236, v232 row_shl:8 row_mask:0xf bank_mask:0x3
	v_mov_b32_dpp v237, v233 row_shl:8 row_mask:0xf bank_mask:0x3
	v_mov_b32_dpp v238, v234 row_shl:8 row_mask:0xf bank_mask:0x3
	v_mov_b32_dpp v239, v235 row_shl:8 row_mask:0xf bank_mask:0x3
	v_mov_b32_dpp v232, v244 row_shr:8 row_mask:0xf bank_mask:0xc
	v_mov_b32_dpp v233, v245 row_shr:8 row_mask:0xf bank_mask:0xc
	v_mov_b32_dpp v234, v246 row_shr:8 row_mask:0xf bank_mask:0xc
	v_mov_b32_dpp v235, v247 row_shr:8 row_mask:0xf bank_mask:0xc
	s_mov_b64 s[98:99], 0x50000
	v_lshl_add_u64 v[156:157], v[184:185], 0, s[98:99]
	s_mov_b64 s[98:99], 0x54000
	v_lshl_add_u64 v[158:159], v[184:185], 0, s[98:99]
	global_store_dwordx4 v[156:157], v[232:235], off
	global_store_dwordx4 v[158:159], v[236:239], off
	s_nop 1
	s_waitcnt vmcnt(6)
	v_mov_b32_e32 v244, v224
	v_mov_b32_e32 v245, v225
	v_mov_b32_e32 v246, v226
	v_mov_b32_e32 v247, v227
	v_mov_b32_dpp v224, v228 row_shr:8 row_mask:0xf bank_mask:0xc
	v_mov_b32_dpp v225, v229 row_shr:8 row_mask:0xf bank_mask:0xc
	v_mov_b32_dpp v226, v230 row_shr:8 row_mask:0xf bank_mask:0xc
	v_mov_b32_dpp v227, v231 row_shr:8 row_mask:0xf bank_mask:0xc
	v_mov_b32_dpp v228, v244 row_shl:8 row_mask:0xf bank_mask:0x3
	v_mov_b32_dpp v229, v245 row_shl:8 row_mask:0xf bank_mask:0x3
	v_mov_b32_dpp v230, v246 row_shl:8 row_mask:0xf bank_mask:0x3
	v_mov_b32_dpp v231, v247 row_shl:8 row_mask:0xf bank_mask:0x3
	v_lshlrev_b32_e32 v180, 16, v224
	v_and_b32_e32 v181, 0xffff0000, v224
	v_mul_f32_e32 v14, v14, v180
	v_mul_f32_e32 v15, v15, v181
	v_cvt_pk_bf16_f32 v232, v14, v15
	v_lshlrev_b32_e32 v180, 16, v225
	v_and_b32_e32 v181, 0xffff0000, v225
	v_mul_f32_e32 v16, v16, v180
	v_mul_f32_e32 v17, v17, v181
	v_cvt_pk_bf16_f32 v233, v16, v17
	v_lshlrev_b32_e32 v180, 16, v226
	v_and_b32_e32 v181, 0xffff0000, v226
	v_mul_f32_e32 v10, v10, v180
	v_mul_f32_e32 v11, v11, v181
	v_cvt_pk_bf16_f32 v234, v10, v11
	v_lshlrev_b32_e32 v180, 16, v227
	v_and_b32_e32 v181, 0xffff0000, v227
	v_mul_f32_e32 v12, v12, v180
	v_mul_f32_e32 v13, v13, v181
	v_cvt_pk_bf16_f32 v235, v12, v13
	v_lshlrev_b32_e32 v180, 16, v228
	v_and_b32_e32 v181, 0xffff0000, v228
	v_mul_f32_e32 v6, v6, v180
	v_mul_f32_e32 v7, v7, v181
	v_cvt_pk_bf16_f32 v236, v6, v7
	v_lshlrev_b32_e32 v180, 16, v229
	v_and_b32_e32 v181, 0xffff0000, v229
	v_mul_f32_e32 v8, v8, v180
	v_mul_f32_e32 v9, v9, v181
	v_cvt_pk_bf16_f32 v237, v8, v9
	v_lshlrev_b32_e32 v180, 16, v230
	v_and_b32_e32 v181, 0xffff0000, v230
	v_mul_f32_e32 v2, v2, v180
	v_mul_f32_e32 v3, v3, v181
	v_cvt_pk_bf16_f32 v238, v2, v3
	v_lshlrev_b32_e32 v180, 16, v231
	v_and_b32_e32 v181, 0xffff0000, v231
	v_mul_f32_e32 v4, v4, v180
	v_mul_f32_e32 v5, v5, v181
	v_cvt_pk_bf16_f32 v239, v4, v5
	v_mov_b32_e32 v244, v236
	v_mov_b32_e32 v245, v237
	v_mov_b32_e32 v246, v238
	v_mov_b32_e32 v247, v239
	v_mov_b32_dpp v236, v232 row_shl:8 row_mask:0xf bank_mask:0x3
	v_mov_b32_dpp v237, v233 row_shl:8 row_mask:0xf bank_mask:0x3
	v_mov_b32_dpp v238, v234 row_shl:8 row_mask:0xf bank_mask:0x3
	v_mov_b32_dpp v239, v235 row_shl:8 row_mask:0xf bank_mask:0x3
	v_mov_b32_dpp v232, v244 row_shr:8 row_mask:0xf bank_mask:0xc
	v_mov_b32_dpp v233, v245 row_shr:8 row_mask:0xf bank_mask:0xc
	v_mov_b32_dpp v234, v246 row_shr:8 row_mask:0xf bank_mask:0xc
	v_mov_b32_dpp v235, v247 row_shr:8 row_mask:0xf bank_mask:0xc
	s_mov_b64 s[98:99], 0x58000
	v_lshl_add_u64 v[156:157], v[184:185], 0, s[98:99]
	s_mov_b64 s[98:99], 0x5c000
	v_lshl_add_u64 v[158:159], v[184:185], 0, s[98:99]
	global_store_dwordx4 v[156:157], v[232:235], off
	global_store_dwordx4 v[158:159], v[236:239], off
	s_nop 1
	s_mov_b64 s[2:3], -1
	s_cbranch_vccnz .LBB0_551
	s_andn2_b64 vcc, exec, s[6:7]
	s_cbranch_vccnz .LBB0_550
	s_barrier
	s_branch .LBB0_550

; #define PG8_STAGE(bufoff, gbase, voff) do { _Pragma("unroll") for (int _i = 0; _i < 2; ++_i) \
;         __builtin_amdgcn_global_load_lds((const unsigned*)((const char*)(gbase) + (voff)[_i]), (PG8_LAS unsigned*)(lds + (bufoff) + ldsw + _i * 8192), 16, 0, 0); } while (0)
; #define PG8_WAIT_V(n) asm volatile("s_waitcnt vmcnt(" #n ")" ::: "memory")
; #define PG8_BAR __builtin_amdgcn_s_barrier()
; template <class Epi, class Sched, bool ALIGN_EPI = false, bool SP2 = false>
; __device__ __forceinline__ void gemm_phase(PG8_LAS unsigned char* lds, const Gemm g, const Sched& S, const Epi& E) {
;     ...
;     for (int i = 0; i < 2; ++i) { int R, C; stage_rc(tid * 16 + i * 8192, R, C); const int Rb = Epi::PERM ? ((R & ~31) + perm32(R & 31)) : R;
;         voffA[i] = (unsigned)(R * K + C) * 2u; voffB[i] = (unsigned)(Rb * K + C) * 2u; }
;     const size_t kstep = (size_t)(BK * 2);
;     const size_t hstep = (size_t)HALF * K * 2;
;     const size_t tstep = 2 * hstep;
;     const unsigned ldsw = (unsigned)wid * 1024u;
;     const int aoff = lds_byte(wr * 64 + fr, fq * 8), boff = lds_byte(wc * 32 + fr, fq * 8);
;     ...
;     const char* cA = (const char*)g.A + (size_t)cur.pm * tstep; const char* cB = (const char*)g.Bt + (size_t)cur.pn * tstep;
;     S.a_ready(cur);
;     if constexpr (SP2) {
;         PG8_STAGE(PG8_SB(0, 0), cB, voffB); PG8_STAGE(PG8_SB(0, 1), cB + hstep, voffB); PG8_STAGE(PG8_SA(0, 0), cA, voffA); PG8_STAGE(PG8_SA(0, 1), cA + hstep, voffA);
;         if (wr == 1) PG8_BAR;
;         PG8_WAIT_V(2); PG8_BAR;
;         PG8_STAGE(PG8_SB(1, 0), cB + kstep, voffB); PG8_STAGE(PG8_SA(1, 0), cA + kstep, voffA); PG8_STAGE(PG8_SB(1, 1), cB + hstep + kstep, voffB);
;         PG8_WAIT_V(6); PG8_BAR;
.LBB0_566:
	v_mov_b32_e32 v7, v188
	s_barrier
	s_and_b64 vcc, exec, s[0:1]
	v_readfirstlane_b32 s4, v7
	s_cbranch_vccnz .LBB0_586
	v_lshlrev_b32_e32 v4, 4, v7
	v_add_u32_e32 v2, 0x2000, v4
	v_ashrrev_i32_e32 v0, 31, v2
	v_lshrrev_b32_e32 v0, 22, v0
	v_add_u32_e32 v0, v2, v0
	v_ashrrev_i32_e32 v0, 10, v0
	v_mul_i32_i24_e32 v3, 0x400, v0
	v_sub_u32_e32 v2, v2, v3
	v_lshrrev_b32_e32 v3, 4, v2
	v_bitop3_b32 v3, v3, v2, 32 bitop3:0x6c
	v_ashrrev_i32_e32 v2, 31, v3
	v_lshrrev_b32_e32 v2, 26, v2
	v_add_u32_e32 v5, v3, v2
	v_lshlrev_b32_e32 v6, 3, v0
	v_ashrrev_i32_e32 v2, 6, v5
	v_and_b32_e32 v6, -16, v6
	v_add_u32_e32 v6, v2, v6
	v_and_b32_e32 v8, 3, v2
	s_mov_b32 s2, 0x1fffe0
	v_lshrrev_b32_e32 v9, 2, v6
	v_lshlrev_b32_e32 v10, 1, v6
	v_and_b32_e32 v5, 0xc0, v5
	v_and_or_b32 v8, v6, s2, v8
	v_and_b32_e32 v9, 4, v9
	v_and_b32_e32 v10, 24, v10
	v_sub_u32_e32 v3, v3, v5
	v_or3_b32 v8, v8, v9, v10
	v_lshlrev_b32_e32 v9, 5, v0
	v_ashrrev_i16_sdwa v3, v189, sext(v3) dst_sel:DWORD dst_unused:UNUSED_PAD src0_sel:DWORD src1_sel:BYTE_0
	v_and_b32_e32 v9, 32, v9
	v_bfe_i32 v3, v3, 0, 16
	v_add_lshl_u32 v5, v9, v3, 1
	v_lshl_add_u32 v130, v8, 11, v5
	v_lshl_add_u32 v132, v6, 11, v5
	v_bfe_i32 v5, v7, 27, 1
	v_lshrrev_b32_e32 v5, 22, v5
	v_add_u32_e32 v5, v4, v5
	v_and_b32_e32 v5, 0xfffffc00, v5
	v_sub_u32_e32 v4, v4, v5
	v_lshrrev_b32_e32 v5, 4, v4
	v_bitop3_b32 v6, v5, v4, 32 bitop3:0x6c
	v_ashrrev_i32_e32 v5, 31, v7
	v_lshrrev_b32_e32 v5, 26, v5
	v_ashrrev_i32_e32 v4, 31, v6
	v_add_u32_e32 v5, v7, v5
	v_lshrrev_b32_e32 v4, 26, v4
	v_ashrrev_i32_e32 v5, 6, v5
	v_add_u32_e32 v8, v6, v4
	v_lshlrev_b32_e32 v9, 3, v5
	v_ashrrev_i32_e32 v4, 6, v8
	v_and_b32_e32 v9, -16, v9
	v_add_u32_e32 v9, v4, v9
	v_and_b32_e32 v10, 3, v4
	v_lshrrev_b32_e32 v11, 2, v9
	v_lshlrev_b32_e32 v12, 1, v9
	v_and_b32_e32 v8, 0xc0, v8
	v_and_or_b32 v10, v9, s2, v10
	v_and_b32_e32 v11, 4, v11
	v_and_b32_e32 v12, 24, v12
	v_sub_u32_e32 v6, v6, v8
	s_ashr_i32 s5, s4, 6
	v_or3_b32 v10, v10, v11, v12
	v_lshlrev_b32_e32 v11, 5, v5
	v_ashrrev_i16_sdwa v6, v189, sext(v6) dst_sel:DWORD dst_unused:UNUSED_PAD src0_sel:DWORD src1_sel:BYTE_0
	s_lshl_b32 s22, s5, 10
	v_and_b32_e32 v11, 32, v11
	v_bfe_i32 v6, v6, 0, 16
	v_add_lshl_u32 v8, v11, v6, 1
	s_add_i32 s23, s22, 0
	v_readlane_b32 s2, v252, 59
	v_lshl_add_u32 v134, v10, 11, v8
	s_add_i32 m0, s23, 0x10000
	v_readlane_b32 s3, v252, 60
	v_lshl_add_u32 v136, v9, 11, v8
	s_add_i32 s24, s23, 0x2000
	s_add_i32 s25, s23, 0x4000
	s_add_i32 s26, s23, 0x6000
	s_ashr_i32 s6, s4, 8
	s_lshl_b32 s98, s6, 16
	v_add_u32_e32 v134, s98, v134
	s_add_i32 s99, s98, 0x20000
	v_add_u32_e32 v130, s99, v130
	global_load_lds_dwordx4 v134, s[2:3]
	s_add_i32 m0, s23, 0x12000
	s_nop 0
	global_load_lds_dwordx4 v130, s[2:3]
	v_readlane_b32 s2, v252, 51
	s_add_i32 m0, s23, 0x14000
	v_readlane_b32 s3, v252, 52
	s_nop 4
	s_sub_u32 s2, s2, 0x30000
	s_subb_u32 s3, s3, 0
	s_nop 0
	global_load_lds_dwordx4 v134, s[2:3]
	s_add_i32 m0, s23, 0x16000
	s_cmp_eq_u32 s6, 1
	global_load_lds_dwordx4 v130, s[2:3]
	v_readlane_b32 s2, v252, 55
	s_mov_b32 m0, s23
	v_readlane_b32 s3, v252, 56
	s_nop 4
	global_load_lds_dwordx4 v136, s[2:3]
	s_mov_b32 m0, s24
	s_nop 0
	global_load_lds_dwordx4 v132, s[2:3]
	v_readlane_b32 s2, v252, 57
	s_mov_b32 m0, s25
	v_readlane_b32 s3, v252, 58
	s_nop 4
	global_load_lds_dwordx4 v136, s[2:3]
	s_mov_b32 m0, s26
	s_nop 0
	global_load_lds_dwordx4 v132, s[2:3]
	s_cselect_b64 s[2:3], -1, 0
	s_cmp_lg_u32 s6, 1
	s_cbranch_scc1 .LBB0_569
	s_barrier
.LBB0_569:
	v_readlane_b32 s18, v252, 59
	v_lshrrev_b32_e32 v17, 1, v7
	v_mov_b32_e32 v135, v1
	v_readlane_b32 s19, v252, 60
	v_and_b32_e32 v17, 24, v17
	v_mov_b32_e32 v131, v1
	v_lshl_add_u64 v[8:9], s[18:19], 0, v[134:135]
	v_readlane_b32 s16, v252, 55
	v_and_b32_e32 v16, 15, v7
	v_lshlrev_b32_e32 v18, 1, v17
	v_lshlrev_b32_e32 v7, 2, v7
	s_lshl_b32 s5, s5, 5
	v_lshl_add_u64 v[10:11], s[18:19], 0, v[130:131]
	v_mov_b32_e32 v137, v1
	v_readlane_b32 s17, v252, 56
	v_lshl_or_b32 v139, s6, 6, v16
	v_lshl_or_b32 v16, v16, 6, v18
	s_lshl_b32 s6, s6, 13
	v_and_b32_e32 v7, 32, v7
	s_and_b32 s5, s5, 0x60
	s_add_i32 m0, s23, 0x18000
	v_lshl_add_u64 v[8:9], v[8:9], 0, s[84:85]
	v_lshl_add_u64 v[12:13], s[16:17], 0, v[136:137]
	v_mov_b32_e32 v133, v1
	v_bitop3_b32 v18, v16, s6, v7 bitop3:0xde
	s_lshl_b32 s6, s5, 7
	s_waitcnt vmcnt(2)
	s_barrier
	global_load_lds_dwordx4 v[8:9], off
	v_lshl_add_u64 v[8:9], v[10:11], 0, s[84:85]
	s_add_i32 m0, s23, 0x1a000
	s_add_i32 s27, s23, 0x8000
	v_lshl_add_u64 v[14:15], s[16:17], 0, v[132:133]
	v_bitop3_b32 v150, v16, s6, v7 bitop3:0xde
	global_load_lds_dwordx4 v[8:9], off
	v_lshl_add_u64 v[8:9], v[12:13], 0, s[84:85]
	s_mov_b32 m0, s27
	s_add_i32 s28, s23, 0xa000
	v_readlane_b32 s6, v252, 61
	global_load_lds_dwordx4 v[8:9], off
	v_lshl_add_u64 v[8:9], v[14:15], 0, s[84:85]
	s_mov_b32 m0, s28
	v_readlane_b32 s7, v252, 62
	global_load_lds_dwordx4 v[8:9], off
	s_add_i32 m0, s23, 0x1c000
	s_sub_u32 s6, s6, 0x30000
	s_subb_u32 s7, s7, 0
	v_lshl_add_u64 v[8:9], s[6:7], 0, v[134:135]
	global_load_lds_dwordx4 v[8:9], off
	v_lshl_add_u64 v[8:9], s[6:7], 0, v[130:131]
	s_add_i32 m0, s23, 0x1e000
	v_lshlrev_b32_e32 v7, 14, v5
	global_load_lds_dwordx4 v[8:9], off
	v_and_b32_e32 v7, 0xffff8000, v7
	v_lshl_add_u32 v4, v4, 11, v7
	v_and_b32_e32 v5, 1, v5
	v_lshl_or_b32 v4, v5, 6, v4
	v_lshl_add_u32 v140, v6, 1, v4
	v_lshlrev_b32_e32 v4, 14, v0
	v_and_b32_e32 v4, 0xffff8000, v4
	s_waitcnt vmcnt(6)
	v_lshl_add_u32 v2, v2, 11, v4
	v_and_b32_e32 v0, 1, v0
	s_cmpk_lt_u32 s4, 0x100
	v_or_b32_e32 v138, s5, v17
	v_lshl_or_b32 v0, v0, 6, v2
	v_readlane_b32 s4, v253, 10
	s_cselect_b64 s[6:7], -1, 0
	v_mov_b32_e32 v141, v1
	v_lshl_add_u32 v142, v3, 1, v0
	v_mov_b32_e32 v143, v1
	s_mov_b32 s29, 0
	v_add_u32_e32 v151, 0, v18
	v_readlane_b32 s30, v252, 35
	s_mov_b32 s31, s4
	s_barrier
	v_readlane_b32 s5, v253, 11
	s_branch .LBB0_572

; #define PG8_STAGE(bufoff, gbase, voff) do { _Pragma("unroll") for (int _i = 0; _i < 2; ++_i) \
;         __builtin_amdgcn_global_load_lds((const unsigned*)((const char*)(gbase) + (voff)[_i]), (PG8_LAS unsigned*)(lds + (bufoff) + ldsw + _i * 8192), 16, 0, 0); } while (0)
; #define PG8_LDA(dst, b, h) do { _Pragma("unroll") for (int m = 0; m < 4; ++m) _Pragma("unroll") for (int k = 0; k < 2; ++k) dst[m][k] = *(const PG8_LAS bf16x8*)(lds + PG8_SA(b, h) + aoff + m * 2048 + k * 1024); } while (0)
; #define PG8_LDB(dst, b, h) do { _Pragma("unroll") for (int n = 0; n < 2; ++n) _Pragma("unroll") for (int k = 0; k < 2; ++k) dst[n][k] = *(const PG8_LAS bf16x8*)(lds + PG8_SB(b, h) + boff + n * 2048 + k * 1024); } while (0)
; #define PG8_MMA(ai, bj, At, Bt) do { __builtin_amdgcn_s_setprio(1); _Pragma("unroll") for (int m = 0; m < 4; ++m) _Pragma("unroll") for (int n = 0; n < 2; ++n) _Pragma("unroll") for (int k = 0; k < 2; ++k) \
;         acc[ai][bj][m][n] = __builtin_amdgcn_mfma_f32_16x16x32_bf16(Bt[n][k], At[m][k], acc[ai][bj][m][n], 0, 0, 0); __builtin_amdgcn_s_setprio(0); } while (0)
; #define PG8_WAIT_V(n) asm volatile("s_waitcnt vmcnt(" #n ")" ::: "memory")
; #define PG8_WAIT_L(n) asm volatile("s_waitcnt lgkmcnt(" #n ")" ::: "memory")
; template <class Epi, class Sched, bool ALIGN_EPI = false, bool SP2 = false>
; __device__ __forceinline__ void gemm_phase(PG8_LAS unsigned char* lds, const Gemm g, const Sched& S, const Epi& E) {
;     ...
;             const bool last = (t == nt - 2);
;             const char* a1 = cA + (size_t)(t + 1) * kstep;
;             const char* a2 = last ? nA : cA + (size_t)(t + 2) * kstep; const char* b2 = last ? nB : cB + (size_t)(t + 2) * kstep;
;             const char* a3 = a2 + kstep; const char* b3 = b2 + kstep;
;             if (last && has_next) S.a_ready(nxt);
;             if constexpr (SP2) {
;             PG8_LDB(B0, 0, 0); PG8_LDB(B1, 0, 1); PG8_SCHED; PG8_LDA(At, 0, 0); PG8_STAGE(PG8_SA(1, 1), a1 + hstep, voffA);
;             PG8_WAIT_V(8); PG8_WAIT_L(0); PG8_BAR; PG8_MMA(0, 0, At, B0); PG8_MMA(0, 1, At, B1); PG8_BAR; PG8_SCHED;
;             PG8_LDA(At, 0, 1); PG8_STAGE(PG8_SB(0, 0), b2, voffB); PG8_STAGE(PG8_SB(0, 1), b2 + hstep, voffB); PG8_STAGE(PG8_SA(0, 0), a2, voffA);
;             PG8_WAIT_V(8); PG8_WAIT_L(0); PG8_BAR; PG8_MMA(1, 0, At, B0); PG8_MMA(1, 1, At, B1); PG8_BAR; PG8_SCHED;
.LBB0_579:
	s_add_u32 s18, s16, 0xfffc0080
	s_addc_u32 s19, s17, -1
	s_add_i32 s38, 0, 0x10000
	s_cmp_eq_u32 s37, 12
	s_cselect_b32 s21, s11, s19
	s_cselect_b32 s20, s33, s18
	v_add_u32_e32 v0, s38, v150
	s_cselect_b32 s19, s9, s36
	s_cselect_b32 s18, s34, s35
	s_add_i32 s40, 0, 0x14000
	ds_read_b128 v[144:147], v0
	ds_read_b128 v[152:155], v0 offset:1024
	ds_read_b128 v[156:159], v0 offset:2048
	ds_read_b128 v[178:181], v0 offset:3072
	v_add_u32_e32 v0, s40, v150
	ds_read_b128 v[182:185], v0
	ds_read_b128 v[200:203], v0 offset:1024
	ds_read_b128 v[204:207], v0 offset:2048
	ds_read_b128 v[208:211], v0 offset:3072
	v_lshl_add_u64 v[148:149], s[16:17], 0, v[140:141]
	s_add_i32 m0, s23, 0xc000
	ds_read_b128 v[212:215], v151
	ds_read_b128 v[216:219], v151 offset:1024
	ds_read_b128 v[220:223], v151 offset:2048
	ds_read_b128 v[224:227], v151 offset:3072
	ds_read_b128 v[228:231], v151 offset:4096
	ds_read_b128 v[232:235], v151 offset:5120
	ds_read_b128 v[236:239], v151 offset:6144
	ds_read_b128 v[244:247], v151 offset:7168
	global_load_lds_dwordx4 v[148:149], off
	v_lshl_add_u64 v[148:149], s[16:17], 0, v[142:143]
	s_add_i32 m0, s23, 0xe000
	s_nop 0
	global_load_lds_dwordx4 v[148:149], off
	s_waitcnt vmcnt(8)
	s_waitcnt lgkmcnt(0)
	s_barrier
	s_setprio 1
	s_waitcnt lgkmcnt(0)
	v_mfma_f32_16x16x32_bf16 v[126:129], v[144:147], v[212:215], v[126:129]
	v_mfma_f32_16x16x32_bf16 v[122:125], v[156:159], v[212:215], v[122:125]
	v_mfma_f32_16x16x32_bf16 v[110:113], v[144:147], v[220:223], v[110:113]
	v_mfma_f32_16x16x32_bf16 v[106:109], v[156:159], v[220:223], v[106:109]
	v_mfma_f32_16x16x32_bf16 v[94:97], v[144:147], v[228:231], v[94:97]
	v_mfma_f32_16x16x32_bf16 v[90:93], v[156:159], v[228:231], v[90:93]
	v_mfma_f32_16x16x32_bf16 v[78:81], v[144:147], v[236:239], v[78:81]
	v_mfma_f32_16x16x32_bf16 v[74:77], v[156:159], v[236:239], v[74:77]
	v_mfma_f32_16x16x32_bf16 v[126:129], v[152:155], v[216:219], v[126:129]
	v_mfma_f32_16x16x32_bf16 v[122:125], v[178:181], v[216:219], v[122:125]
	v_mfma_f32_16x16x32_bf16 v[110:113], v[152:155], v[224:227], v[110:113]
	v_mfma_f32_16x16x32_bf16 v[106:109], v[178:181], v[224:227], v[106:109]
	v_mfma_f32_16x16x32_bf16 v[94:97], v[152:155], v[232:235], v[94:97]
	v_mfma_f32_16x16x32_bf16 v[90:93], v[178:181], v[232:235], v[90:93]
	v_mfma_f32_16x16x32_bf16 v[78:81], v[152:155], v[244:247], v[78:81]
	v_mfma_f32_16x16x32_bf16 v[74:77], v[178:181], v[244:247], v[74:77]
	s_setprio 0
	s_setprio 1
	v_mfma_f32_16x16x32_bf16 v[118:121], v[182:185], v[212:215], v[118:121]
	v_mfma_f32_16x16x32_bf16 v[114:117], v[204:207], v[212:215], v[114:117]
	v_mfma_f32_16x16x32_bf16 v[102:105], v[182:185], v[220:223], v[102:105]
	v_mfma_f32_16x16x32_bf16 v[98:101], v[204:207], v[220:223], v[98:101]
	v_mfma_f32_16x16x32_bf16 v[86:89], v[182:185], v[228:231], v[86:89]
	v_mfma_f32_16x16x32_bf16 v[82:85], v[204:207], v[228:231], v[82:85]
	v_mfma_f32_16x16x32_bf16 v[70:73], v[182:185], v[236:239], v[70:73]
	v_mfma_f32_16x16x32_bf16 v[66:69], v[204:207], v[236:239], v[66:69]
	v_mfma_f32_16x16x32_bf16 v[118:121], v[200:203], v[216:219], v[118:121]
	v_mfma_f32_16x16x32_bf16 v[114:117], v[208:211], v[216:219], v[114:117]
	v_mfma_f32_16x16x32_bf16 v[102:105], v[200:203], v[224:227], v[102:105]
	v_mfma_f32_16x16x32_bf16 v[98:101], v[208:211], v[224:227], v[98:101]
	v_mfma_f32_16x16x32_bf16 v[86:89], v[200:203], v[232:235], v[86:89]
	v_mfma_f32_16x16x32_bf16 v[82:85], v[208:211], v[232:235], v[82:85]
	v_mfma_f32_16x16x32_bf16 v[70:73], v[200:203], v[244:247], v[70:73]
	v_mfma_f32_16x16x32_bf16 v[66:69], v[208:211], v[244:247], v[66:69]
	s_setprio 0
	s_barrier
	s_add_i32 s38, s38, s22
	v_lshl_add_u64 v[148:149], s[18:19], 0, v[134:135]
	s_mov_b32 m0, s38
	ds_read_b128 v[212:215], v151 offset:16384
	ds_read_b128 v[216:219], v151 offset:17408
	ds_read_b128 v[220:223], v151 offset:18432
	ds_read_b128 v[224:227], v151 offset:19456
	ds_read_b128 v[228:231], v151 offset:20480
	ds_read_b128 v[232:235], v151 offset:21504
	ds_read_b128 v[236:239], v151 offset:22528
	ds_read_b128 v[244:247], v151 offset:23552
	global_load_lds_dwordx4 v[148:149], off
	s_add_i32 m0, s38, 0x2000
	s_add_u32 s38, s18, 0x10000
	v_lshl_add_u64 v[160:161], s[18:19], 0, v[130:131]
	s_addc_u32 s39, s19, 0
	s_add_i32 s40, s40, s22
	global_load_lds_dwordx4 v[160:161], off
	v_lshl_add_u64 v[162:163], s[38:39], 0, v[134:135]
	s_mov_b32 m0, s40
	v_lshl_add_u64 v[164:165], s[20:21], 0, v[132:133]
	global_load_lds_dwordx4 v[162:163], off
	v_lshl_add_u64 v[162:163], s[38:39], 0, v[130:131]
	s_add_i32 m0, s40, 0x2000
	s_nop 0
	global_load_lds_dwordx4 v[162:163], off
	v_lshl_add_u64 v[162:163], s[20:21], 0, v[136:137]
	s_mov_b32 m0, s23
	s_nop 0
	global_load_lds_dwordx4 v[162:163], off
	s_mov_b32 m0, s24
	s_nop 0
	global_load_lds_dwordx4 v[164:165], off
	s_waitcnt vmcnt(8)
	s_waitcnt lgkmcnt(0)
	s_barrier
; #define PG8_STAGE(bufoff, gbase, voff) do { _Pragma("unroll") for (int _i = 0; _i < 2; ++_i) \
;         __builtin_amdgcn_global_load_lds((const unsigned*)((const char*)(gbase) + (voff)[_i]), (PG8_LAS unsigned*)(lds + (bufoff) + ldsw + _i * 8192), 16, 0, 0); } while (0)
; #define PG8_LDA(dst, b, h) do { _Pragma("unroll") for (int m = 0; m < 4; ++m) _Pragma("unroll") for (int k = 0; k < 2; ++k) dst[m][k] = *(const PG8_LAS bf16x8*)(lds + PG8_SA(b, h) + aoff + m * 2048 + k * 1024); } while (0)
; #define PG8_LDB(dst, b, h) do { _Pragma("unroll") for (int n = 0; n < 2; ++n) _Pragma("unroll") for (int k = 0; k < 2; ++k) dst[n][k] = *(const PG8_LAS bf16x8*)(lds + PG8_SB(b, h) + boff + n * 2048 + k * 1024); } while (0)
; #define PG8_MMA(ai, bj, At, Bt) do { __builtin_amdgcn_s_setprio(1); _Pragma("unroll") for (int m = 0; m < 4; ++m) _Pragma("unroll") for (int n = 0; n < 2; ++n) _Pragma("unroll") for (int k = 0; k < 2; ++k) \
;         acc[ai][bj][m][n] = __builtin_amdgcn_mfma_f32_16x16x32_bf16(Bt[n][k], At[m][k], acc[ai][bj][m][n], 0, 0, 0); __builtin_amdgcn_s_setprio(0); } while (0)
; #define PG8_WAIT_V(n) asm volatile("s_waitcnt vmcnt(" #n ")" ::: "memory")
; #define PG8_WAIT_L(n) asm volatile("s_waitcnt lgkmcnt(" #n ")" ::: "memory")
; #define PG8_BAR __builtin_amdgcn_s_barrier()
; #define PG8_SCHED __builtin_amdgcn_sched_barrier(0)
; template <class Epi, class Sched, bool ALIGN_EPI = false, bool SP2 = false>
; __device__ __forceinline__ void gemm_phase(PG8_LAS unsigned char* lds, const Gemm g, const Sched& S, const Epi& E) {
;     ...
;             PG8_WAIT_V(8); PG8_WAIT_L(0); PG8_BAR; PG8_MMA(1, 0, At, B0); PG8_MMA(1, 1, At, B1); PG8_BAR; PG8_SCHED;
;             PG8_LDB(B0, 1, 0); PG8_LDB(B1, 1, 1); PG8_SCHED; PG8_LDA(At, 1, 0); PG8_STAGE(PG8_SA(0, 1), a2 + hstep, voffA);
;             PG8_WAIT_V(8); PG8_WAIT_L(0); PG8_BAR; PG8_MMA(0, 0, At, B0); PG8_MMA(0, 1, At, B1); PG8_BAR; PG8_SCHED;
;             PG8_LDA(At, 1, 1); PG8_STAGE(PG8_SB(1, 0), b3, voffB); PG8_STAGE(PG8_SB(1, 1), b3 + hstep, voffB); PG8_STAGE(PG8_SA(1, 0), a3, voffA);
	s_setprio 1
	s_waitcnt lgkmcnt(0)
	v_mfma_f32_16x16x32_bf16 v[62:65], v[144:147], v[212:215], v[62:65]
	v_mfma_f32_16x16x32_bf16 v[58:61], v[156:159], v[212:215], v[58:61]
	v_mfma_f32_16x16x32_bf16 v[46:49], v[144:147], v[220:223], v[46:49]
	v_mfma_f32_16x16x32_bf16 v[42:45], v[156:159], v[220:223], v[42:45]
	v_mfma_f32_16x16x32_bf16 v[30:33], v[144:147], v[228:231], v[30:33]
	v_mfma_f32_16x16x32_bf16 v[26:29], v[156:159], v[228:231], v[26:29]
	v_mfma_f32_16x16x32_bf16 v[14:17], v[144:147], v[236:239], v[14:17]
	v_mfma_f32_16x16x32_bf16 v[10:13], v[156:159], v[236:239], v[10:13]
	v_mfma_f32_16x16x32_bf16 v[62:65], v[152:155], v[216:219], v[62:65]
	v_mfma_f32_16x16x32_bf16 v[58:61], v[178:181], v[216:219], v[58:61]
	v_mfma_f32_16x16x32_bf16 v[46:49], v[152:155], v[224:227], v[46:49]
	v_mfma_f32_16x16x32_bf16 v[42:45], v[178:181], v[224:227], v[42:45]
	v_mfma_f32_16x16x32_bf16 v[30:33], v[152:155], v[232:235], v[30:33]
	v_mfma_f32_16x16x32_bf16 v[26:29], v[178:181], v[232:235], v[26:29]
	v_mfma_f32_16x16x32_bf16 v[14:17], v[152:155], v[244:247], v[14:17]
	v_mfma_f32_16x16x32_bf16 v[10:13], v[178:181], v[244:247], v[10:13]
	s_setprio 0
	s_setprio 1
	v_mfma_f32_16x16x32_bf16 v[54:57], v[182:185], v[212:215], v[54:57]
	v_mfma_f32_16x16x32_bf16 v[50:53], v[204:207], v[212:215], v[50:53]
	v_mfma_f32_16x16x32_bf16 v[38:41], v[182:185], v[220:223], v[38:41]
	v_mfma_f32_16x16x32_bf16 v[34:37], v[204:207], v[220:223], v[34:37]
	v_mfma_f32_16x16x32_bf16 v[22:25], v[182:185], v[228:231], v[22:25]
	v_mfma_f32_16x16x32_bf16 v[18:21], v[204:207], v[228:231], v[18:21]
	v_mfma_f32_16x16x32_bf16 v[6:9], v[182:185], v[236:239], v[6:9]
	v_mfma_f32_16x16x32_bf16 v[2:5], v[204:207], v[236:239], v[2:5]
	v_mfma_f32_16x16x32_bf16 v[54:57], v[200:203], v[216:219], v[54:57]
	v_mfma_f32_16x16x32_bf16 v[50:53], v[208:211], v[216:219], v[50:53]
	v_mfma_f32_16x16x32_bf16 v[38:41], v[200:203], v[224:227], v[38:41]
	v_mfma_f32_16x16x32_bf16 v[34:37], v[208:211], v[224:227], v[34:37]
	v_mfma_f32_16x16x32_bf16 v[22:25], v[200:203], v[232:235], v[22:25]
	v_mfma_f32_16x16x32_bf16 v[18:21], v[208:211], v[232:235], v[18:21]
	v_mfma_f32_16x16x32_bf16 v[6:9], v[200:203], v[244:247], v[6:9]
	v_mfma_f32_16x16x32_bf16 v[2:5], v[208:211], v[244:247], v[2:5]
	s_setprio 0
	s_barrier
	s_add_i32 s38, 0, 0x18000
	v_add_u32_e32 v0, s38, v150
	s_add_i32 s39, 0, 0x1c000
	ds_read_b128 v[144:147], v0
	ds_read_b128 v[152:155], v0 offset:1024
	ds_read_b128 v[156:159], v0 offset:2048
	ds_read_b128 v[178:181], v0 offset:3072
	v_add_u32_e32 v0, s39, v150
	ds_read_b128 v[182:185], v0
	ds_read_b128 v[200:203], v0 offset:1024
	ds_read_b128 v[204:207], v0 offset:2048
	ds_read_b128 v[208:211], v0 offset:3072
	s_add_u32 s20, s20, 0x40000
	s_addc_u32 s21, s21, 0
	s_mov_b32 m0, s25
	v_lshl_add_u64 v[186:187], s[20:21], 0, v[136:137]
	ds_read_b128 v[212:215], v151 offset:32768
	ds_read_b128 v[216:219], v151 offset:33792
	ds_read_b128 v[220:223], v151 offset:34816
	ds_read_b128 v[224:227], v151 offset:35840
	ds_read_b128 v[228:231], v151 offset:36864
	ds_read_b128 v[232:235], v151 offset:37888
	ds_read_b128 v[236:239], v151 offset:38912
	ds_read_b128 v[244:247], v151 offset:39936
	global_load_lds_dwordx4 v[186:187], off
	v_lshl_add_u64 v[186:187], s[20:21], 0, v[132:133]
	s_mov_b32 m0, s26
	s_nop 0
	global_load_lds_dwordx4 v[186:187], off
	s_waitcnt vmcnt(8)
	s_waitcnt lgkmcnt(0)
	s_barrier
	s_setprio 1
	s_waitcnt lgkmcnt(0)
	v_mfma_f32_16x16x32_bf16 v[126:129], v[144:147], v[212:215], v[126:129]
	v_mfma_f32_16x16x32_bf16 v[122:125], v[156:159], v[212:215], v[122:125]
	v_mfma_f32_16x16x32_bf16 v[110:113], v[144:147], v[220:223], v[110:113]
	v_mfma_f32_16x16x32_bf16 v[106:109], v[156:159], v[220:223], v[106:109]
	v_mfma_f32_16x16x32_bf16 v[94:97], v[144:147], v[228:231], v[94:97]
	v_mfma_f32_16x16x32_bf16 v[90:93], v[156:159], v[228:231], v[90:93]
	v_mfma_f32_16x16x32_bf16 v[78:81], v[144:147], v[236:239], v[78:81]
	v_mfma_f32_16x16x32_bf16 v[74:77], v[156:159], v[236:239], v[74:77]
	v_mfma_f32_16x16x32_bf16 v[126:129], v[152:155], v[216:219], v[126:129]
	v_mfma_f32_16x16x32_bf16 v[122:125], v[178:181], v[216:219], v[122:125]
	v_mfma_f32_16x16x32_bf16 v[110:113], v[152:155], v[224:227], v[110:113]
	v_mfma_f32_16x16x32_bf16 v[106:109], v[178:181], v[224:227], v[106:109]
	v_mfma_f32_16x16x32_bf16 v[94:97], v[152:155], v[232:235], v[94:97]
	v_mfma_f32_16x16x32_bf16 v[90:93], v[178:181], v[232:235], v[90:93]
	v_mfma_f32_16x16x32_bf16 v[78:81], v[152:155], v[244:247], v[78:81]
	v_mfma_f32_16x16x32_bf16 v[74:77], v[178:181], v[244:247], v[74:77]
	s_setprio 0
	s_setprio 1
	v_mfma_f32_16x16x32_bf16 v[118:121], v[182:185], v[212:215], v[118:121]
	v_mfma_f32_16x16x32_bf16 v[114:117], v[204:207], v[212:215], v[114:117]
	v_mfma_f32_16x16x32_bf16 v[102:105], v[182:185], v[220:223], v[102:105]
	v_mfma_f32_16x16x32_bf16 v[98:101], v[204:207], v[220:223], v[98:101]
	v_mfma_f32_16x16x32_bf16 v[86:89], v[182:185], v[228:231], v[86:89]
	v_mfma_f32_16x16x32_bf16 v[82:85], v[204:207], v[228:231], v[82:85]
	v_mfma_f32_16x16x32_bf16 v[70:73], v[182:185], v[236:239], v[70:73]
	v_mfma_f32_16x16x32_bf16 v[66:69], v[204:207], v[236:239], v[66:69]
	v_mfma_f32_16x16x32_bf16 v[118:121], v[200:203], v[216:219], v[118:121]
	v_mfma_f32_16x16x32_bf16 v[114:117], v[208:211], v[216:219], v[114:117]
	v_mfma_f32_16x16x32_bf16 v[102:105], v[200:203], v[224:227], v[102:105]
	v_mfma_f32_16x16x32_bf16 v[98:101], v[208:211], v[224:227], v[98:101]
	v_mfma_f32_16x16x32_bf16 v[86:89], v[200:203], v[232:235], v[86:89]
	v_mfma_f32_16x16x32_bf16 v[82:85], v[208:211], v[232:235], v[82:85]
	v_mfma_f32_16x16x32_bf16 v[70:73], v[200:203], v[244:247], v[70:73]
	v_mfma_f32_16x16x32_bf16 v[66:69], v[208:211], v[244:247], v[66:69]
	s_setprio 0
	s_barrier
; #define PG8_STAGE(bufoff, gbase, voff) do { _Pragma("unroll") for (int _i = 0; _i < 2; ++_i) \
;         __builtin_amdgcn_global_load_lds((const unsigned*)((const char*)(gbase) + (voff)[_i]), (PG8_LAS unsigned*)(lds + (bufoff) + ldsw + _i * 8192), 16, 0, 0); } while (0)
; #define PG8_LDA(dst, b, h) do { _Pragma("unroll") for (int m = 0; m < 4; ++m) _Pragma("unroll") for (int k = 0; k < 2; ++k) dst[m][k] = *(const PG8_LAS bf16x8*)(lds + PG8_SA(b, h) + aoff + m * 2048 + k * 1024); } while (0)
; #define PG8_MMA(ai, bj, At, Bt) do { __builtin_amdgcn_s_setprio(1); _Pragma("unroll") for (int m = 0; m < 4; ++m) _Pragma("unroll") for (int n = 0; n < 2; ++n) _Pragma("unroll") for (int k = 0; k < 2; ++k) \
;         acc[ai][bj][m][n] = __builtin_amdgcn_mfma_f32_16x16x32_bf16(Bt[n][k], At[m][k], acc[ai][bj][m][n], 0, 0, 0); __builtin_amdgcn_s_setprio(0); } while (0)
; #define PG8_WAIT_V(n) asm volatile("s_waitcnt vmcnt(" #n ")" ::: "memory")
; #define PG8_WAIT_L(n) asm volatile("s_waitcnt lgkmcnt(" #n ")" ::: "memory")
; #define PG8_BAR __builtin_amdgcn_s_barrier()
; #define PG8_SCHED __builtin_amdgcn_sched_barrier(0)
; DI size_t pidx(size_t row, int col) { return (size_t)(col >> 8) * ((size_t)TH * 256) + row * 256 + (size_t)(col & 255); }
; template <class Epi, class Sched, bool ALIGN_EPI = false, bool SP2 = false>
; __device__ __forceinline__ void gemm_phase(PG8_LAS unsigned char* lds, const Gemm g, const Sched& S, const Epi& E) {
;     ...
;             PG8_LDA(At, 1, 1); PG8_STAGE(PG8_SB(1, 0), b3, voffB); PG8_STAGE(PG8_SB(1, 1), b3 + hstep, voffB); PG8_STAGE(PG8_SA(1, 0), a3, voffA);
;             PG8_WAIT_V(8); PG8_WAIT_L(0); PG8_BAR; PG8_MMA(1, 0, At, B0); PG8_MMA(1, 1, At, B1); PG8_BAR; PG8_SCHED;
;     DI void operator()(const f32x4 (&acc)[2][2][4][2], const Unit& u, int wr, int wc, int fr, int fq) const {
;         const int row0 = u.pm * 256 + wr * 64 + fr, col0 = u.pn * 256 + wc * 32 + 8 * fq;
; #pragma unroll
;         for (int ai = 0; ai < 2; ++ai)
; #pragma unroll
;             for (int m = 0; m < 4; ++m) { const size_t r = (size_t)(row0 + ai * 128 + m * 16);
; #pragma unroll
;                 for (int bj = 0; bj < 2; ++bj) { const int c = col0 + bj * 128; const v4u g = *(const v4u*)(P + pidx(r, 8704 + c)); const v4u y = *(const v4u*)(Y + r * 1024 + c);
	s_add_i32 s20, s38, s22
	v_lshl_add_u64 v[148:149], v[148:149], 0, s[84:85]
	s_mov_b32 m0, s20
	ds_read_b128 v[212:215], v151 offset:49152
	ds_read_b128 v[216:219], v151 offset:50176
	ds_read_b128 v[220:223], v151 offset:51200
	ds_read_b128 v[224:227], v151 offset:52224
	ds_read_b128 v[228:231], v151 offset:53248
	ds_read_b128 v[232:235], v151 offset:54272
	ds_read_b128 v[236:239], v151 offset:55296
	ds_read_b128 v[244:247], v151 offset:56320
	global_load_lds_dwordx4 v[148:149], off
	s_add_i32 m0, s20, 0x2000
	s_add_u32 s18, s18, 0x10080
	v_lshl_add_u64 v[148:149], v[160:161], 0, s[84:85]
	s_addc_u32 s19, s19, 0
	s_add_i32 s20, s39, s22
	global_load_lds_dwordx4 v[148:149], off
	v_lshl_add_u64 v[148:149], s[18:19], 0, v[134:135]
	s_mov_b32 m0, s20
	s_nop 0
	global_load_lds_dwordx4 v[148:149], off
	v_lshl_add_u64 v[148:149], s[18:19], 0, v[130:131]
	s_add_i32 m0, s20, 0x2000
	s_nop 0
	global_load_lds_dwordx4 v[148:149], off
	v_lshl_add_u64 v[148:149], v[162:163], 0, s[84:85]
	s_mov_b32 m0, s27
	s_nop 0
	global_load_lds_dwordx4 v[148:149], off
	v_lshl_add_u64 v[148:149], v[164:165], 0, s[84:85]
	s_mov_b32 m0, s28
	s_nop 0
	global_load_lds_dwordx4 v[148:149], off
	s_waitcnt vmcnt(8)
	s_waitcnt lgkmcnt(0)
	s_barrier
	s_setprio 1
	s_waitcnt lgkmcnt(0)
	v_mfma_f32_16x16x32_bf16 v[62:65], v[144:147], v[212:215], v[62:65]
	v_mfma_f32_16x16x32_bf16 v[58:61], v[156:159], v[212:215], v[58:61]
	v_mfma_f32_16x16x32_bf16 v[46:49], v[144:147], v[220:223], v[46:49]
	v_mfma_f32_16x16x32_bf16 v[42:45], v[156:159], v[220:223], v[42:45]
	v_mfma_f32_16x16x32_bf16 v[30:33], v[144:147], v[228:231], v[30:33]
	v_mfma_f32_16x16x32_bf16 v[26:29], v[156:159], v[228:231], v[26:29]
	v_mfma_f32_16x16x32_bf16 v[14:17], v[144:147], v[236:239], v[14:17]
	v_mfma_f32_16x16x32_bf16 v[10:13], v[156:159], v[236:239], v[10:13]
	v_mfma_f32_16x16x32_bf16 v[62:65], v[152:155], v[216:219], v[62:65]
	v_mfma_f32_16x16x32_bf16 v[58:61], v[178:181], v[216:219], v[58:61]
	v_mfma_f32_16x16x32_bf16 v[46:49], v[152:155], v[224:227], v[46:49]
	v_mfma_f32_16x16x32_bf16 v[42:45], v[178:181], v[224:227], v[42:45]
	v_mfma_f32_16x16x32_bf16 v[30:33], v[152:155], v[232:235], v[30:33]
	v_mfma_f32_16x16x32_bf16 v[26:29], v[178:181], v[232:235], v[26:29]
	v_mfma_f32_16x16x32_bf16 v[14:17], v[152:155], v[244:247], v[14:17]
	v_mfma_f32_16x16x32_bf16 v[10:13], v[178:181], v[244:247], v[10:13]
	s_setprio 0
	s_setprio 1
	v_mfma_f32_16x16x32_bf16 v[54:57], v[182:185], v[212:215], v[54:57]
	v_mfma_f32_16x16x32_bf16 v[50:53], v[204:207], v[212:215], v[50:53]
	v_mfma_f32_16x16x32_bf16 v[38:41], v[182:185], v[220:223], v[38:41]
	v_mfma_f32_16x16x32_bf16 v[34:37], v[204:207], v[220:223], v[34:37]
	v_mfma_f32_16x16x32_bf16 v[22:25], v[182:185], v[228:231], v[22:25]
	v_mfma_f32_16x16x32_bf16 v[18:21], v[204:207], v[228:231], v[18:21]
	v_mfma_f32_16x16x32_bf16 v[6:9], v[182:185], v[236:239], v[6:9]
	v_mfma_f32_16x16x32_bf16 v[2:5], v[204:207], v[236:239], v[2:5]
	v_mfma_f32_16x16x32_bf16 v[54:57], v[200:203], v[216:219], v[54:57]
	v_mfma_f32_16x16x32_bf16 v[50:53], v[208:211], v[216:219], v[50:53]
	v_mfma_f32_16x16x32_bf16 v[38:41], v[200:203], v[224:227], v[38:41]
	v_mfma_f32_16x16x32_bf16 v[34:37], v[208:211], v[224:227], v[34:37]
	v_mfma_f32_16x16x32_bf16 v[22:25], v[200:203], v[232:235], v[22:25]
	v_mfma_f32_16x16x32_bf16 v[18:21], v[208:211], v[232:235], v[18:21]
	v_mfma_f32_16x16x32_bf16 v[6:9], v[200:203], v[244:247], v[6:9]
	v_mfma_f32_16x16x32_bf16 v[2:5], v[208:211], v[244:247], v[2:5]
	s_setprio 0
	s_barrier
	s_add_i32 s37, s37, 2
	s_add_u32 s16, s16, 0x100
	s_addc_u32 s17, s17, 0
	s_add_u32 s35, s35, 0x100
	s_addc_u32 s36, s36, 0
	s_cmp_gt_u32 s37, 13
	s_cbranch_scc0 .LBB0_579
	s_and_b64 vcc, exec, s[6:7]
	s_cbranch_vccz .LBB0_582
	s_barrier
.LBB0_582:
	s_lshl_b32 s9, s30, 8
	v_or_b32_e32 v146, s9, v138
	s_addk_i32 s9, 0x2200
	s_ashr_i32 s16, s9, 8
	s_ashr_i32 s17, s16, 31
	v_lshl_add_u32 v144, s31, 8, v139
	s_lshl_b64 s[16:17], s[16:17], 24
	v_ashrrev_i32_e32 v145, 31, v144
	s_add_u32 s16, s86, s16
	v_lshlrev_b64 v[148:149], 11, v[144:145]
	v_ashrrev_i32_e32 v147, 31, v146
	v_lshlrev_b64 v[156:157], 9, v[144:145]
	s_addc_u32 s17, s87, s17
	v_lshl_add_u64 v[148:149], s[88:89], 0, v[148:149]
	v_lshlrev_b64 v[146:147], 1, v[146:147]
	v_lshl_add_u64 v[160:161], s[16:17], 0, v[156:157]
	v_lshlrev_b32_e32 v0, 1, v138
	v_lshl_add_u64 v[148:149], v[148:149], 0, v[146:147]
	v_lshl_add_u64 v[156:157], v[160:161], 0, v[0:1]
	s_andn2_b64 vcc, exec, s[4:5]
	s_lshl_b32 s9, s30, 8
	v_or_b32_e32 v186, s9, v138
	v_lshrrev_b32_e32 v182, 5, v138
	v_lshlrev_b32_e32 v182, 6, v182
	v_and_b32_e32 v183, 24, v138
	v_or_b32_e32 v182, v182, v183
	v_bfe_u32 v183, v144, 3, 1
	v_lshl_or_b32 v182, v183, 5, v182
	v_and_b32_e32 v184, 0xfffffff7, v144
	v_ashrrev_i32_e32 v185, 31, v184
	v_lshlrev_b64 v[178:179], 9, v[184:185]
	v_lshl_add_u64 v[178:179], s[16:17], 0, v[178:179]
	v_lshlrev_b32_e32 v180, 1, v182
	v_add_u32_e32 v180, 0x1000, v180
	v_mov_b32_e32 v181, 0
	v_lshl_add_u64 v[178:179], v[178:179], 0, v[180:181]
	v_lshlrev_b64 v[184:185], 11, v[184:185]
	v_lshl_add_u64 v[184:185], s[88:89], 0, v[184:185]
	v_and_b32_e32 v180, 0xffffff00, v186
	v_or_b32_e32 v180, v180, v182
	v_lshlrev_b32_e32 v180, 1, v180
	v_lshl_add_u64 v[184:185], v[184:185], 0, v[180:181]
	s_mov_b64 s[98:99], 0x0
	v_lshl_add_u64 v[180:181], v[178:179], 0, s[98:99]
	global_load_dwordx4 v[200:203], v[180:181], off offset:-4096
	global_load_dwordx4 v[204:207], v[180:181], off
	s_mov_b64 s[98:99], 0x0
	v_lshl_add_u64 v[180:181], v[184:185], 0, s[98:99]
	global_load_dwordx4 v[208:211], v[180:181], off
	s_mov_b64 s[98:99], 0x4000
	v_lshl_add_u64 v[180:181], v[184:185], 0, s[98:99]
	global_load_dwordx4 v[212:215], v[180:181], off
	s_mov_b64 s[98:99], 0x2000
	v_lshl_add_u64 v[180:181], v[178:179], 0, s[98:99]
	global_load_dwordx4 v[216:219], v[180:181], off offset:-4096
	global_load_dwordx4 v[220:223], v[180:181], off
	s_mov_b64 s[98:99], 0x8000
	v_lshl_add_u64 v[180:181], v[184:185], 0, s[98:99]
	global_load_dwordx4 v[224:227], v[180:181], off
	s_mov_b64 s[98:99], 0xc000
	v_lshl_add_u64 v[180:181], v[184:185], 0, s[98:99]
	global_load_dwordx4 v[228:231], v[180:181], off
	s_waitcnt vmcnt(4)
; DI size_t pidx(size_t row, int col) { return (size_t)(col >> 8) * ((size_t)TH * 256) + row * 256 + (size_t)(col & 255); }
; DI float lo_f(unsigned u) { return __uint_as_float(u << 16); }
; DI float hi_f(unsigned u) { return __uint_as_float(u & 0xffff0000u); }
; DI unsigned pk2(float lo, float hi) { return pg8::cvt_pk_bf16(lo, hi); }
;     DI void operator()(const f32x4 (&acc)[2][2][4][2], const Unit& u, int wr, int wc, int fr, int fq) const {
;         const int row0 = u.pm * 256 + wr * 64 + fr, col0 = u.pn * 256 + wc * 32 + 8 * fq;
; #pragma unroll
;         for (int ai = 0; ai < 2; ++ai)
; #pragma unroll
;             for (int m = 0; m < 4; ++m) { const size_t r = (size_t)(row0 + ai * 128 + m * 16);
; #pragma unroll
;                 for (int bj = 0; bj < 2; ++bj) { const int c = col0 + bj * 128; const v4u g = *(const v4u*)(P + pidx(r, 8704 + c)); const v4u y = *(const v4u*)(Y + r * 1024 + c);
;                     const f32x4 a0 = acc[ai][bj][m][0], a1 = acc[ai][bj][m][1];
;                     v4u w; w.x = pk2(lo_f(y.x) + a0[0] * lo_f(g.x), hi_f(y.x) + a0[1] * hi_f(g.x)); w.y = pk2(lo_f(y.y) + a0[2] * lo_f(g.y), hi_f(y.y) + a0[3] * hi_f(g.y));
;                     w.z = pk2(lo_f(y.z) + a1[0] * lo_f(g.z), hi_f(y.z) + a1[1] * hi_f(g.z)); w.w = pk2(lo_f(y.w) + a1[2] * lo_f(g.w), hi_f(y.w) + a1[3] * hi_f(g.w));
;                     *(v4u*)(Y + r * 1024 + c) = w; } }
	v_mov_b32_e32 v244, v200
	v_mov_b32_e32 v245, v201
	v_mov_b32_e32 v246, v202
	v_mov_b32_e32 v247, v203
	v_mov_b32_dpp v200, v204 row_shr:8 row_mask:0xf bank_mask:0xc
	v_mov_b32_dpp v201, v205 row_shr:8 row_mask:0xf bank_mask:0xc
	v_mov_b32_dpp v202, v206 row_shr:8 row_mask:0xf bank_mask:0xc
	v_mov_b32_dpp v203, v207 row_shr:8 row_mask:0xf bank_mask:0xc
	v_mov_b32_dpp v204, v244 row_shl:8 row_mask:0xf bank_mask:0x3
	v_mov_b32_dpp v205, v245 row_shl:8 row_mask:0xf bank_mask:0x3
	v_mov_b32_dpp v206, v246 row_shl:8 row_mask:0xf bank_mask:0x3
	v_mov_b32_dpp v207, v247 row_shl:8 row_mask:0xf bank_mask:0x3
	v_mov_b32_e32 v244, v208
	v_mov_b32_e32 v245, v209
	v_mov_b32_e32 v246, v210
	v_mov_b32_e32 v247, v211
	v_mov_b32_dpp v208, v212 row_shr:8 row_mask:0xf bank_mask:0xc
	v_mov_b32_dpp v209, v213 row_shr:8 row_mask:0xf bank_mask:0xc
	v_mov_b32_dpp v210, v214 row_shr:8 row_mask:0xf bank_mask:0xc
	v_mov_b32_dpp v211, v215 row_shr:8 row_mask:0xf bank_mask:0xc
	v_mov_b32_dpp v212, v244 row_shl:8 row_mask:0xf bank_mask:0x3
	v_mov_b32_dpp v213, v245 row_shl:8 row_mask:0xf bank_mask:0x3
	v_mov_b32_dpp v214, v246 row_shl:8 row_mask:0xf bank_mask:0x3
	v_mov_b32_dpp v215, v247 row_shl:8 row_mask:0xf bank_mask:0x3
	v_lshlrev_b32_e32 v180, 16, v208
	v_and_b32_e32 v181, 0xffff0000, v208
	v_lshlrev_b32_e32 v182, 16, v200
	v_and_b32_e32 v183, 0xffff0000, v200
	v_fmac_f32_e32 v180, v126, v182
	v_fmac_f32_e32 v181, v127, v183
	v_cvt_pk_bf16_f32 v232, v180, v181
	v_lshlrev_b32_e32 v180, 16, v209
	v_and_b32_e32 v181, 0xffff0000, v209
	v_lshlrev_b32_e32 v182, 16, v201
	v_and_b32_e32 v183, 0xffff0000, v201
	v_fmac_f32_e32 v180, v128, v182
	v_fmac_f32_e32 v181, v129, v183
	v_cvt_pk_bf16_f32 v233, v180, v181
	v_lshlrev_b32_e32 v180, 16, v210
	v_and_b32_e32 v181, 0xffff0000, v210
	v_lshlrev_b32_e32 v182, 16, v202
	v_and_b32_e32 v183, 0xffff0000, v202
	v_fmac_f32_e32 v180, v122, v182
	v_fmac_f32_e32 v181, v123, v183
	v_cvt_pk_bf16_f32 v234, v180, v181
	v_lshlrev_b32_e32 v180, 16, v211
	v_and_b32_e32 v181, 0xffff0000, v211
	v_lshlrev_b32_e32 v182, 16, v203
	v_and_b32_e32 v183, 0xffff0000, v203
	v_fmac_f32_e32 v180, v124, v182
	v_fmac_f32_e32 v181, v125, v183
	v_cvt_pk_bf16_f32 v235, v180, v181
	v_lshlrev_b32_e32 v180, 16, v212
	v_and_b32_e32 v181, 0xffff0000, v212
	v_lshlrev_b32_e32 v182, 16, v204
	v_and_b32_e32 v183, 0xffff0000, v204
	v_fmac_f32_e32 v180, v118, v182
	v_fmac_f32_e32 v181, v119, v183
	v_cvt_pk_bf16_f32 v236, v180, v181
	v_lshlrev_b32_e32 v180, 16, v213
	v_and_b32_e32 v181, 0xffff0000, v213
	v_lshlrev_b32_e32 v182, 16, v205
	v_and_b32_e32 v183, 0xffff0000, v205
	v_fmac_f32_e32 v180, v120, v182
	v_fmac_f32_e32 v181, v121, v183
	v_cvt_pk_bf16_f32 v237, v180, v181
	v_lshlrev_b32_e32 v180, 16, v214
	v_and_b32_e32 v181, 0xffff0000, v214
	v_lshlrev_b32_e32 v182, 16, v206
	v_and_b32_e32 v183, 0xffff0000, v206
	v_fmac_f32_e32 v180, v114, v182
	v_fmac_f32_e32 v181, v115, v183
	v_cvt_pk_bf16_f32 v238, v180, v181
	v_lshlrev_b32_e32 v180, 16, v215
	v_and_b32_e32 v181, 0xffff0000, v215
	v_lshlrev_b32_e32 v182, 16, v207
	v_and_b32_e32 v183, 0xffff0000, v207
	v_fmac_f32_e32 v180, v116, v182
	v_fmac_f32_e32 v181, v117, v183
	v_cvt_pk_bf16_f32 v239, v180, v181
	v_mov_b32_e32 v244, v236
	v_mov_b32_e32 v245, v237
	v_mov_b32_e32 v246, v238
	v_mov_b32_e32 v247, v239
	v_mov_b32_dpp v236, v232 row_shl:8 row_mask:0xf bank_mask:0x3
	v_mov_b32_dpp v237, v233 row_shl:8 row_mask:0xf bank_mask:0x3
	v_mov_b32_dpp v238, v234 row_shl:8 row_mask:0xf bank_mask:0x3
	v_mov_b32_dpp v239, v235 row_shl:8 row_mask:0xf bank_mask:0x3
	v_mov_b32_dpp v232, v244 row_shr:8 row_mask:0xf bank_mask:0xc
	v_mov_b32_dpp v233, v245 row_shr:8 row_mask:0xf bank_mask:0xc
	v_mov_b32_dpp v234, v246 row_shr:8 row_mask:0xf bank_mask:0xc
	v_mov_b32_dpp v235, v247 row_shr:8 row_mask:0xf bank_mask:0xc
	s_mov_b64 s[98:99], 0x0
	v_lshl_add_u64 v[156:157], v[184:185], 0, s[98:99]
	s_mov_b64 s[98:99], 0x4000
	v_lshl_add_u64 v[158:159], v[184:185], 0, s[98:99]
	global_store_dwordx4 v[156:157], v[232:235], off
	global_store_dwordx4 v[158:159], v[236:239], off
	s_mov_b64 s[98:99], 0x4000
	v_lshl_add_u64 v[180:181], v[178:179], 0, s[98:99]
	global_load_dwordx4 v[200:203], v[180:181], off offset:-4096
	global_load_dwordx4 v[204:207], v[180:181], off
	s_mov_b64 s[98:99], 0x10000
	v_lshl_add_u64 v[180:181], v[184:185], 0, s[98:99]
	global_load_dwordx4 v[208:211], v[180:181], off
	s_mov_b64 s[98:99], 0x14000
	v_lshl_add_u64 v[180:181], v[184:185], 0, s[98:99]
	global_load_dwordx4 v[212:215], v[180:181], off
	s_waitcnt vmcnt(6)
; DI size_t pidx(size_t row, int col) { return (size_t)(col >> 8) * ((size_t)TH * 256) + row * 256 + (size_t)(col & 255); }
; DI float lo_f(unsigned u) { return __uint_as_float(u << 16); }
; DI float hi_f(unsigned u) { return __uint_as_float(u & 0xffff0000u); }
; DI unsigned pk2(float lo, float hi) { return pg8::cvt_pk_bf16(lo, hi); }
;     DI void operator()(const f32x4 (&acc)[2][2][4][2], const Unit& u, int wr, int wc, int fr, int fq) const {
;         const int row0 = u.pm * 256 + wr * 64 + fr, col0 = u.pn * 256 + wc * 32 + 8 * fq;
; #pragma unroll
;         for (int ai = 0; ai < 2; ++ai)
; #pragma unroll
;             for (int m = 0; m < 4; ++m) { const size_t r = (size_t)(row0 + ai * 128 + m * 16);
; #pragma unroll
;                 for (int bj = 0; bj < 2; ++bj) { const int c = col0 + bj * 128; const v4u g = *(const v4u*)(P + pidx(r, 8704 + c)); const v4u y = *(const v4u*)(Y + r * 1024 + c);
;                     const f32x4 a0 = acc[ai][bj][m][0], a1 = acc[ai][bj][m][1];
;                     v4u w; w.x = pk2(lo_f(y.x) + a0[0] * lo_f(g.x), hi_f(y.x) + a0[1] * hi_f(g.x)); w.y = pk2(lo_f(y.y) + a0[2] * lo_f(g.y), hi_f(y.y) + a0[3] * hi_f(g.y));
;                     w.z = pk2(lo_f(y.z) + a1[0] * lo_f(g.z), hi_f(y.z) + a1[1] * hi_f(g.z)); w.w = pk2(lo_f(y.w) + a1[2] * lo_f(g.w), hi_f(y.w) + a1[3] * hi_f(g.w));
;                     *(v4u*)(Y + r * 1024 + c) = w; } }
	v_mov_b32_e32 v244, v216
	v_mov_b32_e32 v245, v217
	v_mov_b32_e32 v246, v218
	v_mov_b32_e32 v247, v219
	v_mov_b32_dpp v216, v220 row_shr:8 row_mask:0xf bank_mask:0xc
	v_mov_b32_dpp v217, v221 row_shr:8 row_mask:0xf bank_mask:0xc
	v_mov_b32_dpp v218, v222 row_shr:8 row_mask:0xf bank_mask:0xc
	v_mov_b32_dpp v219, v223 row_shr:8 row_mask:0xf bank_mask:0xc
	v_mov_b32_dpp v220, v244 row_shl:8 row_mask:0xf bank_mask:0x3
	v_mov_b32_dpp v221, v245 row_shl:8 row_mask:0xf bank_mask:0x3
	v_mov_b32_dpp v222, v246 row_shl:8 row_mask:0xf bank_mask:0x3
	v_mov_b32_dpp v223, v247 row_shl:8 row_mask:0xf bank_mask:0x3
	v_mov_b32_e32 v244, v224
	v_mov_b32_e32 v245, v225
	v_mov_b32_e32 v246, v226
	v_mov_b32_e32 v247, v227
	v_mov_b32_dpp v224, v228 row_shr:8 row_mask:0xf bank_mask:0xc
	v_mov_b32_dpp v225, v229 row_shr:8 row_mask:0xf bank_mask:0xc
	v_mov_b32_dpp v226, v230 row_shr:8 row_mask:0xf bank_mask:0xc
	v_mov_b32_dpp v227, v231 row_shr:8 row_mask:0xf bank_mask:0xc
	v_mov_b32_dpp v228, v244 row_shl:8 row_mask:0xf bank_mask:0x3
	v_mov_b32_dpp v229, v245 row_shl:8 row_mask:0xf bank_mask:0x3
	v_mov_b32_dpp v230, v246 row_shl:8 row_mask:0xf bank_mask:0x3
	v_mov_b32_dpp v231, v247 row_shl:8 row_mask:0xf bank_mask:0x3
	v_lshlrev_b32_e32 v180, 16, v224
	v_and_b32_e32 v181, 0xffff0000, v224
	v_lshlrev_b32_e32 v182, 16, v216
	v_and_b32_e32 v183, 0xffff0000, v216
	v_fmac_f32_e32 v180, v110, v182
	v_fmac_f32_e32 v181, v111, v183
	v_cvt_pk_bf16_f32 v232, v180, v181
	v_lshlrev_b32_e32 v180, 16, v225
	v_and_b32_e32 v181, 0xffff0000, v225
	v_lshlrev_b32_e32 v182, 16, v217
	v_and_b32_e32 v183, 0xffff0000, v217
	v_fmac_f32_e32 v180, v112, v182
	v_fmac_f32_e32 v181, v113, v183
	v_cvt_pk_bf16_f32 v233, v180, v181
	v_lshlrev_b32_e32 v180, 16, v226
	v_and_b32_e32 v181, 0xffff0000, v226
	v_lshlrev_b32_e32 v182, 16, v218
	v_and_b32_e32 v183, 0xffff0000, v218
	v_fmac_f32_e32 v180, v106, v182
	v_fmac_f32_e32 v181, v107, v183
	v_cvt_pk_bf16_f32 v234, v180, v181
	v_lshlrev_b32_e32 v180, 16, v227
	v_and_b32_e32 v181, 0xffff0000, v227
	v_lshlrev_b32_e32 v182, 16, v219
	v_and_b32_e32 v183, 0xffff0000, v219
	v_fmac_f32_e32 v180, v108, v182
	v_fmac_f32_e32 v181, v109, v183
	v_cvt_pk_bf16_f32 v235, v180, v181
	v_lshlrev_b32_e32 v180, 16, v228
	v_and_b32_e32 v181, 0xffff0000, v228
	v_lshlrev_b32_e32 v182, 16, v220
	v_and_b32_e32 v183, 0xffff0000, v220
	v_fmac_f32_e32 v180, v102, v182
	v_fmac_f32_e32 v181, v103, v183
	v_cvt_pk_bf16_f32 v236, v180, v181
	v_lshlrev_b32_e32 v180, 16, v229
	v_and_b32_e32 v181, 0xffff0000, v229
	v_lshlrev_b32_e32 v182, 16, v221
	v_and_b32_e32 v183, 0xffff0000, v221
	v_fmac_f32_e32 v180, v104, v182
	v_fmac_f32_e32 v181, v105, v183
	v_cvt_pk_bf16_f32 v237, v180, v181
	v_lshlrev_b32_e32 v180, 16, v230
	v_and_b32_e32 v181, 0xffff0000, v230
	v_lshlrev_b32_e32 v182, 16, v222
	v_and_b32_e32 v183, 0xffff0000, v222
	v_fmac_f32_e32 v180, v98, v182
	v_fmac_f32_e32 v181, v99, v183
	v_cvt_pk_bf16_f32 v238, v180, v181
	v_lshlrev_b32_e32 v180, 16, v231
	v_and_b32_e32 v181, 0xffff0000, v231
	v_lshlrev_b32_e32 v182, 16, v223
	v_and_b32_e32 v183, 0xffff0000, v223
	v_fmac_f32_e32 v180, v100, v182
	v_fmac_f32_e32 v181, v101, v183
	v_cvt_pk_bf16_f32 v239, v180, v181
	v_mov_b32_e32 v244, v236
	v_mov_b32_e32 v245, v237
	v_mov_b32_e32 v246, v238
	v_mov_b32_e32 v247, v239
	v_mov_b32_dpp v236, v232 row_shl:8 row_mask:0xf bank_mask:0x3
	v_mov_b32_dpp v237, v233 row_shl:8 row_mask:0xf bank_mask:0x3
	v_mov_b32_dpp v238, v234 row_shl:8 row_mask:0xf bank_mask:0x3
	v_mov_b32_dpp v239, v235 row_shl:8 row_mask:0xf bank_mask:0x3
	v_mov_b32_dpp v232, v244 row_shr:8 row_mask:0xf bank_mask:0xc
	v_mov_b32_dpp v233, v245 row_shr:8 row_mask:0xf bank_mask:0xc
	v_mov_b32_dpp v234, v246 row_shr:8 row_mask:0xf bank_mask:0xc
	v_mov_b32_dpp v235, v247 row_shr:8 row_mask:0xf bank_mask:0xc
	s_mov_b64 s[98:99], 0x8000
	v_lshl_add_u64 v[156:157], v[184:185], 0, s[98:99]
	s_mov_b64 s[98:99], 0xc000
	v_lshl_add_u64 v[158:159], v[184:185], 0, s[98:99]
	global_store_dwordx4 v[156:157], v[232:235], off
	global_store_dwordx4 v[158:159], v[236:239], off
	s_mov_b64 s[98:99], 0x6000
	v_lshl_add_u64 v[180:181], v[178:179], 0, s[98:99]
	global_load_dwordx4 v[216:219], v[180:181], off offset:-4096
	global_load_dwordx4 v[220:223], v[180:181], off
	s_mov_b64 s[98:99], 0x18000
	v_lshl_add_u64 v[180:181], v[184:185], 0, s[98:99]
	global_load_dwordx4 v[224:227], v[180:181], off
	s_mov_b64 s[98:99], 0x1c000
	v_lshl_add_u64 v[180:181], v[184:185], 0, s[98:99]
	global_load_dwordx4 v[228:231], v[180:181], off
	s_waitcnt vmcnt(6)
; DI size_t pidx(size_t row, int col) { return (size_t)(col >> 8) * ((size_t)TH * 256) + row * 256 + (size_t)(col & 255); }
; DI float lo_f(unsigned u) { return __uint_as_float(u << 16); }
; DI float hi_f(unsigned u) { return __uint_as_float(u & 0xffff0000u); }
; DI unsigned pk2(float lo, float hi) { return pg8::cvt_pk_bf16(lo, hi); }
;     DI void operator()(const f32x4 (&acc)[2][2][4][2], const Unit& u, int wr, int wc, int fr, int fq) const {
;         const int row0 = u.pm * 256 + wr * 64 + fr, col0 = u.pn * 256 + wc * 32 + 8 * fq;
; #pragma unroll
;         for (int ai = 0; ai < 2; ++ai)
; #pragma unroll
;             for (int m = 0; m < 4; ++m) { const size_t r = (size_t)(row0 + ai * 128 + m * 16);
; #pragma unroll
;                 for (int bj = 0; bj < 2; ++bj) { const int c = col0 + bj * 128; const v4u g = *(const v4u*)(P + pidx(r, 8704 + c)); const v4u y = *(const v4u*)(Y + r * 1024 + c);
;                     const f32x4 a0 = acc[ai][bj][m][0], a1 = acc[ai][bj][m][1];
;                     v4u w; w.x = pk2(lo_f(y.x) + a0[0] * lo_f(g.x), hi_f(y.x) + a0[1] * hi_f(g.x)); w.y = pk2(lo_f(y.y) + a0[2] * lo_f(g.y), hi_f(y.y) + a0[3] * hi_f(g.y));
;                     w.z = pk2(lo_f(y.z) + a1[0] * lo_f(g.z), hi_f(y.z) + a1[1] * hi_f(g.z)); w.w = pk2(lo_f(y.w) + a1[2] * lo_f(g.w), hi_f(y.w) + a1[3] * hi_f(g.w));
;                     *(v4u*)(Y + r * 1024 + c) = w; } }
	v_mov_b32_e32 v244, v200
	v_mov_b32_e32 v245, v201
	v_mov_b32_e32 v246, v202
	v_mov_b32_e32 v247, v203
	v_mov_b32_dpp v200, v204 row_shr:8 row_mask:0xf bank_mask:0xc
	v_mov_b32_dpp v201, v205 row_shr:8 row_mask:0xf bank_mask:0xc
	v_mov_b32_dpp v202, v206 row_shr:8 row_mask:0xf bank_mask:0xc
	v_mov_b32_dpp v203, v207 row_shr:8 row_mask:0xf bank_mask:0xc
	v_mov_b32_dpp v204, v244 row_shl:8 row_mask:0xf bank_mask:0x3
	v_mov_b32_dpp v205, v245 row_shl:8 row_mask:0xf bank_mask:0x3
	v_mov_b32_dpp v206, v246 row_shl:8 row_mask:0xf bank_mask:0x3
	v_mov_b32_dpp v207, v247 row_shl:8 row_mask:0xf bank_mask:0x3
	v_mov_b32_e32 v244, v208
	v_mov_b32_e32 v245, v209
	v_mov_b32_e32 v246, v210
	v_mov_b32_e32 v247, v211
	v_mov_b32_dpp v208, v212 row_shr:8 row_mask:0xf bank_mask:0xc
	v_mov_b32_dpp v209, v213 row_shr:8 row_mask:0xf bank_mask:0xc
	v_mov_b32_dpp v210, v214 row_shr:8 row_mask:0xf bank_mask:0xc
	v_mov_b32_dpp v211, v215 row_shr:8 row_mask:0xf bank_mask:0xc
	v_mov_b32_dpp v212, v244 row_shl:8 row_mask:0xf bank_mask:0x3
	v_mov_b32_dpp v213, v245 row_shl:8 row_mask:0xf bank_mask:0x3
	v_mov_b32_dpp v214, v246 row_shl:8 row_mask:0xf bank_mask:0x3
	v_mov_b32_dpp v215, v247 row_shl:8 row_mask:0xf bank_mask:0x3
	v_lshlrev_b32_e32 v180, 16, v208
	v_and_b32_e32 v181, 0xffff0000, v208
	v_lshlrev_b32_e32 v182, 16, v200
	v_and_b32_e32 v183, 0xffff0000, v200
	v_fmac_f32_e32 v180, v94, v182
	v_fmac_f32_e32 v181, v95, v183
	v_cvt_pk_bf16_f32 v232, v180, v181
	v_lshlrev_b32_e32 v180, 16, v209
	v_and_b32_e32 v181, 0xffff0000, v209
	v_lshlrev_b32_e32 v182, 16, v201
	v_and_b32_e32 v183, 0xffff0000, v201
	v_fmac_f32_e32 v180, v96, v182
	v_fmac_f32_e32 v181, v97, v183
	v_cvt_pk_bf16_f32 v233, v180, v181
	v_lshlrev_b32_e32 v180, 16, v210
	v_and_b32_e32 v181, 0xffff0000, v210
	v_lshlrev_b32_e32 v182, 16, v202
	v_and_b32_e32 v183, 0xffff0000, v202
	v_fmac_f32_e32 v180, v90, v182
	v_fmac_f32_e32 v181, v91, v183
	v_cvt_pk_bf16_f32 v234, v180, v181
	v_lshlrev_b32_e32 v180, 16, v211
	v_and_b32_e32 v181, 0xffff0000, v211
	v_lshlrev_b32_e32 v182, 16, v203
	v_and_b32_e32 v183, 0xffff0000, v203
	v_fmac_f32_e32 v180, v92, v182
	v_fmac_f32_e32 v181, v93, v183
	v_cvt_pk_bf16_f32 v235, v180, v181
	v_lshlrev_b32_e32 v180, 16, v212
	v_and_b32_e32 v181, 0xffff0000, v212
	v_lshlrev_b32_e32 v182, 16, v204
	v_and_b32_e32 v183, 0xffff0000, v204
	v_fmac_f32_e32 v180, v86, v182
	v_fmac_f32_e32 v181, v87, v183
	v_cvt_pk_bf16_f32 v236, v180, v181
	v_lshlrev_b32_e32 v180, 16, v213
	v_and_b32_e32 v181, 0xffff0000, v213
	v_lshlrev_b32_e32 v182, 16, v205
	v_and_b32_e32 v183, 0xffff0000, v205
	v_fmac_f32_e32 v180, v88, v182
	v_fmac_f32_e32 v181, v89, v183
	v_cvt_pk_bf16_f32 v237, v180, v181
	v_lshlrev_b32_e32 v180, 16, v214
	v_and_b32_e32 v181, 0xffff0000, v214
	v_lshlrev_b32_e32 v182, 16, v206
	v_and_b32_e32 v183, 0xffff0000, v206
	v_fmac_f32_e32 v180, v82, v182
	v_fmac_f32_e32 v181, v83, v183
	v_cvt_pk_bf16_f32 v238, v180, v181
	v_lshlrev_b32_e32 v180, 16, v215
	v_and_b32_e32 v181, 0xffff0000, v215
	v_lshlrev_b32_e32 v182, 16, v207
	v_and_b32_e32 v183, 0xffff0000, v207
	v_fmac_f32_e32 v180, v84, v182
	v_fmac_f32_e32 v181, v85, v183
	v_cvt_pk_bf16_f32 v239, v180, v181
	v_mov_b32_e32 v244, v236
	v_mov_b32_e32 v245, v237
	v_mov_b32_e32 v246, v238
	v_mov_b32_e32 v247, v239
	v_mov_b32_dpp v236, v232 row_shl:8 row_mask:0xf bank_mask:0x3
	v_mov_b32_dpp v237, v233 row_shl:8 row_mask:0xf bank_mask:0x3
	v_mov_b32_dpp v238, v234 row_shl:8 row_mask:0xf bank_mask:0x3
	v_mov_b32_dpp v239, v235 row_shl:8 row_mask:0xf bank_mask:0x3
	v_mov_b32_dpp v232, v244 row_shr:8 row_mask:0xf bank_mask:0xc
	v_mov_b32_dpp v233, v245 row_shr:8 row_mask:0xf bank_mask:0xc
	v_mov_b32_dpp v234, v246 row_shr:8 row_mask:0xf bank_mask:0xc
	v_mov_b32_dpp v235, v247 row_shr:8 row_mask:0xf bank_mask:0xc
	s_mov_b64 s[98:99], 0x10000
	v_lshl_add_u64 v[156:157], v[184:185], 0, s[98:99]
	s_mov_b64 s[98:99], 0x14000
	v_lshl_add_u64 v[158:159], v[184:185], 0, s[98:99]
	global_store_dwordx4 v[156:157], v[232:235], off
	global_store_dwordx4 v[158:159], v[236:239], off
	s_mov_b64 s[98:99], 0x10000
	v_lshl_add_u64 v[180:181], v[178:179], 0, s[98:99]
	global_load_dwordx4 v[200:203], v[180:181], off offset:-4096
	global_load_dwordx4 v[204:207], v[180:181], off
	s_mov_b64 s[98:99], 0x40000
	v_lshl_add_u64 v[180:181], v[184:185], 0, s[98:99]
	global_load_dwordx4 v[208:211], v[180:181], off
	s_mov_b64 s[98:99], 0x44000
	v_lshl_add_u64 v[180:181], v[184:185], 0, s[98:99]
	global_load_dwordx4 v[212:215], v[180:181], off
	s_waitcnt vmcnt(6)
; DI size_t pidx(size_t row, int col) { return (size_t)(col >> 8) * ((size_t)TH * 256) + row * 256 + (size_t)(col & 255); }
; DI float lo_f(unsigned u) { return __uint_as_float(u << 16); }
; DI float hi_f(unsigned u) { return __uint_as_float(u & 0xffff0000u); }
; DI unsigned pk2(float lo, float hi) { return pg8::cvt_pk_bf16(lo, hi); }
;     DI void operator()(const f32x4 (&acc)[2][2][4][2], const Unit& u, int wr, int wc, int fr, int fq) const {
;         const int row0 = u.pm * 256 + wr * 64 + fr, col0 = u.pn * 256 + wc * 32 + 8 * fq;
; #pragma unroll
;         for (int ai = 0; ai < 2; ++ai)
; #pragma unroll
;             for (int m = 0; m < 4; ++m) { const size_t r = (size_t)(row0 + ai * 128 + m * 16);
; #pragma unroll
;                 for (int bj = 0; bj < 2; ++bj) { const int c = col0 + bj * 128; const v4u g = *(const v4u*)(P + pidx(r, 8704 + c)); const v4u y = *(const v4u*)(Y + r * 1024 + c);
;                     const f32x4 a0 = acc[ai][bj][m][0], a1 = acc[ai][bj][m][1];
;                     v4u w; w.x = pk2(lo_f(y.x) + a0[0] * lo_f(g.x), hi_f(y.x) + a0[1] * hi_f(g.x)); w.y = pk2(lo_f(y.y) + a0[2] * lo_f(g.y), hi_f(y.y) + a0[3] * hi_f(g.y));
;                     w.z = pk2(lo_f(y.z) + a1[0] * lo_f(g.z), hi_f(y.z) + a1[1] * hi_f(g.z)); w.w = pk2(lo_f(y.w) + a1[2] * lo_f(g.w), hi_f(y.w) + a1[3] * hi_f(g.w));
;                     *(v4u*)(Y + r * 1024 + c) = w; } }
	v_mov_b32_e32 v244, v216
	v_mov_b32_e32 v245, v217
	v_mov_b32_e32 v246, v218
	v_mov_b32_e32 v247, v219
	v_mov_b32_dpp v216, v220 row_shr:8 row_mask:0xf bank_mask:0xc
	v_mov_b32_dpp v217, v221 row_shr:8 row_mask:0xf bank_mask:0xc
	v_mov_b32_dpp v218, v222 row_shr:8 row_mask:0xf bank_mask:0xc
	v_mov_b32_dpp v219, v223 row_shr:8 row_mask:0xf bank_mask:0xc
	v_mov_b32_dpp v220, v244 row_shl:8 row_mask:0xf bank_mask:0x3
	v_mov_b32_dpp v221, v245 row_shl:8 row_mask:0xf bank_mask:0x3
	v_mov_b32_dpp v222, v246 row_shl:8 row_mask:0xf bank_mask:0x3
	v_mov_b32_dpp v223, v247 row_shl:8 row_mask:0xf bank_mask:0x3
	v_mov_b32_e32 v244, v224
	v_mov_b32_e32 v245, v225
	v_mov_b32_e32 v246, v226
	v_mov_b32_e32 v247, v227
	v_mov_b32_dpp v224, v228 row_shr:8 row_mask:0xf bank_mask:0xc
	v_mov_b32_dpp v225, v229 row_shr:8 row_mask:0xf bank_mask:0xc
	v_mov_b32_dpp v226, v230 row_shr:8 row_mask:0xf bank_mask:0xc
	v_mov_b32_dpp v227, v231 row_shr:8 row_mask:0xf bank_mask:0xc
	v_mov_b32_dpp v228, v244 row_shl:8 row_mask:0xf bank_mask:0x3
	v_mov_b32_dpp v229, v245 row_shl:8 row_mask:0xf bank_mask:0x3
	v_mov_b32_dpp v230, v246 row_shl:8 row_mask:0xf bank_mask:0x3
	v_mov_b32_dpp v231, v247 row_shl:8 row_mask:0xf bank_mask:0x3
	v_lshlrev_b32_e32 v180, 16, v224
	v_and_b32_e32 v181, 0xffff0000, v224
	v_lshlrev_b32_e32 v182, 16, v216
	v_and_b32_e32 v183, 0xffff0000, v216
	v_fmac_f32_e32 v180, v78, v182
	v_fmac_f32_e32 v181, v79, v183
	v_cvt_pk_bf16_f32 v232, v180, v181
	v_lshlrev_b32_e32 v180, 16, v225
	v_and_b32_e32 v181, 0xffff0000, v225
	v_lshlrev_b32_e32 v182, 16, v217
	v_and_b32_e32 v183, 0xffff0000, v217
	v_fmac_f32_e32 v180, v80, v182
	v_fmac_f32_e32 v181, v81, v183
	v_cvt_pk_bf16_f32 v233, v180, v181
	v_lshlrev_b32_e32 v180, 16, v226
	v_and_b32_e32 v181, 0xffff0000, v226
	v_lshlrev_b32_e32 v182, 16, v218
	v_and_b32_e32 v183, 0xffff0000, v218
	v_fmac_f32_e32 v180, v74, v182
	v_fmac_f32_e32 v181, v75, v183
	v_cvt_pk_bf16_f32 v234, v180, v181
	v_lshlrev_b32_e32 v180, 16, v227
	v_and_b32_e32 v181, 0xffff0000, v227
	v_lshlrev_b32_e32 v182, 16, v219
	v_and_b32_e32 v183, 0xffff0000, v219
	v_fmac_f32_e32 v180, v76, v182
	v_fmac_f32_e32 v181, v77, v183
	v_cvt_pk_bf16_f32 v235, v180, v181
	v_lshlrev_b32_e32 v180, 16, v228
	v_and_b32_e32 v181, 0xffff0000, v228
	v_lshlrev_b32_e32 v182, 16, v220
	v_and_b32_e32 v183, 0xffff0000, v220
	v_fmac_f32_e32 v180, v70, v182
	v_fmac_f32_e32 v181, v71, v183
	v_cvt_pk_bf16_f32 v236, v180, v181
	v_lshlrev_b32_e32 v180, 16, v229
	v_and_b32_e32 v181, 0xffff0000, v229
	v_lshlrev_b32_e32 v182, 16, v221
	v_and_b32_e32 v183, 0xffff0000, v221
	v_fmac_f32_e32 v180, v72, v182
	v_fmac_f32_e32 v181, v73, v183
	v_cvt_pk_bf16_f32 v237, v180, v181
	v_lshlrev_b32_e32 v180, 16, v230
	v_and_b32_e32 v181, 0xffff0000, v230
	v_lshlrev_b32_e32 v182, 16, v222
	v_and_b32_e32 v183, 0xffff0000, v222
	v_fmac_f32_e32 v180, v66, v182
	v_fmac_f32_e32 v181, v67, v183
	v_cvt_pk_bf16_f32 v238, v180, v181
	v_lshlrev_b32_e32 v180, 16, v231
	v_and_b32_e32 v181, 0xffff0000, v231
	v_lshlrev_b32_e32 v182, 16, v223
	v_and_b32_e32 v183, 0xffff0000, v223
	v_fmac_f32_e32 v180, v68, v182
	v_fmac_f32_e32 v181, v69, v183
	v_cvt_pk_bf16_f32 v239, v180, v181
	v_mov_b32_e32 v244, v236
	v_mov_b32_e32 v245, v237
	v_mov_b32_e32 v246, v238
	v_mov_b32_e32 v247, v239
	v_mov_b32_dpp v236, v232 row_shl:8 row_mask:0xf bank_mask:0x3
	v_mov_b32_dpp v237, v233 row_shl:8 row_mask:0xf bank_mask:0x3
	v_mov_b32_dpp v238, v234 row_shl:8 row_mask:0xf bank_mask:0x3
	v_mov_b32_dpp v239, v235 row_shl:8 row_mask:0xf bank_mask:0x3
	v_mov_b32_dpp v232, v244 row_shr:8 row_mask:0xf bank_mask:0xc
	v_mov_b32_dpp v233, v245 row_shr:8 row_mask:0xf bank_mask:0xc
	v_mov_b32_dpp v234, v246 row_shr:8 row_mask:0xf bank_mask:0xc
	v_mov_b32_dpp v235, v247 row_shr:8 row_mask:0xf bank_mask:0xc
	s_mov_b64 s[98:99], 0x18000
	v_lshl_add_u64 v[156:157], v[184:185], 0, s[98:99]
	s_mov_b64 s[98:99], 0x1c000
	v_lshl_add_u64 v[158:159], v[184:185], 0, s[98:99]
	global_store_dwordx4 v[156:157], v[232:235], off
	global_store_dwordx4 v[158:159], v[236:239], off
	s_mov_b64 s[98:99], 0x12000
	v_lshl_add_u64 v[180:181], v[178:179], 0, s[98:99]
	global_load_dwordx4 v[216:219], v[180:181], off offset:-4096
	global_load_dwordx4 v[220:223], v[180:181], off
	s_mov_b64 s[98:99], 0x48000
	v_lshl_add_u64 v[180:181], v[184:185], 0, s[98:99]
	global_load_dwordx4 v[224:227], v[180:181], off
	s_mov_b64 s[98:99], 0x4c000
	v_lshl_add_u64 v[180:181], v[184:185], 0, s[98:99]
	global_load_dwordx4 v[228:231], v[180:181], off
	s_waitcnt vmcnt(6)
; DI size_t pidx(size_t row, int col) { return (size_t)(col >> 8) * ((size_t)TH * 256) + row * 256 + (size_t)(col & 255); }
; DI float lo_f(unsigned u) { return __uint_as_float(u << 16); }
; DI float hi_f(unsigned u) { return __uint_as_float(u & 0xffff0000u); }
; DI unsigned pk2(float lo, float hi) { return pg8::cvt_pk_bf16(lo, hi); }
;     DI void operator()(const f32x4 (&acc)[2][2][4][2], const Unit& u, int wr, int wc, int fr, int fq) const {
;         const int row0 = u.pm * 256 + wr * 64 + fr, col0 = u.pn * 256 + wc * 32 + 8 * fq;
; #pragma unroll
;         for (int ai = 0; ai < 2; ++ai)
; #pragma unroll
;             for (int m = 0; m < 4; ++m) { const size_t r = (size_t)(row0 + ai * 128 + m * 16);
; #pragma unroll
;                 for (int bj = 0; bj < 2; ++bj) { const int c = col0 + bj * 128; const v4u g = *(const v4u*)(P + pidx(r, 8704 + c)); const v4u y = *(const v4u*)(Y + r * 1024 + c);
;                     const f32x4 a0 = acc[ai][bj][m][0], a1 = acc[ai][bj][m][1];
;                     v4u w; w.x = pk2(lo_f(y.x) + a0[0] * lo_f(g.x), hi_f(y.x) + a0[1] * hi_f(g.x)); w.y = pk2(lo_f(y.y) + a0[2] * lo_f(g.y), hi_f(y.y) + a0[3] * hi_f(g.y));
;                     w.z = pk2(lo_f(y.z) + a1[0] * lo_f(g.z), hi_f(y.z) + a1[1] * hi_f(g.z)); w.w = pk2(lo_f(y.w) + a1[2] * lo_f(g.w), hi_f(y.w) + a1[3] * hi_f(g.w));
;                     *(v4u*)(Y + r * 1024 + c) = w; } }
	v_mov_b32_e32 v244, v200
	v_mov_b32_e32 v245, v201
	v_mov_b32_e32 v246, v202
	v_mov_b32_e32 v247, v203
	v_mov_b32_dpp v200, v204 row_shr:8 row_mask:0xf bank_mask:0xc
	v_mov_b32_dpp v201, v205 row_shr:8 row_mask:0xf bank_mask:0xc
	v_mov_b32_dpp v202, v206 row_shr:8 row_mask:0xf bank_mask:0xc
	v_mov_b32_dpp v203, v207 row_shr:8 row_mask:0xf bank_mask:0xc
	v_mov_b32_dpp v204, v244 row_shl:8 row_mask:0xf bank_mask:0x3
	v_mov_b32_dpp v205, v245 row_shl:8 row_mask:0xf bank_mask:0x3
	v_mov_b32_dpp v206, v246 row_shl:8 row_mask:0xf bank_mask:0x3
	v_mov_b32_dpp v207, v247 row_shl:8 row_mask:0xf bank_mask:0x3
	v_mov_b32_e32 v244, v208
	v_mov_b32_e32 v245, v209
	v_mov_b32_e32 v246, v210
	v_mov_b32_e32 v247, v211
	v_mov_b32_dpp v208, v212 row_shr:8 row_mask:0xf bank_mask:0xc
	v_mov_b32_dpp v209, v213 row_shr:8 row_mask:0xf bank_mask:0xc
	v_mov_b32_dpp v210, v214 row_shr:8 row_mask:0xf bank_mask:0xc
	v_mov_b32_dpp v211, v215 row_shr:8 row_mask:0xf bank_mask:0xc
	v_mov_b32_dpp v212, v244 row_shl:8 row_mask:0xf bank_mask:0x3
	v_mov_b32_dpp v213, v245 row_shl:8 row_mask:0xf bank_mask:0x3
	v_mov_b32_dpp v214, v246 row_shl:8 row_mask:0xf bank_mask:0x3
	v_mov_b32_dpp v215, v247 row_shl:8 row_mask:0xf bank_mask:0x3
	v_lshlrev_b32_e32 v180, 16, v208
	v_and_b32_e32 v181, 0xffff0000, v208
	v_lshlrev_b32_e32 v182, 16, v200
	v_and_b32_e32 v183, 0xffff0000, v200
	v_fmac_f32_e32 v180, v62, v182
	v_fmac_f32_e32 v181, v63, v183
	v_cvt_pk_bf16_f32 v232, v180, v181
	v_lshlrev_b32_e32 v180, 16, v209
	v_and_b32_e32 v181, 0xffff0000, v209
	v_lshlrev_b32_e32 v182, 16, v201
	v_and_b32_e32 v183, 0xffff0000, v201
	v_fmac_f32_e32 v180, v64, v182
	v_fmac_f32_e32 v181, v65, v183
	v_cvt_pk_bf16_f32 v233, v180, v181
	v_lshlrev_b32_e32 v180, 16, v210
	v_and_b32_e32 v181, 0xffff0000, v210
	v_lshlrev_b32_e32 v182, 16, v202
	v_and_b32_e32 v183, 0xffff0000, v202
	v_fmac_f32_e32 v180, v58, v182
	v_fmac_f32_e32 v181, v59, v183
	v_cvt_pk_bf16_f32 v234, v180, v181
	v_lshlrev_b32_e32 v180, 16, v211
	v_and_b32_e32 v181, 0xffff0000, v211
	v_lshlrev_b32_e32 v182, 16, v203
	v_and_b32_e32 v183, 0xffff0000, v203
	v_fmac_f32_e32 v180, v60, v182
	v_fmac_f32_e32 v181, v61, v183
	v_cvt_pk_bf16_f32 v235, v180, v181
	v_lshlrev_b32_e32 v180, 16, v212
	v_and_b32_e32 v181, 0xffff0000, v212
	v_lshlrev_b32_e32 v182, 16, v204
	v_and_b32_e32 v183, 0xffff0000, v204
	v_fmac_f32_e32 v180, v54, v182
	v_fmac_f32_e32 v181, v55, v183
	v_cvt_pk_bf16_f32 v236, v180, v181
	v_lshlrev_b32_e32 v180, 16, v213
	v_and_b32_e32 v181, 0xffff0000, v213
	v_lshlrev_b32_e32 v182, 16, v205
	v_and_b32_e32 v183, 0xffff0000, v205
	v_fmac_f32_e32 v180, v56, v182
	v_fmac_f32_e32 v181, v57, v183
	v_cvt_pk_bf16_f32 v237, v180, v181
	v_lshlrev_b32_e32 v180, 16, v214
	v_and_b32_e32 v181, 0xffff0000, v214
	v_lshlrev_b32_e32 v182, 16, v206
	v_and_b32_e32 v183, 0xffff0000, v206
	v_fmac_f32_e32 v180, v50, v182
	v_fmac_f32_e32 v181, v51, v183
	v_cvt_pk_bf16_f32 v238, v180, v181
	v_lshlrev_b32_e32 v180, 16, v215
	v_and_b32_e32 v181, 0xffff0000, v215
	v_lshlrev_b32_e32 v182, 16, v207
	v_and_b32_e32 v183, 0xffff0000, v207
	v_fmac_f32_e32 v180, v52, v182
	v_fmac_f32_e32 v181, v53, v183
	v_cvt_pk_bf16_f32 v239, v180, v181
	v_mov_b32_e32 v244, v236
	v_mov_b32_e32 v245, v237
	v_mov_b32_e32 v246, v238
	v_mov_b32_e32 v247, v239
	v_mov_b32_dpp v236, v232 row_shl:8 row_mask:0xf bank_mask:0x3
	v_mov_b32_dpp v237, v233 row_shl:8 row_mask:0xf bank_mask:0x3
	v_mov_b32_dpp v238, v234 row_shl:8 row_mask:0xf bank_mask:0x3
	v_mov_b32_dpp v239, v235 row_shl:8 row_mask:0xf bank_mask:0x3
	v_mov_b32_dpp v232, v244 row_shr:8 row_mask:0xf bank_mask:0xc
	v_mov_b32_dpp v233, v245 row_shr:8 row_mask:0xf bank_mask:0xc
	v_mov_b32_dpp v234, v246 row_shr:8 row_mask:0xf bank_mask:0xc
	v_mov_b32_dpp v235, v247 row_shr:8 row_mask:0xf bank_mask:0xc
	s_mov_b64 s[98:99], 0x40000
	v_lshl_add_u64 v[156:157], v[184:185], 0, s[98:99]
	s_mov_b64 s[98:99], 0x44000
	v_lshl_add_u64 v[158:159], v[184:185], 0, s[98:99]
	global_store_dwordx4 v[156:157], v[232:235], off
	global_store_dwordx4 v[158:159], v[236:239], off
	s_mov_b64 s[98:99], 0x14000
	v_lshl_add_u64 v[180:181], v[178:179], 0, s[98:99]
	global_load_dwordx4 v[200:203], v[180:181], off offset:-4096
	global_load_dwordx4 v[204:207], v[180:181], off
	s_mov_b64 s[98:99], 0x50000
	v_lshl_add_u64 v[180:181], v[184:185], 0, s[98:99]
	global_load_dwordx4 v[208:211], v[180:181], off
	s_mov_b64 s[98:99], 0x54000
	v_lshl_add_u64 v[180:181], v[184:185], 0, s[98:99]
	global_load_dwordx4 v[212:215], v[180:181], off
	s_waitcnt vmcnt(6)
; DI size_t pidx(size_t row, int col) { return (size_t)(col >> 8) * ((size_t)TH * 256) + row * 256 + (size_t)(col & 255); }
; DI float lo_f(unsigned u) { return __uint_as_float(u << 16); }
; DI float hi_f(unsigned u) { return __uint_as_float(u & 0xffff0000u); }
; DI unsigned pk2(float lo, float hi) { return pg8::cvt_pk_bf16(lo, hi); }
;     DI void operator()(const f32x4 (&acc)[2][2][4][2], const Unit& u, int wr, int wc, int fr, int fq) const {
;         const int row0 = u.pm * 256 + wr * 64 + fr, col0 = u.pn * 256 + wc * 32 + 8 * fq;
; #pragma unroll
;         for (int ai = 0; ai < 2; ++ai)
; #pragma unroll
;             for (int m = 0; m < 4; ++m) { const size_t r = (size_t)(row0 + ai * 128 + m * 16);
; #pragma unroll
;                 for (int bj = 0; bj < 2; ++bj) { const int c = col0 + bj * 128; const v4u g = *(const v4u*)(P + pidx(r, 8704 + c)); const v4u y = *(const v4u*)(Y + r * 1024 + c);
;                     const f32x4 a0 = acc[ai][bj][m][0], a1 = acc[ai][bj][m][1];
;                     v4u w; w.x = pk2(lo_f(y.x) + a0[0] * lo_f(g.x), hi_f(y.x) + a0[1] * hi_f(g.x)); w.y = pk2(lo_f(y.y) + a0[2] * lo_f(g.y), hi_f(y.y) + a0[3] * hi_f(g.y));
;                     w.z = pk2(lo_f(y.z) + a1[0] * lo_f(g.z), hi_f(y.z) + a1[1] * hi_f(g.z)); w.w = pk2(lo_f(y.w) + a1[2] * lo_f(g.w), hi_f(y.w) + a1[3] * hi_f(g.w));
;                     *(v4u*)(Y + r * 1024 + c) = w; } }
	v_mov_b32_e32 v244, v216
	v_mov_b32_e32 v245, v217
	v_mov_b32_e32 v246, v218
	v_mov_b32_e32 v247, v219
	v_mov_b32_dpp v216, v220 row_shr:8 row_mask:0xf bank_mask:0xc
	v_mov_b32_dpp v217, v221 row_shr:8 row_mask:0xf bank_mask:0xc
	v_mov_b32_dpp v218, v222 row_shr:8 row_mask:0xf bank_mask:0xc
	v_mov_b32_dpp v219, v223 row_shr:8 row_mask:0xf bank_mask:0xc
	v_mov_b32_dpp v220, v244 row_shl:8 row_mask:0xf bank_mask:0x3
	v_mov_b32_dpp v221, v245 row_shl:8 row_mask:0xf bank_mask:0x3
	v_mov_b32_dpp v222, v246 row_shl:8 row_mask:0xf bank_mask:0x3
	v_mov_b32_dpp v223, v247 row_shl:8 row_mask:0xf bank_mask:0x3
	v_mov_b32_e32 v244, v224
	v_mov_b32_e32 v245, v225
	v_mov_b32_e32 v246, v226
	v_mov_b32_e32 v247, v227
	v_mov_b32_dpp v224, v228 row_shr:8 row_mask:0xf bank_mask:0xc
	v_mov_b32_dpp v225, v229 row_shr:8 row_mask:0xf bank_mask:0xc
	v_mov_b32_dpp v226, v230 row_shr:8 row_mask:0xf bank_mask:0xc
	v_mov_b32_dpp v227, v231 row_shr:8 row_mask:0xf bank_mask:0xc
	v_mov_b32_dpp v228, v244 row_shl:8 row_mask:0xf bank_mask:0x3
	v_mov_b32_dpp v229, v245 row_shl:8 row_mask:0xf bank_mask:0x3
	v_mov_b32_dpp v230, v246 row_shl:8 row_mask:0xf bank_mask:0x3
	v_mov_b32_dpp v231, v247 row_shl:8 row_mask:0xf bank_mask:0x3
	v_lshlrev_b32_e32 v180, 16, v224
	v_and_b32_e32 v181, 0xffff0000, v224
	v_lshlrev_b32_e32 v182, 16, v216
	v_and_b32_e32 v183, 0xffff0000, v216
	v_fmac_f32_e32 v180, v46, v182
	v_fmac_f32_e32 v181, v47, v183
	v_cvt_pk_bf16_f32 v232, v180, v181
	v_lshlrev_b32_e32 v180, 16, v225
	v_and_b32_e32 v181, 0xffff0000, v225
	v_lshlrev_b32_e32 v182, 16, v217
	v_and_b32_e32 v183, 0xffff0000, v217
	v_fmac_f32_e32 v180, v48, v182
	v_fmac_f32_e32 v181, v49, v183
	v_cvt_pk_bf16_f32 v233, v180, v181
	v_lshlrev_b32_e32 v180, 16, v226
	v_and_b32_e32 v181, 0xffff0000, v226
	v_lshlrev_b32_e32 v182, 16, v218
	v_and_b32_e32 v183, 0xffff0000, v218
	v_fmac_f32_e32 v180, v42, v182
	v_fmac_f32_e32 v181, v43, v183
	v_cvt_pk_bf16_f32 v234, v180, v181
	v_lshlrev_b32_e32 v180, 16, v227
	v_and_b32_e32 v181, 0xffff0000, v227
	v_lshlrev_b32_e32 v182, 16, v219
	v_and_b32_e32 v183, 0xffff0000, v219
	v_fmac_f32_e32 v180, v44, v182
	v_fmac_f32_e32 v181, v45, v183
	v_cvt_pk_bf16_f32 v235, v180, v181
	v_lshlrev_b32_e32 v180, 16, v228
	v_and_b32_e32 v181, 0xffff0000, v228
	v_lshlrev_b32_e32 v182, 16, v220
	v_and_b32_e32 v183, 0xffff0000, v220
	v_fmac_f32_e32 v180, v38, v182
	v_fmac_f32_e32 v181, v39, v183
	v_cvt_pk_bf16_f32 v236, v180, v181
	v_lshlrev_b32_e32 v180, 16, v229
	v_and_b32_e32 v181, 0xffff0000, v229
	v_lshlrev_b32_e32 v182, 16, v221
	v_and_b32_e32 v183, 0xffff0000, v221
	v_fmac_f32_e32 v180, v40, v182
	v_fmac_f32_e32 v181, v41, v183
	v_cvt_pk_bf16_f32 v237, v180, v181
	v_lshlrev_b32_e32 v180, 16, v230
	v_and_b32_e32 v181, 0xffff0000, v230
	v_lshlrev_b32_e32 v182, 16, v222
	v_and_b32_e32 v183, 0xffff0000, v222
	v_fmac_f32_e32 v180, v34, v182
	v_fmac_f32_e32 v181, v35, v183
	v_cvt_pk_bf16_f32 v238, v180, v181
	v_lshlrev_b32_e32 v180, 16, v231
	v_and_b32_e32 v181, 0xffff0000, v231
	v_lshlrev_b32_e32 v182, 16, v223
	v_and_b32_e32 v183, 0xffff0000, v223
	v_fmac_f32_e32 v180, v36, v182
	v_fmac_f32_e32 v181, v37, v183
	v_cvt_pk_bf16_f32 v239, v180, v181
	v_mov_b32_e32 v244, v236
	v_mov_b32_e32 v245, v237
	v_mov_b32_e32 v246, v238
	v_mov_b32_e32 v247, v239
	v_mov_b32_dpp v236, v232 row_shl:8 row_mask:0xf bank_mask:0x3
	v_mov_b32_dpp v237, v233 row_shl:8 row_mask:0xf bank_mask:0x3
	v_mov_b32_dpp v238, v234 row_shl:8 row_mask:0xf bank_mask:0x3
	v_mov_b32_dpp v239, v235 row_shl:8 row_mask:0xf bank_mask:0x3
	v_mov_b32_dpp v232, v244 row_shr:8 row_mask:0xf bank_mask:0xc
	v_mov_b32_dpp v233, v245 row_shr:8 row_mask:0xf bank_mask:0xc
	v_mov_b32_dpp v234, v246 row_shr:8 row_mask:0xf bank_mask:0xc
	v_mov_b32_dpp v235, v247 row_shr:8 row_mask:0xf bank_mask:0xc
	s_mov_b64 s[98:99], 0x48000
	v_lshl_add_u64 v[156:157], v[184:185], 0, s[98:99]
	s_mov_b64 s[98:99], 0x4c000
	v_lshl_add_u64 v[158:159], v[184:185], 0, s[98:99]
	global_store_dwordx4 v[156:157], v[232:235], off
	global_store_dwordx4 v[158:159], v[236:239], off
	s_mov_b64 s[98:99], 0x16000
	v_lshl_add_u64 v[180:181], v[178:179], 0, s[98:99]
	global_load_dwordx4 v[216:219], v[180:181], off offset:-4096
	global_load_dwordx4 v[220:223], v[180:181], off
	s_mov_b64 s[98:99], 0x58000
	v_lshl_add_u64 v[180:181], v[184:185], 0, s[98:99]
	global_load_dwordx4 v[224:227], v[180:181], off
	s_mov_b64 s[98:99], 0x5c000
	v_lshl_add_u64 v[180:181], v[184:185], 0, s[98:99]
	global_load_dwordx4 v[228:231], v[180:181], off
	s_waitcnt vmcnt(6)
; DI size_t pidx(size_t row, int col) { return (size_t)(col >> 8) * ((size_t)TH * 256) + row * 256 + (size_t)(col & 255); }
; DI float lo_f(unsigned u) { return __uint_as_float(u << 16); }
; DI float hi_f(unsigned u) { return __uint_as_float(u & 0xffff0000u); }
; DI unsigned pk2(float lo, float hi) { return pg8::cvt_pk_bf16(lo, hi); }
;     DI void operator()(const f32x4 (&acc)[2][2][4][2], const Unit& u, int wr, int wc, int fr, int fq) const {
;         const int row0 = u.pm * 256 + wr * 64 + fr, col0 = u.pn * 256 + wc * 32 + 8 * fq;
; #pragma unroll
;         for (int ai = 0; ai < 2; ++ai)
; #pragma unroll
;             for (int m = 0; m < 4; ++m) { const size_t r = (size_t)(row0 + ai * 128 + m * 16);
; #pragma unroll
;                 for (int bj = 0; bj < 2; ++bj) { const int c = col0 + bj * 128; const v4u g = *(const v4u*)(P + pidx(r, 8704 + c)); const v4u y = *(const v4u*)(Y + r * 1024 + c);
;                     const f32x4 a0 = acc[ai][bj][m][0], a1 = acc[ai][bj][m][1];
;                     v4u w; w.x = pk2(lo_f(y.x) + a0[0] * lo_f(g.x), hi_f(y.x) + a0[1] * hi_f(g.x)); w.y = pk2(lo_f(y.y) + a0[2] * lo_f(g.y), hi_f(y.y) + a0[3] * hi_f(g.y));
;                     w.z = pk2(lo_f(y.z) + a1[0] * lo_f(g.z), hi_f(y.z) + a1[1] * hi_f(g.z)); w.w = pk2(lo_f(y.w) + a1[2] * lo_f(g.w), hi_f(y.w) + a1[3] * hi_f(g.w));
;                     *(v4u*)(Y + r * 1024 + c) = w; } }
	v_mov_b32_e32 v244, v200
	v_mov_b32_e32 v245, v201
	v_mov_b32_e32 v246, v202
	v_mov_b32_e32 v247, v203
	v_mov_b32_dpp v200, v204 row_shr:8 row_mask:0xf bank_mask:0xc
	v_mov_b32_dpp v201, v205 row_shr:8 row_mask:0xf bank_mask:0xc
	v_mov_b32_dpp v202, v206 row_shr:8 row_mask:0xf bank_mask:0xc
	v_mov_b32_dpp v203, v207 row_shr:8 row_mask:0xf bank_mask:0xc
	v_mov_b32_dpp v204, v244 row_shl:8 row_mask:0xf bank_mask:0x3
	v_mov_b32_dpp v205, v245 row_shl:8 row_mask:0xf bank_mask:0x3
	v_mov_b32_dpp v206, v246 row_shl:8 row_mask:0xf bank_mask:0x3
	v_mov_b32_dpp v207, v247 row_shl:8 row_mask:0xf bank_mask:0x3
	v_mov_b32_e32 v244, v208
	v_mov_b32_e32 v245, v209
	v_mov_b32_e32 v246, v210
	v_mov_b32_e32 v247, v211
	v_mov_b32_dpp v208, v212 row_shr:8 row_mask:0xf bank_mask:0xc
	v_mov_b32_dpp v209, v213 row_shr:8 row_mask:0xf bank_mask:0xc
	v_mov_b32_dpp v210, v214 row_shr:8 row_mask:0xf bank_mask:0xc
	v_mov_b32_dpp v211, v215 row_shr:8 row_mask:0xf bank_mask:0xc
	v_mov_b32_dpp v212, v244 row_shl:8 row_mask:0xf bank_mask:0x3
	v_mov_b32_dpp v213, v245 row_shl:8 row_mask:0xf bank_mask:0x3
	v_mov_b32_dpp v214, v246 row_shl:8 row_mask:0xf bank_mask:0x3
	v_mov_b32_dpp v215, v247 row_shl:8 row_mask:0xf bank_mask:0x3
	v_lshlrev_b32_e32 v180, 16, v208
	v_and_b32_e32 v181, 0xffff0000, v208
	v_lshlrev_b32_e32 v182, 16, v200
	v_and_b32_e32 v183, 0xffff0000, v200
	v_fmac_f32_e32 v180, v30, v182
	v_fmac_f32_e32 v181, v31, v183
	v_cvt_pk_bf16_f32 v232, v180, v181
	v_lshlrev_b32_e32 v180, 16, v209
	v_and_b32_e32 v181, 0xffff0000, v209
	v_lshlrev_b32_e32 v182, 16, v201
	v_and_b32_e32 v183, 0xffff0000, v201
	v_fmac_f32_e32 v180, v32, v182
	v_fmac_f32_e32 v181, v33, v183
	v_cvt_pk_bf16_f32 v233, v180, v181
	v_lshlrev_b32_e32 v180, 16, v210
	v_and_b32_e32 v181, 0xffff0000, v210
	v_lshlrev_b32_e32 v182, 16, v202
	v_and_b32_e32 v183, 0xffff0000, v202
	v_fmac_f32_e32 v180, v26, v182
	v_fmac_f32_e32 v181, v27, v183
	v_cvt_pk_bf16_f32 v234, v180, v181
	v_lshlrev_b32_e32 v180, 16, v211
	v_and_b32_e32 v181, 0xffff0000, v211
	v_lshlrev_b32_e32 v182, 16, v203
	v_and_b32_e32 v183, 0xffff0000, v203
	v_fmac_f32_e32 v180, v28, v182
	v_fmac_f32_e32 v181, v29, v183
	v_cvt_pk_bf16_f32 v235, v180, v181
	v_lshlrev_b32_e32 v180, 16, v212
	v_and_b32_e32 v181, 0xffff0000, v212
	v_lshlrev_b32_e32 v182, 16, v204
	v_and_b32_e32 v183, 0xffff0000, v204
	v_fmac_f32_e32 v180, v22, v182
	v_fmac_f32_e32 v181, v23, v183
	v_cvt_pk_bf16_f32 v236, v180, v181
	v_lshlrev_b32_e32 v180, 16, v213
	v_and_b32_e32 v181, 0xffff0000, v213
	v_lshlrev_b32_e32 v182, 16, v205
	v_and_b32_e32 v183, 0xffff0000, v205
	v_fmac_f32_e32 v180, v24, v182
	v_fmac_f32_e32 v181, v25, v183
	v_cvt_pk_bf16_f32 v237, v180, v181
	v_lshlrev_b32_e32 v180, 16, v214
	v_and_b32_e32 v181, 0xffff0000, v214
	v_lshlrev_b32_e32 v182, 16, v206
	v_and_b32_e32 v183, 0xffff0000, v206
	v_fmac_f32_e32 v180, v18, v182
	v_fmac_f32_e32 v181, v19, v183
	v_cvt_pk_bf16_f32 v238, v180, v181
	v_lshlrev_b32_e32 v180, 16, v215
	v_and_b32_e32 v181, 0xffff0000, v215
	v_lshlrev_b32_e32 v182, 16, v207
	v_and_b32_e32 v183, 0xffff0000, v207
	v_fmac_f32_e32 v180, v20, v182
	v_fmac_f32_e32 v181, v21, v183
	v_cvt_pk_bf16_f32 v239, v180, v181
	v_mov_b32_e32 v244, v236
	v_mov_b32_e32 v245, v237
	v_mov_b32_e32 v246, v238
	v_mov_b32_e32 v247, v239
	v_mov_b32_dpp v236, v232 row_shl:8 row_mask:0xf bank_mask:0x3
	v_mov_b32_dpp v237, v233 row_shl:8 row_mask:0xf bank_mask:0x3
	v_mov_b32_dpp v238, v234 row_shl:8 row_mask:0xf bank_mask:0x3
	v_mov_b32_dpp v239, v235 row_shl:8 row_mask:0xf bank_mask:0x3
	v_mov_b32_dpp v232, v244 row_shr:8 row_mask:0xf bank_mask:0xc
	v_mov_b32_dpp v233, v245 row_shr:8 row_mask:0xf bank_mask:0xc
	v_mov_b32_dpp v234, v246 row_shr:8 row_mask:0xf bank_mask:0xc
	v_mov_b32_dpp v235, v247 row_shr:8 row_mask:0xf bank_mask:0xc
	s_mov_b64 s[98:99], 0x50000
	v_lshl_add_u64 v[156:157], v[184:185], 0, s[98:99]
	s_mov_b64 s[98:99], 0x54000
	v_lshl_add_u64 v[158:159], v[184:185], 0, s[98:99]
	global_store_dwordx4 v[156:157], v[232:235], off
	global_store_dwordx4 v[158:159], v[236:239], off
	s_nop 1
	s_waitcnt vmcnt(2)
; DI size_t pidx(size_t row, int col) { return (size_t)(col >> 8) * ((size_t)TH * 256) + row * 256 + (size_t)(col & 255); }
; DI float lo_f(unsigned u) { return __uint_as_float(u << 16); }
; DI float hi_f(unsigned u) { return __uint_as_float(u & 0xffff0000u); }
; DI unsigned pk2(float lo, float hi) { return pg8::cvt_pk_bf16(lo, hi); }
;     DI void operator()(const f32x4 (&acc)[2][2][4][2], const Unit& u, int wr, int wc, int fr, int fq) const {
;         const int row0 = u.pm * 256 + wr * 64 + fr, col0 = u.pn * 256 + wc * 32 + 8 * fq;
; #pragma unroll
;         for (int ai = 0; ai < 2; ++ai)
; #pragma unroll
;             for (int m = 0; m < 4; ++m) { const size_t r = (size_t)(row0 + ai * 128 + m * 16);
; #pragma unroll
;                 for (int bj = 0; bj < 2; ++bj) { const int c = col0 + bj * 128; const v4u g = *(const v4u*)(P + pidx(r, 8704 + c)); const v4u y = *(const v4u*)(Y + r * 1024 + c);
;                     const f32x4 a0 = acc[ai][bj][m][0], a1 = acc[ai][bj][m][1];
;                     v4u w; w.x = pk2(lo_f(y.x) + a0[0] * lo_f(g.x), hi_f(y.x) + a0[1] * hi_f(g.x)); w.y = pk2(lo_f(y.y) + a0[2] * lo_f(g.y), hi_f(y.y) + a0[3] * hi_f(g.y));
;                     w.z = pk2(lo_f(y.z) + a1[0] * lo_f(g.z), hi_f(y.z) + a1[1] * hi_f(g.z)); w.w = pk2(lo_f(y.w) + a1[2] * lo_f(g.w), hi_f(y.w) + a1[3] * hi_f(g.w));
;                     *(v4u*)(Y + r * 1024 + c) = w; } }
	v_mov_b32_e32 v244, v216
	v_mov_b32_e32 v245, v217
	v_mov_b32_e32 v246, v218
	v_mov_b32_e32 v247, v219
	v_mov_b32_dpp v216, v220 row_shr:8 row_mask:0xf bank_mask:0xc
	v_mov_b32_dpp v217, v221 row_shr:8 row_mask:0xf bank_mask:0xc
	v_mov_b32_dpp v218, v222 row_shr:8 row_mask:0xf bank_mask:0xc
	v_mov_b32_dpp v219, v223 row_shr:8 row_mask:0xf bank_mask:0xc
	v_mov_b32_dpp v220, v244 row_shl:8 row_mask:0xf bank_mask:0x3
	v_mov_b32_dpp v221, v245 row_shl:8 row_mask:0xf bank_mask:0x3
	v_mov_b32_dpp v222, v246 row_shl:8 row_mask:0xf bank_mask:0x3
	v_mov_b32_dpp v223, v247 row_shl:8 row_mask:0xf bank_mask:0x3
	v_mov_b32_e32 v244, v224
	v_mov_b32_e32 v245, v225
	v_mov_b32_e32 v246, v226
	v_mov_b32_e32 v247, v227
	v_mov_b32_dpp v224, v228 row_shr:8 row_mask:0xf bank_mask:0xc
	v_mov_b32_dpp v225, v229 row_shr:8 row_mask:0xf bank_mask:0xc
	v_mov_b32_dpp v226, v230 row_shr:8 row_mask:0xf bank_mask:0xc
	v_mov_b32_dpp v227, v231 row_shr:8 row_mask:0xf bank_mask:0xc
	v_mov_b32_dpp v228, v244 row_shl:8 row_mask:0xf bank_mask:0x3
	v_mov_b32_dpp v229, v245 row_shl:8 row_mask:0xf bank_mask:0x3
	v_mov_b32_dpp v230, v246 row_shl:8 row_mask:0xf bank_mask:0x3
	v_mov_b32_dpp v231, v247 row_shl:8 row_mask:0xf bank_mask:0x3
	v_lshlrev_b32_e32 v180, 16, v224
	v_and_b32_e32 v181, 0xffff0000, v224
	v_lshlrev_b32_e32 v182, 16, v216
	v_and_b32_e32 v183, 0xffff0000, v216
	v_fmac_f32_e32 v180, v14, v182
	v_fmac_f32_e32 v181, v15, v183
	v_cvt_pk_bf16_f32 v232, v180, v181
	v_lshlrev_b32_e32 v180, 16, v225
	v_and_b32_e32 v181, 0xffff0000, v225
	v_lshlrev_b32_e32 v182, 16, v217
	v_and_b32_e32 v183, 0xffff0000, v217
	v_fmac_f32_e32 v180, v16, v182
	v_fmac_f32_e32 v181, v17, v183
	v_cvt_pk_bf16_f32 v233, v180, v181
	v_lshlrev_b32_e32 v180, 16, v226
	v_and_b32_e32 v181, 0xffff0000, v226
	v_lshlrev_b32_e32 v182, 16, v218
	v_and_b32_e32 v183, 0xffff0000, v218
	v_fmac_f32_e32 v180, v10, v182
	v_fmac_f32_e32 v181, v11, v183
	v_cvt_pk_bf16_f32 v234, v180, v181
	v_lshlrev_b32_e32 v180, 16, v227
	v_and_b32_e32 v181, 0xffff0000, v227
	v_lshlrev_b32_e32 v182, 16, v219
	v_and_b32_e32 v183, 0xffff0000, v219
	v_fmac_f32_e32 v180, v12, v182
	v_fmac_f32_e32 v181, v13, v183
	v_cvt_pk_bf16_f32 v235, v180, v181
	v_lshlrev_b32_e32 v180, 16, v228
	v_and_b32_e32 v181, 0xffff0000, v228
	v_lshlrev_b32_e32 v182, 16, v220
	v_and_b32_e32 v183, 0xffff0000, v220
	v_fmac_f32_e32 v180, v6, v182
	v_fmac_f32_e32 v181, v7, v183
	v_cvt_pk_bf16_f32 v236, v180, v181
	v_lshlrev_b32_e32 v180, 16, v229
	v_and_b32_e32 v181, 0xffff0000, v229
	v_lshlrev_b32_e32 v182, 16, v221
	v_and_b32_e32 v183, 0xffff0000, v221
	v_fmac_f32_e32 v180, v8, v182
	v_fmac_f32_e32 v181, v9, v183
	v_cvt_pk_bf16_f32 v237, v180, v181
	v_lshlrev_b32_e32 v180, 16, v230
	v_and_b32_e32 v181, 0xffff0000, v230
	v_lshlrev_b32_e32 v182, 16, v222
	v_and_b32_e32 v183, 0xffff0000, v222
	v_fmac_f32_e32 v180, v2, v182
	v_fmac_f32_e32 v181, v3, v183
	v_cvt_pk_bf16_f32 v238, v180, v181
	v_lshlrev_b32_e32 v180, 16, v231
	v_and_b32_e32 v181, 0xffff0000, v231
	v_lshlrev_b32_e32 v182, 16, v223
	v_and_b32_e32 v183, 0xffff0000, v223
	v_fmac_f32_e32 v180, v4, v182
	v_fmac_f32_e32 v181, v5, v183
	v_cvt_pk_bf16_f32 v239, v180, v181
	v_mov_b32_e32 v244, v236
	v_mov_b32_e32 v245, v237
	v_mov_b32_e32 v246, v238
	v_mov_b32_e32 v247, v239
	v_mov_b32_dpp v236, v232 row_shl:8 row_mask:0xf bank_mask:0x3
	v_mov_b32_dpp v237, v233 row_shl:8 row_mask:0xf bank_mask:0x3
	v_mov_b32_dpp v238, v234 row_shl:8 row_mask:0xf bank_mask:0x3
	v_mov_b32_dpp v239, v235 row_shl:8 row_mask:0xf bank_mask:0x3
	v_mov_b32_dpp v232, v244 row_shr:8 row_mask:0xf bank_mask:0xc
	v_mov_b32_dpp v233, v245 row_shr:8 row_mask:0xf bank_mask:0xc
	v_mov_b32_dpp v234, v246 row_shr:8 row_mask:0xf bank_mask:0xc
	v_mov_b32_dpp v235, v247 row_shr:8 row_mask:0xf bank_mask:0xc
	s_mov_b64 s[98:99], 0x58000
	v_lshl_add_u64 v[156:157], v[184:185], 0, s[98:99]
	s_mov_b64 s[98:99], 0x5c000
	v_lshl_add_u64 v[158:159], v[184:185], 0, s[98:99]
	global_store_dwordx4 v[156:157], v[232:235], off
	global_store_dwordx4 v[158:159], v[236:239], off
	s_nop 1
	s_movk_i32 s9, 0xf8
	s_mov_b64 s[4:5], -1
	s_cbranch_vccnz .LBB0_571
	s_andn2_b64 vcc, exec, s[2:3]
	s_cbranch_vccnz .LBB0_570
	s_barrier
	s_branch .LBB0_570
